# Wout and FFN-out residual epilogues: all gate and residual loads of a tile issued up front instead of 16 serialized load-wait-store round trips; plus QKV rotary loads batched
# speedup vs baseline: 1.0130x; 1.0130x over previous
; DI int lat_tile(int i) { return (i >> 4) * 18 + 2 + (i & 15); }
; template <int KSEL> DI void run_phase(const Params& p, int ph, char* lds) {
;     ...
;       EpiRes e{&p, l, false, 5 * 1024};
;       const int nm = last ? 128 : 144;
;       for (int i = 0, tm, tn; xcd_tile(bid, G, i, nm, 8, tm, tn); ++i) gemm_tile(p.ACT, 2816, p.Wffo, 2816, 2816, (last ? lat_tile(tm) : tm) * 128, tn * 128, lds, e);
.LBB0_69:
	s_cbranch_execnz .LBB0_696
	s_branch .LBB0_7
.LBB0_71:
	s_and_b64 vcc, exec, s[0:1]
	s_mov_b32 s28, s39
	s_mov_b32 s29, s40
	s_cbranch_vccnz .LBB0_117

; template <class Epi>
; DI void gemm_tile(const bf16_t* __restrict__ A, int lda, const bf16_t* __restrict__ Bt, int ldb, int K, int row0, int col0, char* lds, const Epi& epi) {
;     ...
;   for (int kt = 0; kt < KT; ++kt) {
;     asm volatile("s_waitcnt vmcnt(0)" ::: "memory");
;     __syncthreads();
;     const char* sa = lds + (kt & 1) * 32768 + (wr * 64 + fr) * 128;
;     const char* sb = lds + (kt & 1) * 32768 + 16384 + (wc * 64 + fr) * 128;
; #pragma unroll
;     for (int kk = 0; kk < 2; ++kk) {
;       if (kt + 1 < KT) { if (kk == 0) stage_a(kt + 1, (kt + 1) & 1); else stage_b(kt + 1, (kt + 1) & 1); }
;       bf16x8 a[4], b[4];
;       const int co = ((kk * 4 + fq) ^ swz) * 16;
; #pragma unroll
;       for (int m = 0; m < 4; ++m) a[m] = *(const bf16x8*)(sa + m * 2048 + co);
; #pragma unroll
;       for (int n = 0; n < 4; ++n) b[n] = *(const bf16x8*)(sb + n * 2048 + co);
; #pragma unroll
;       for (int m = 0; m < 4; ++m)
; #pragma unroll
;         for (int n = 0; n < 4; ++n) acc[m][n] = __builtin_amdgcn_mfma_f32_16x16x32_bf16(b[n], a[m], acc[m][n], 0, 0, 0);
;     }
;   }
.LBB0_84:
	s_add_i32 s20, s28, 0xffff8000
	s_and_b32 s29, s28, 0x8000
	s_and_b32 s20, s20, 0x8000
	v_add_u32_e32 v102, s29, v90
	v_add_u32_e32 v110, s20, v91
	v_or_b32_e32 v136, s20, v93
	v_add_u32_e32 v103, 0x1000, v102
	v_readfirstlane_b32 s20, v102
	v_lshl_add_u64 v[94:95], v[74:75], 0, s[0:1]
	v_add_u32_e32 v104, 0x2000, v102
	s_mov_b32 m0, s20
	v_readfirstlane_b32 s20, v103
	s_waitcnt vmcnt(0)
	s_waitcnt vmcnt(0) lgkmcnt(0)
	s_barrier
	v_lshl_add_u64 v[96:97], v[76:77], 0, s[0:1]
	v_add_u32_e32 v105, 0x3000, v102
	global_load_lds_dwordx4 v[94:95], off
	s_mov_b32 m0, s20
	v_readfirstlane_b32 s20, v104
	v_add_u32_e32 v137, 0x4000, v102
	v_lshl_add_u64 v[98:99], v[78:79], 0, s[0:1]
	global_load_lds_dwordx4 v[96:97], off
	s_mov_b32 m0, s20
	v_readfirstlane_b32 s20, v105
	v_add_u32_e32 v159, 0x5000, v102
	v_lshl_add_u64 v[100:101], v[80:81], 0, s[0:1]
	global_load_lds_dwordx4 v[98:99], off
	s_mov_b32 m0, s20
	v_readfirstlane_b32 s20, v137
	v_lshl_add_u64 v[132:133], v[66:67], 0, s[0:1]
	v_add_u32_e32 v160, 0x6000, v102
	global_load_lds_dwordx4 v[100:101], off
	v_add_u32_e32 v106, v110, v92
	v_add_u32_e32 v128, v136, v92
	s_mov_b32 m0, s20
	v_readfirstlane_b32 s20, v159
	v_lshl_add_u64 v[134:135], v[68:69], 0, s[0:1]
	v_add_u32_e32 v161, 0x7000, v102
	ds_read_b128 v[94:97], v106
	ds_read_b128 v[98:101], v106 offset:2048
	ds_read_b128 v[102:105], v106 offset:4096
	ds_read_b128 v[106:109], v106 offset:6144
	ds_read_b128 v[116:119], v128 offset:16384
	ds_read_b128 v[120:123], v128 offset:18432
	ds_read_b128 v[124:127], v128 offset:20480
	ds_read_b128 v[128:131], v128 offset:22528
	global_load_lds_dwordx4 v[132:133], off
	s_mov_b32 m0, s20
	v_readfirstlane_b32 s20, v160
	v_lshl_add_u64 v[84:85], v[70:71], 0, s[0:1]
	global_load_lds_dwordx4 v[134:135], off
	s_mov_b32 m0, s20
	v_readfirstlane_b32 s20, v161
	v_lshl_add_u64 v[82:83], v[72:73], 0, s[0:1]
	global_load_lds_dwordx4 v[84:85], off
	s_mov_b32 m0, s20
	s_waitcnt lgkmcnt(0)
	v_mfma_f32_16x16x32_bf16 v[30:33], v[116:119], v[102:105], v[30:33]
	global_load_lds_dwordx4 v[82:83], off
	s_add_u32 s0, s0, 0x80
	v_mfma_f32_16x16x32_bf16 v[26:29], v[120:123], v[102:105], v[26:29]
	s_addc_u32 s1, s1, 0
	s_add_i32 s28, s28, 0x8000
	s_cmpk_eq_i32 s0, 0x1580
	v_mfma_f32_16x16x32_bf16 v[22:25], v[124:127], v[102:105], v[22:25]
	v_mfma_f32_16x16x32_bf16 v[18:21], v[128:131], v[102:105], v[18:21]
	v_add_u32_e32 v102, v110, v89
	v_add_u32_e32 v110, v136, v89
	v_mfma_f32_16x16x32_bf16 v[62:65], v[116:119], v[94:97], v[62:65]
	v_mfma_f32_16x16x32_bf16 v[58:61], v[120:123], v[94:97], v[58:61]
	v_mfma_f32_16x16x32_bf16 v[54:57], v[124:127], v[94:97], v[54:57]
	v_mfma_f32_16x16x32_bf16 v[50:53], v[128:131], v[94:97], v[50:53]
	v_mfma_f32_16x16x32_bf16 v[46:49], v[116:119], v[98:101], v[46:49]
	v_mfma_f32_16x16x32_bf16 v[42:45], v[120:123], v[98:101], v[42:45]
	v_mfma_f32_16x16x32_bf16 v[38:41], v[124:127], v[98:101], v[38:41]
	v_mfma_f32_16x16x32_bf16 v[34:37], v[128:131], v[98:101], v[34:37]
	ds_read_b128 v[82:85], v102
	ds_read_b128 v[94:97], v102 offset:2048
	ds_read_b128 v[98:101], v102 offset:4096
	ds_read_b128 v[102:105], v102 offset:6144
	v_mfma_f32_16x16x32_bf16 v[14:17], v[116:119], v[106:109], v[14:17]
	v_mfma_f32_16x16x32_bf16 v[10:13], v[120:123], v[106:109], v[10:13]
	v_mfma_f32_16x16x32_bf16 v[6:9], v[124:127], v[106:109], v[6:9]
	v_mfma_f32_16x16x32_bf16 v[2:5], v[128:131], v[106:109], v[2:5]
	ds_read_b128 v[106:109], v110 offset:16384
	ds_read_b128 v[116:119], v110 offset:18432
	ds_read_b128 v[120:123], v110 offset:20480
	ds_read_b128 v[124:127], v110 offset:22528
	s_waitcnt lgkmcnt(0)
	v_mfma_f32_16x16x32_bf16 v[62:65], v[106:109], v[82:85], v[62:65]
	v_mfma_f32_16x16x32_bf16 v[58:61], v[116:119], v[82:85], v[58:61]
	v_mfma_f32_16x16x32_bf16 v[54:57], v[120:123], v[82:85], v[54:57]
	v_mfma_f32_16x16x32_bf16 v[50:53], v[124:127], v[82:85], v[50:53]
	v_mfma_f32_16x16x32_bf16 v[46:49], v[106:109], v[94:97], v[46:49]
	v_mfma_f32_16x16x32_bf16 v[42:45], v[116:119], v[94:97], v[42:45]
	v_mfma_f32_16x16x32_bf16 v[38:41], v[120:123], v[94:97], v[38:41]
	v_mfma_f32_16x16x32_bf16 v[34:37], v[124:127], v[94:97], v[34:37]
	v_mfma_f32_16x16x32_bf16 v[30:33], v[106:109], v[98:101], v[30:33]
	v_mfma_f32_16x16x32_bf16 v[26:29], v[116:119], v[98:101], v[26:29]
	v_mfma_f32_16x16x32_bf16 v[22:25], v[120:123], v[98:101], v[22:25]
	v_mfma_f32_16x16x32_bf16 v[18:21], v[124:127], v[98:101], v[18:21]
	v_mfma_f32_16x16x32_bf16 v[14:17], v[106:109], v[102:105], v[14:17]
	v_mfma_f32_16x16x32_bf16 v[10:13], v[116:119], v[102:105], v[10:13]
	v_mfma_f32_16x16x32_bf16 v[6:9], v[120:123], v[102:105], v[6:9]
	v_mfma_f32_16x16x32_bf16 v[2:5], v[124:127], v[102:105], v[2:5]
	s_cbranch_scc0 .LBB0_84
	v_add_u32_e32 v90, s29, v93
	v_add_u32_e32 v91, s29, v91
	v_add_u32_e32 v82, v90, v92
	v_add_u32_e32 v92, v91, v92
	s_waitcnt vmcnt(0)
	s_waitcnt vmcnt(0)
	s_barrier
; template <class Epi>
; DI void gemm_tile(const bf16_t* __restrict__ A, int lda, const bf16_t* __restrict__ Bt, int ldb, int K, int row0, int col0, char* lds, const Epi& epi) {
;     ...
;       for (int m = 0; m < 4; ++m)
; #pragma unroll
;         for (int n = 0; n < 4; ++n) acc[m][n] = __builtin_amdgcn_mfma_f32_16x16x32_bf16(b[n], a[m], acc[m][n], 0, 0, 0);
;     }
;   }
;   epi(acc, row0 + wr * 64, col0 + wc * 64, fr, fq);
;   DI void operator()(const f32x4 (&acc)[4][4], int r0, int c0, int fr, int fq) const {
; #pragma unroll
;     for (int m = 0; m < 4; ++m) {
;       const int row = r0 + m * 16 + fr; const int b = row / TB, s = row % TB;
;       const float* src = xsrc_row(*p, from_inputs, b, s);
;       float* dst = xdst_row(*p, b, s);
;       const float* gate = p->MOD + (size_t)(l * 9 + (s < NCTX ? 8 : b)) * 6144 + gate_off;
; #pragma unroll
;       for (int n = 0; n < 4; ++n) {
;         const int col = c0 + n * 16 + fq * 4;
;         f32x4 g = *(const f32x4*)(gate + col), xv = *(const f32x4*)(src + col);
;         *(f32x4*)(dst + col) = xv + g * acc[m][n];
;       }
;     }
	ds_read_b128 v[66:69], v82 offset:16384
	ds_read_b128 v[74:77], v82 offset:18432
	ds_read_b128 v[70:73], v92
	ds_read_b128 v[78:81], v82 offset:20480
	ds_read_b128 v[82:85], v82 offset:22528
	s_waitcnt lgkmcnt(2)
	v_mfma_f32_16x16x32_bf16 v[62:65], v[66:69], v[70:73], v[62:65]
	v_mfma_f32_16x16x32_bf16 v[58:61], v[74:77], v[70:73], v[58:61]
	s_waitcnt lgkmcnt(1)
	v_mfma_f32_16x16x32_bf16 v[54:57], v[78:81], v[70:73], v[54:57]
	s_waitcnt lgkmcnt(0)
	v_mfma_f32_16x16x32_bf16 v[50:53], v[82:85], v[70:73], v[50:53]
	ds_read_b128 v[70:73], v92 offset:2048
	s_waitcnt lgkmcnt(0)
	v_mfma_f32_16x16x32_bf16 v[46:49], v[66:69], v[70:73], v[46:49]
	v_mfma_f32_16x16x32_bf16 v[42:45], v[74:77], v[70:73], v[42:45]
	v_mfma_f32_16x16x32_bf16 v[38:41], v[78:81], v[70:73], v[38:41]
	v_mfma_f32_16x16x32_bf16 v[34:37], v[82:85], v[70:73], v[34:37]
	ds_read_b128 v[70:73], v92 offset:4096
	s_waitcnt lgkmcnt(0)
	v_mfma_f32_16x16x32_bf16 v[30:33], v[66:69], v[70:73], v[30:33]
	v_mfma_f32_16x16x32_bf16 v[26:29], v[74:77], v[70:73], v[26:29]
	v_mfma_f32_16x16x32_bf16 v[22:25], v[78:81], v[70:73], v[22:25]
	v_mfma_f32_16x16x32_bf16 v[18:21], v[82:85], v[70:73], v[18:21]
	ds_read_b128 v[70:73], v92 offset:6144
	s_waitcnt lgkmcnt(0)
	v_mfma_f32_16x16x32_bf16 v[10:13], v[74:77], v[70:73], v[10:13]
	v_add_u32_e32 v74, v90, v89
	v_add_u32_e32 v75, v91, v89
	ds_read_b128 v[90:93], v74 offset:22528
	v_mfma_f32_16x16x32_bf16 v[14:17], v[66:69], v[70:73], v[14:17]
	ds_read_b128 v[66:69], v74 offset:16384
	ds_read_b128 v[94:97], v75 offset:6144
	v_mfma_f32_16x16x32_bf16 v[6:9], v[78:81], v[70:73], v[6:9]
	ds_read_b128 v[76:79], v74 offset:18432
	v_mfma_f32_16x16x32_bf16 v[2:5], v[82:85], v[70:73], v[2:5]
	ds_read_b128 v[80:83], v74 offset:20480
	ds_read_b128 v[70:73], v75
	s_waitcnt lgkmcnt(0)
	v_mfma_f32_16x16x32_bf16 v[62:65], v[66:69], v[70:73], v[62:65]
	v_mfma_f32_16x16x32_bf16 v[58:61], v[76:79], v[70:73], v[58:61]
	v_mfma_f32_16x16x32_bf16 v[54:57], v[80:83], v[70:73], v[54:57]
	v_mfma_f32_16x16x32_bf16 v[50:53], v[90:93], v[70:73], v[50:53]
	ds_read_b128 v[70:73], v75 offset:2048
	s_waitcnt lgkmcnt(0)
	v_mfma_f32_16x16x32_bf16 v[46:49], v[66:69], v[70:73], v[46:49]
	v_mfma_f32_16x16x32_bf16 v[42:45], v[76:79], v[70:73], v[42:45]
	v_mfma_f32_16x16x32_bf16 v[38:41], v[80:83], v[70:73], v[38:41]
	v_mfma_f32_16x16x32_bf16 v[34:37], v[90:93], v[70:73], v[34:37]
	ds_read_b128 v[70:73], v75 offset:4096
	s_waitcnt lgkmcnt(0)
	v_mfma_f32_16x16x32_bf16 v[30:33], v[66:69], v[70:73], v[30:33]
	v_mfma_f32_16x16x32_bf16 v[26:29], v[76:79], v[70:73], v[26:29]
	v_mfma_f32_16x16x32_bf16 v[22:25], v[80:83], v[70:73], v[22:25]
	v_mfma_f32_16x16x32_bf16 v[18:21], v[90:93], v[70:73], v[18:21]
	v_or_b32_e32 v70, s3, v87
	v_lshl_add_u32 v74, v88, 6, v70
	v_mfma_f32_16x16x32_bf16 v[14:17], v[66:69], v[94:97], v[14:17]
	v_mul_hi_i32 v66, v74, s47
	v_lshrrev_b32_e32 v67, 31, v66
	v_ashrrev_i32_e32 v66, 9, v66
	v_mfma_f32_16x16x32_bf16 v[10:13], v[76:79], v[94:97], v[10:13]
	v_add_u32_e32 v75, v66, v67
	v_mul_i32_i24_e32 v66, 0x900, v75
	v_sub_u32_e32 v71, v74, v66
	v_mfma_f32_16x16x32_bf16 v[6:9], v[80:83], v[94:97], v[6:9]
	v_lshlrev_b32_e32 v67, 11, v75
	v_cmp_lt_i32_e32 vcc, s33, v71
	v_mov_b64_e32 v[68:69], s[64:65]
	v_mfma_f32_16x16x32_bf16 v[2:5], v[90:93], v[94:97], v[2:5]
	v_lshlrev_b32_e32 v1, 6, v1
	v_lshlrev_b32_e32 v67, 2, v86
	v_or3_b32 v80, v1, v67, s2
	v_lshlrev_b32_e32 v66, 2, v80
	v_mov_b32_e32 v67, 0
	v_mov_b32_e32 v100, s64
	v_mov_b32_e32 v101, s65
	v_mov_b32_e32 v102, s56
	v_mov_b32_e32 v103, s57
	s_add_u32 s0, s58, 0x5000
	s_addc_u32 s1, s59, 0
	v_mov_b32_e32 v108, s0
	v_mov_b32_e32 v109, s1
	v_mov_b32_e32 v110, 8
	v_mov_b32_e32 v88, v74
	v_mul_hi_i32 v89, v88, s47
	v_lshrrev_b32_e32 v90, 31, v89
	v_ashrrev_i32_e32 v89, 9, v89
	v_add_u32_e32 v91, v89, v90
	v_mul_i32_i24_e32 v89, 0x900, v91
	v_sub_u32_e32 v92, v88, v89
	v_cmp_lt_i32_e32 vcc, s33, v92
	v_lshlrev_b32_e32 v89, 11, v91
	v_add3_u32 v89, v92, v89, s75
	v_lshl_add_u32 v90, v91, 8, v92
	v_cndmask_b32_e32 v94, v90, v89, vcc
	v_ashrrev_i32_e32 v95, 31, v94
	v_lshlrev_b64 v[96:97], 12, v[94:95]
	v_lshl_add_u64 v[96:97], v[96:97], 0, v[66:67]
	v_cndmask_b32_e32 v98, v100, v102, vcc
	v_cndmask_b32_e32 v99, v101, v103, vcc
	v_lshl_add_u64 v[224:225], v[98:99], 0, v[96:97]
	v_cndmask_b32_e32 v93, v110, v91, vcc
	v_add_u32_e32 v93, s82, v93
	v_mad_i64_i32 v[240:241], s[0:1], v93, s24, v[108:109]
	s_nop 0
	v_lshl_add_u64 v[240:241], v[240:241], 0, v[66:67]
	global_load_dwordx4 v[116:119], v[240:241], off
	global_load_dwordx4 v[120:123], v[240:241], off offset:64
	global_load_dwordx4 v[124:127], v[240:241], off offset:128
	global_load_dwordx4 v[128:131], v[240:241], off offset:192
	global_load_dwordx4 v[160:163], v[224:225], off
	global_load_dwordx4 v[164:167], v[224:225], off offset:64
	global_load_dwordx4 v[168:171], v[224:225], off offset:128
	global_load_dwordx4 v[172:175], v[224:225], off offset:192
	v_or_b32_e32 v88, 16, v74
	v_mul_hi_i32 v89, v88, s47
	v_lshrrev_b32_e32 v90, 31, v89
	v_ashrrev_i32_e32 v89, 9, v89
	v_add_u32_e32 v91, v89, v90
	v_mul_i32_i24_e32 v89, 0x900, v91
	v_sub_u32_e32 v92, v88, v89
	v_cmp_lt_i32_e32 vcc, s33, v92
	v_lshlrev_b32_e32 v89, 11, v91
	v_add3_u32 v89, v92, v89, s75
	v_lshl_add_u32 v90, v91, 8, v92
	v_cndmask_b32_e32 v94, v90, v89, vcc
;   DI void operator()(const f32x4 (&acc)[4][4], int r0, int c0, int fr, int fq) const {
; #pragma unroll
;     for (int m = 0; m < 4; ++m) {
;       const int row = r0 + m * 16 + fr; const int b = row / TB, s = row % TB;
;       const float* src = xsrc_row(*p, from_inputs, b, s);
;       float* dst = xdst_row(*p, b, s);
;       const float* gate = p->MOD + (size_t)(l * 9 + (s < NCTX ? 8 : b)) * 6144 + gate_off;
; #pragma unroll
;       for (int n = 0; n < 4; ++n) {
;         const int col = c0 + n * 16 + fq * 4;
;         f32x4 g = *(const f32x4*)(gate + col), xv = *(const f32x4*)(src + col);
;         *(f32x4*)(dst + col) = xv + g * acc[m][n];
;       }
;     }
	v_ashrrev_i32_e32 v95, 31, v94
	v_lshlrev_b64 v[96:97], 12, v[94:95]
	v_lshl_add_u64 v[96:97], v[96:97], 0, v[66:67]
	v_cndmask_b32_e32 v98, v100, v102, vcc
	v_cndmask_b32_e32 v99, v101, v103, vcc
	v_lshl_add_u64 v[226:227], v[98:99], 0, v[96:97]
	global_load_dwordx4 v[176:179], v[226:227], off
	global_load_dwordx4 v[180:183], v[226:227], off offset:64
	global_load_dwordx4 v[184:187], v[226:227], off offset:128
	global_load_dwordx4 v[188:191], v[226:227], off offset:192
	v_or_b32_e32 v88, 32, v74
	v_mul_hi_i32 v89, v88, s47
	v_lshrrev_b32_e32 v90, 31, v89
	v_ashrrev_i32_e32 v89, 9, v89
	v_add_u32_e32 v91, v89, v90
	v_mul_i32_i24_e32 v89, 0x900, v91
	v_sub_u32_e32 v92, v88, v89
	v_cmp_lt_i32_e32 vcc, s33, v92
	v_lshlrev_b32_e32 v89, 11, v91
	v_add3_u32 v89, v92, v89, s75
	v_lshl_add_u32 v90, v91, 8, v92
	v_cndmask_b32_e32 v94, v90, v89, vcc
	v_ashrrev_i32_e32 v95, 31, v94
	v_lshlrev_b64 v[96:97], 12, v[94:95]
	v_lshl_add_u64 v[96:97], v[96:97], 0, v[66:67]
	v_cndmask_b32_e32 v98, v100, v102, vcc
	v_cndmask_b32_e32 v99, v101, v103, vcc
	v_lshl_add_u64 v[228:229], v[98:99], 0, v[96:97]
	global_load_dwordx4 v[192:195], v[228:229], off
	global_load_dwordx4 v[196:199], v[228:229], off offset:64
	global_load_dwordx4 v[200:203], v[228:229], off offset:128
	global_load_dwordx4 v[204:207], v[228:229], off offset:192
	v_or_b32_e32 v88, 48, v74
	v_mul_hi_i32 v89, v88, s47
	v_lshrrev_b32_e32 v90, 31, v89
	v_ashrrev_i32_e32 v89, 9, v89
	v_add_u32_e32 v91, v89, v90
	v_mul_i32_i24_e32 v89, 0x900, v91
	v_sub_u32_e32 v92, v88, v89
	v_cmp_lt_i32_e32 vcc, s33, v92
	v_lshlrev_b32_e32 v89, 11, v91
	v_add3_u32 v89, v92, v89, s75
	v_lshl_add_u32 v90, v91, 8, v92
	v_cndmask_b32_e32 v94, v90, v89, vcc
	v_ashrrev_i32_e32 v95, 31, v94
	v_lshlrev_b64 v[96:97], 12, v[94:95]
	v_lshl_add_u64 v[96:97], v[96:97], 0, v[66:67]
	v_cndmask_b32_e32 v98, v100, v102, vcc
	v_cndmask_b32_e32 v99, v101, v103, vcc
	v_lshl_add_u64 v[230:231], v[98:99], 0, v[96:97]
	global_load_dwordx4 v[208:211], v[230:231], off
	global_load_dwordx4 v[212:215], v[230:231], off offset:64
	global_load_dwordx4 v[216:219], v[230:231], off offset:128
	global_load_dwordx4 v[220:223], v[230:231], off offset:192
	s_waitcnt vmcnt(15)
	v_pk_fma_f32 v[64:65], v[64:65], v[118:119], v[162:163]
	v_pk_fma_f32 v[62:63], v[62:63], v[116:117], v[160:161]
	global_store_dwordx4 v[224:225], v[62:65], off
	s_waitcnt vmcnt(15)
	v_pk_fma_f32 v[60:61], v[60:61], v[122:123], v[166:167]
	v_pk_fma_f32 v[58:59], v[58:59], v[120:121], v[164:165]
	global_store_dwordx4 v[224:225], v[58:61], off offset:64
	s_waitcnt vmcnt(15)
	v_pk_fma_f32 v[56:57], v[56:57], v[126:127], v[170:171]
	v_pk_fma_f32 v[54:55], v[54:55], v[124:125], v[168:169]
	global_store_dwordx4 v[224:225], v[54:57], off offset:128
	s_waitcnt vmcnt(15)
	v_pk_fma_f32 v[52:53], v[52:53], v[130:131], v[174:175]
	v_pk_fma_f32 v[50:51], v[50:51], v[128:129], v[172:173]
	global_store_dwordx4 v[224:225], v[50:53], off offset:192
	s_waitcnt vmcnt(15)
	v_pk_fma_f32 v[48:49], v[48:49], v[118:119], v[178:179]
	v_pk_fma_f32 v[46:47], v[46:47], v[116:117], v[176:177]
	global_store_dwordx4 v[226:227], v[46:49], off
	s_waitcnt vmcnt(15)
	v_pk_fma_f32 v[44:45], v[44:45], v[122:123], v[182:183]
	v_pk_fma_f32 v[42:43], v[42:43], v[120:121], v[180:181]
	global_store_dwordx4 v[226:227], v[42:45], off offset:64
	s_waitcnt vmcnt(15)
	v_pk_fma_f32 v[40:41], v[40:41], v[126:127], v[186:187]
	v_pk_fma_f32 v[38:39], v[38:39], v[124:125], v[184:185]
	global_store_dwordx4 v[226:227], v[38:41], off offset:128
	s_waitcnt vmcnt(15)
	v_pk_fma_f32 v[36:37], v[36:37], v[130:131], v[190:191]
	v_pk_fma_f32 v[34:35], v[34:35], v[128:129], v[188:189]
	global_store_dwordx4 v[226:227], v[34:37], off offset:192
	s_waitcnt vmcnt(15)
	v_pk_fma_f32 v[32:33], v[32:33], v[118:119], v[194:195]
	v_pk_fma_f32 v[30:31], v[30:31], v[116:117], v[192:193]
	global_store_dwordx4 v[228:229], v[30:33], off
	s_waitcnt vmcnt(15)
	v_pk_fma_f32 v[28:29], v[28:29], v[122:123], v[198:199]
	v_pk_fma_f32 v[26:27], v[26:27], v[120:121], v[196:197]
	global_store_dwordx4 v[228:229], v[26:29], off offset:64
	s_waitcnt vmcnt(15)
	v_pk_fma_f32 v[24:25], v[24:25], v[126:127], v[202:203]
	v_pk_fma_f32 v[22:23], v[22:23], v[124:125], v[200:201]
	global_store_dwordx4 v[228:229], v[22:25], off offset:128
	s_waitcnt vmcnt(15)
	v_pk_fma_f32 v[20:21], v[20:21], v[130:131], v[206:207]
	v_pk_fma_f32 v[18:19], v[18:19], v[128:129], v[204:205]
	global_store_dwordx4 v[228:229], v[18:21], off offset:192
	s_waitcnt vmcnt(15)
	v_pk_fma_f32 v[16:17], v[16:17], v[118:119], v[210:211]
	v_pk_fma_f32 v[14:15], v[14:15], v[116:117], v[208:209]
	global_store_dwordx4 v[230:231], v[14:17], off
	s_waitcnt vmcnt(15)
	v_pk_fma_f32 v[12:13], v[12:13], v[122:123], v[214:215]
	v_pk_fma_f32 v[10:11], v[10:11], v[120:121], v[212:213]
	global_store_dwordx4 v[230:231], v[10:13], off offset:64
	s_waitcnt vmcnt(15)
	v_pk_fma_f32 v[8:9], v[8:9], v[126:127], v[218:219]
	v_pk_fma_f32 v[6:7], v[6:7], v[124:125], v[216:217]
	global_store_dwordx4 v[230:231], v[6:9], off offset:128
	s_waitcnt vmcnt(15)
	v_pk_fma_f32 v[4:5], v[4:5], v[130:131], v[222:223]
	v_pk_fma_f32 v[2:3], v[2:3], v[128:129], v[220:221]
	global_store_dwordx4 v[230:231], v[2:5], off offset:192
	s_add_i32 s27, s27, 1
	s_mov_b64 s[0:1], 0
	s_branch .LBB0_71

; DI int lat_tile(int i) { return (i >> 4) * 18 + 2 + (i & 15); }
; template <int KSEL> DI void run_phase(const Params& p, int ph, char* lds) {
;     ...
;       EpiRes e{&p, l, l == 0, 2 * 1024};
;       const int nm = last ? 128 : 144;
;       for (int i = 0, tm, tn; xcd_tile(bid, G, i, nm, 8, tm, tn); ++i) gemm_tile(p.HY, DM, p.Wout, DM, DM, (last ? lat_tile(tm) : tm) * 128, tn * 128, lds, e);
.LBB0_250:
	s_andn2_b64 vcc, exec, s[0:1]
	s_cbranch_vccnz .LBB0_356
	s_cmp_gt_i32 s44, 5
	s_mov_b64 s[0:1], -1
	s_cbranch_scc0 .LBB0_333
	s_add_i32 s0, s77, 7
	s_cmp_gt_u32 s0, 16
	v_readlane_b32 s0, v250, 4
	v_readlane_b32 s1, v250, 5
	s_cselect_b64 s[38:39], -1, 0
	s_and_b64 s[0:1], s[0:1], exec
	s_movk_i32 s0, 0x80
	s_cselect_b32 s26, s0, 0x90
	v_cvt_f32_ubyte0_e32 v1, s26
	v_rcp_iflag_f32_e32 v1, v1
	s_lshr_b32 s40, s26, 3
	v_readlane_b32 s0, v251, 50
	s_mul_i32 s40, s40, s0
	v_mul_f32_e32 v1, 0x4f7ffffe, v1
	v_cvt_u32_f32_e32 v1, v1
	s_sub_i32 s0, 0, s26
	s_mov_b32 s45, s44
	s_lshl_b32 s27, s26, 3
	v_readfirstlane_b32 s1, v1
	s_mul_i32 s0, s0, s1
	s_mul_hi_u32 s0, s1, s0
	s_mov_b32 s41, 0
	s_add_i32 s42, s1, s0
	s_branch .LBB0_255
.LBB0_254:
	s_and_b64 vcc, exec, s[0:1]
	s_mov_b32 s29, s44
	s_mov_b32 s28, s43
	s_cbranch_vccnz .LBB0_332

; template <class Epi>
; DI void gemm_tile(const bf16_t* __restrict__ A, int lda, const bf16_t* __restrict__ Bt, int ldb, int K, int row0, int col0, char* lds, const Epi& epi) {
;     ...
;   for (int kt = 0; kt < KT; ++kt) {
;     asm volatile("s_waitcnt vmcnt(0)" ::: "memory");
;     __syncthreads();
;     const char* sa = lds + (kt & 1) * 32768 + (wr * 64 + fr) * 128;
;     const char* sb = lds + (kt & 1) * 32768 + 16384 + (wc * 64 + fr) * 128;
; #pragma unroll
;     for (int kk = 0; kk < 2; ++kk) {
;       if (kt + 1 < KT) { if (kk == 0) stage_a(kt + 1, (kt + 1) & 1); else stage_b(kt + 1, (kt + 1) & 1); }
;       bf16x8 a[4], b[4];
;       const int co = ((kk * 4 + fq) ^ swz) * 16;
; #pragma unroll
;       for (int m = 0; m < 4; ++m) a[m] = *(const bf16x8*)(sa + m * 2048 + co);
; #pragma unroll
;       for (int n = 0; n < 4; ++n) b[n] = *(const bf16x8*)(sb + n * 2048 + co);
; #pragma unroll
;       for (int m = 0; m < 4; ++m)
; #pragma unroll
;         for (int n = 0; n < 4; ++n) acc[m][n] = __builtin_amdgcn_mfma_f32_16x16x32_bf16(b[n], a[m], acc[m][n], 0, 0, 0);
;     }
;   }
.LBB0_267:
	s_add_i32 s20, s3, 0xffff8000
	s_and_b32 s29, s3, 0x8000
	s_and_b32 s20, s20, 0x8000
	v_add_u32_e32 v102, s29, v90
	v_add_u32_e32 v110, s20, v91
	v_or_b32_e32 v136, s20, v93
	v_add_u32_e32 v103, 0x1000, v102
	v_readfirstlane_b32 s20, v102
	v_lshl_add_u64 v[94:95], v[74:75], 0, s[0:1]
	v_add_u32_e32 v104, 0x2000, v102
	s_mov_b32 m0, s20
	v_readfirstlane_b32 s20, v103
	s_waitcnt vmcnt(0)
	s_waitcnt vmcnt(0) lgkmcnt(0)
	s_barrier
	v_lshl_add_u64 v[96:97], v[76:77], 0, s[0:1]
	v_add_u32_e32 v105, 0x3000, v102
	global_load_lds_dwordx4 v[94:95], off
	s_mov_b32 m0, s20
	v_readfirstlane_b32 s20, v104
	v_add_u32_e32 v137, 0x4000, v102
	v_lshl_add_u64 v[98:99], v[78:79], 0, s[0:1]
	global_load_lds_dwordx4 v[96:97], off
	s_mov_b32 m0, s20
	v_readfirstlane_b32 s20, v105
	v_add_u32_e32 v159, 0x5000, v102
	v_lshl_add_u64 v[100:101], v[80:81], 0, s[0:1]
	global_load_lds_dwordx4 v[98:99], off
	s_mov_b32 m0, s20
	v_readfirstlane_b32 s20, v137
	v_lshl_add_u64 v[132:133], v[66:67], 0, s[0:1]
	v_add_u32_e32 v160, 0x6000, v102
	global_load_lds_dwordx4 v[100:101], off
	v_add_u32_e32 v106, v110, v92
	v_add_u32_e32 v128, v136, v92
	s_mov_b32 m0, s20
	v_readfirstlane_b32 s20, v159
	v_lshl_add_u64 v[134:135], v[68:69], 0, s[0:1]
	v_add_u32_e32 v161, 0x7000, v102
	ds_read_b128 v[94:97], v106
	ds_read_b128 v[98:101], v106 offset:2048
	ds_read_b128 v[102:105], v106 offset:4096
	ds_read_b128 v[106:109], v106 offset:6144
	ds_read_b128 v[116:119], v128 offset:16384
	ds_read_b128 v[120:123], v128 offset:18432
	ds_read_b128 v[124:127], v128 offset:20480
	ds_read_b128 v[128:131], v128 offset:22528
	global_load_lds_dwordx4 v[132:133], off
	s_mov_b32 m0, s20
	v_readfirstlane_b32 s20, v160
	v_lshl_add_u64 v[84:85], v[70:71], 0, s[0:1]
	global_load_lds_dwordx4 v[134:135], off
	s_mov_b32 m0, s20
	v_readfirstlane_b32 s20, v161
	v_lshl_add_u64 v[82:83], v[72:73], 0, s[0:1]
	global_load_lds_dwordx4 v[84:85], off
	s_mov_b32 m0, s20
	s_waitcnt lgkmcnt(0)
	v_mfma_f32_16x16x32_bf16 v[30:33], v[116:119], v[102:105], v[30:33]
	global_load_lds_dwordx4 v[82:83], off
	s_add_u32 s0, s0, 0x80
	v_mfma_f32_16x16x32_bf16 v[26:29], v[120:123], v[102:105], v[26:29]
	s_addc_u32 s1, s1, 0
	s_add_i32 s3, s3, 0x8000
	s_cmpk_eq_i32 s0, 0x780
	v_mfma_f32_16x16x32_bf16 v[22:25], v[124:127], v[102:105], v[22:25]
	v_mfma_f32_16x16x32_bf16 v[18:21], v[128:131], v[102:105], v[18:21]
	v_add_u32_e32 v102, v110, v89
	v_add_u32_e32 v110, v136, v89
	v_mfma_f32_16x16x32_bf16 v[62:65], v[116:119], v[94:97], v[62:65]
	v_mfma_f32_16x16x32_bf16 v[58:61], v[120:123], v[94:97], v[58:61]
	v_mfma_f32_16x16x32_bf16 v[54:57], v[124:127], v[94:97], v[54:57]
	v_mfma_f32_16x16x32_bf16 v[50:53], v[128:131], v[94:97], v[50:53]
	v_mfma_f32_16x16x32_bf16 v[46:49], v[116:119], v[98:101], v[46:49]
	v_mfma_f32_16x16x32_bf16 v[42:45], v[120:123], v[98:101], v[42:45]
	v_mfma_f32_16x16x32_bf16 v[38:41], v[124:127], v[98:101], v[38:41]
	v_mfma_f32_16x16x32_bf16 v[34:37], v[128:131], v[98:101], v[34:37]
	ds_read_b128 v[82:85], v102
	ds_read_b128 v[94:97], v102 offset:2048
	ds_read_b128 v[98:101], v102 offset:4096
	ds_read_b128 v[102:105], v102 offset:6144
	v_mfma_f32_16x16x32_bf16 v[14:17], v[116:119], v[106:109], v[14:17]
	v_mfma_f32_16x16x32_bf16 v[10:13], v[120:123], v[106:109], v[10:13]
	v_mfma_f32_16x16x32_bf16 v[6:9], v[124:127], v[106:109], v[6:9]
	v_mfma_f32_16x16x32_bf16 v[2:5], v[128:131], v[106:109], v[2:5]
	ds_read_b128 v[106:109], v110 offset:16384
	ds_read_b128 v[116:119], v110 offset:18432
	ds_read_b128 v[120:123], v110 offset:20480
	ds_read_b128 v[124:127], v110 offset:22528
	s_waitcnt lgkmcnt(0)
	v_mfma_f32_16x16x32_bf16 v[62:65], v[106:109], v[82:85], v[62:65]
	v_mfma_f32_16x16x32_bf16 v[58:61], v[116:119], v[82:85], v[58:61]
	v_mfma_f32_16x16x32_bf16 v[54:57], v[120:123], v[82:85], v[54:57]
	v_mfma_f32_16x16x32_bf16 v[50:53], v[124:127], v[82:85], v[50:53]
	v_mfma_f32_16x16x32_bf16 v[46:49], v[106:109], v[94:97], v[46:49]
	v_mfma_f32_16x16x32_bf16 v[42:45], v[116:119], v[94:97], v[42:45]
	v_mfma_f32_16x16x32_bf16 v[38:41], v[120:123], v[94:97], v[38:41]
	v_mfma_f32_16x16x32_bf16 v[34:37], v[124:127], v[94:97], v[34:37]
	v_mfma_f32_16x16x32_bf16 v[30:33], v[106:109], v[98:101], v[30:33]
	v_mfma_f32_16x16x32_bf16 v[26:29], v[116:119], v[98:101], v[26:29]
	v_mfma_f32_16x16x32_bf16 v[22:25], v[120:123], v[98:101], v[22:25]
	v_mfma_f32_16x16x32_bf16 v[18:21], v[124:127], v[98:101], v[18:21]
	v_mfma_f32_16x16x32_bf16 v[14:17], v[106:109], v[102:105], v[14:17]
	v_mfma_f32_16x16x32_bf16 v[10:13], v[116:119], v[102:105], v[10:13]
	v_mfma_f32_16x16x32_bf16 v[6:9], v[120:123], v[102:105], v[6:9]
	v_mfma_f32_16x16x32_bf16 v[2:5], v[124:127], v[102:105], v[2:5]
	s_cbranch_scc0 .LBB0_267
	v_add_u32_e32 v90, s29, v93
	v_add_u32_e32 v91, s29, v91
	v_add_u32_e32 v82, v90, v92
	v_add_u32_e32 v92, v91, v92
	s_waitcnt vmcnt(0)
	s_waitcnt vmcnt(0)
	s_barrier
; DI const float* xsrc_row(const Params& p, bool from_inputs, int b, int s) {
;   if (from_inputs) return s < NCTX ? p.ctx + (size_t)(b * NCTX + s) * DM : p.x + (size_t)(b * NLAT + s - NCTX) * DM;
;   return s < NCTX ? p.XCTX + (size_t)(b * NCTX + s) * DM : p.out + (size_t)(b * NLAT + s - NCTX) * DM;
; }
;   DI void operator()(const f32x4 (&acc)[4][4], int r0, int c0, int fr, int fq) const {
; #pragma unroll
;     for (int m = 0; m < 4; ++m) {
;       const int row = r0 + m * 16 + fr; const int b = row / TB, s = row % TB;
;       const float* src = xsrc_row(*p, from_inputs, b, s);
;       float* dst = xdst_row(*p, b, s);
;       const float* gate = p->MOD + (size_t)(l * 9 + (s < NCTX ? 8 : b)) * 6144 + gate_off;
; #pragma unroll
;       for (int n = 0; n < 4; ++n) {
;         const int col = c0 + n * 16 + fq * 4;
;         f32x4 g = *(const f32x4*)(gate + col), xv = *(const f32x4*)(src + col);
;         *(f32x4*)(dst + col) = xv + g * acc[m][n];
;       }
;     }
	ds_read_b128 v[66:69], v82 offset:16384
	ds_read_b128 v[74:77], v82 offset:18432
	ds_read_b128 v[70:73], v92
	ds_read_b128 v[78:81], v82 offset:20480
	ds_read_b128 v[82:85], v82 offset:22528
	s_waitcnt lgkmcnt(2)
	v_mfma_f32_16x16x32_bf16 v[62:65], v[66:69], v[70:73], v[62:65]
	s_and_b64 vcc, exec, s[38:39]
	v_mfma_f32_16x16x32_bf16 v[58:61], v[74:77], v[70:73], v[58:61]
	s_waitcnt lgkmcnt(1)
	v_mfma_f32_16x16x32_bf16 v[54:57], v[78:81], v[70:73], v[54:57]
	s_waitcnt lgkmcnt(0)
	v_mfma_f32_16x16x32_bf16 v[50:53], v[82:85], v[70:73], v[50:53]
	ds_read_b128 v[70:73], v92 offset:2048
	s_waitcnt lgkmcnt(0)
	v_mfma_f32_16x16x32_bf16 v[46:49], v[66:69], v[70:73], v[46:49]
	v_mfma_f32_16x16x32_bf16 v[42:45], v[74:77], v[70:73], v[42:45]
	v_mfma_f32_16x16x32_bf16 v[38:41], v[78:81], v[70:73], v[38:41]
	v_mfma_f32_16x16x32_bf16 v[34:37], v[82:85], v[70:73], v[34:37]
	ds_read_b128 v[70:73], v92 offset:4096
	s_waitcnt lgkmcnt(0)
	v_mfma_f32_16x16x32_bf16 v[30:33], v[66:69], v[70:73], v[30:33]
	v_mfma_f32_16x16x32_bf16 v[26:29], v[74:77], v[70:73], v[26:29]
	v_mfma_f32_16x16x32_bf16 v[22:25], v[78:81], v[70:73], v[22:25]
	v_mfma_f32_16x16x32_bf16 v[18:21], v[82:85], v[70:73], v[18:21]
	ds_read_b128 v[70:73], v92 offset:6144
	s_waitcnt lgkmcnt(0)
	v_mfma_f32_16x16x32_bf16 v[10:13], v[74:77], v[70:73], v[10:13]
	v_add_u32_e32 v74, v90, v89
	v_add_u32_e32 v75, v91, v89
	ds_read_b128 v[90:93], v74 offset:22528
	v_mfma_f32_16x16x32_bf16 v[14:17], v[66:69], v[70:73], v[14:17]
	ds_read_b128 v[66:69], v74 offset:16384
	v_mfma_f32_16x16x32_bf16 v[6:9], v[78:81], v[70:73], v[6:9]
	ds_read_b128 v[76:79], v74 offset:18432
	v_mfma_f32_16x16x32_bf16 v[2:5], v[82:85], v[70:73], v[2:5]
	ds_read_b128 v[80:83], v74 offset:20480
	ds_read_b128 v[70:73], v75
	v_or_b32_e32 v74, s2, v87
	s_waitcnt lgkmcnt(0)
	v_mfma_f32_16x16x32_bf16 v[62:65], v[66:69], v[70:73], v[62:65]
	v_lshl_add_u32 v74, v88, 6, v74
	s_mov_b64 s[2:3], -1
	v_mfma_f32_16x16x32_bf16 v[58:61], v[76:79], v[70:73], v[58:61]
	v_mfma_f32_16x16x32_bf16 v[54:57], v[80:83], v[70:73], v[54:57]
	v_mfma_f32_16x16x32_bf16 v[50:53], v[90:93], v[70:73], v[50:53]
	ds_read_b128 v[70:73], v75 offset:2048
	s_waitcnt lgkmcnt(0)
	v_mfma_f32_16x16x32_bf16 v[46:49], v[66:69], v[70:73], v[46:49]
	v_mfma_f32_16x16x32_bf16 v[42:45], v[76:79], v[70:73], v[42:45]
	v_mfma_f32_16x16x32_bf16 v[38:41], v[80:83], v[70:73], v[38:41]
	v_mfma_f32_16x16x32_bf16 v[34:37], v[90:93], v[70:73], v[34:37]
	ds_read_b128 v[70:73], v75 offset:4096
	s_waitcnt lgkmcnt(0)
	v_mfma_f32_16x16x32_bf16 v[30:33], v[66:69], v[70:73], v[30:33]
	v_mfma_f32_16x16x32_bf16 v[26:29], v[76:79], v[70:73], v[26:29]
	v_mfma_f32_16x16x32_bf16 v[22:25], v[80:83], v[70:73], v[22:25]
	v_mfma_f32_16x16x32_bf16 v[18:21], v[90:93], v[70:73], v[18:21]
	ds_read_b128 v[70:73], v75 offset:6144
	s_waitcnt lgkmcnt(0)
	v_mfma_f32_16x16x32_bf16 v[14:17], v[66:69], v[70:73], v[14:17]
	v_mul_hi_i32 v66, v74, s47
	v_lshrrev_b32_e32 v67, 31, v66
	v_ashrrev_i32_e32 v66, 9, v66
	v_mfma_f32_16x16x32_bf16 v[10:13], v[76:79], v[70:73], v[10:13]
	v_add_u32_e32 v75, v66, v67
	v_mul_i32_i24_e32 v66, 0x900, v75
	v_sub_u32_e32 v67, v74, v66
	v_mfma_f32_16x16x32_bf16 v[6:9], v[80:83], v[70:73], v[6:9]
	v_cmp_lt_i32_e64 s[0:1], s33, v67
	v_mfma_f32_16x16x32_bf16 v[2:5], v[90:93], v[70:73], v[2:5]
	v_readlane_b32 s4, v254, 28
	v_readlane_b32 s5, v254, 29
	v_readlane_b32 s8, v254, 32
	v_readlane_b32 s9, v254, 33
	s_nop 3
	s_cmp_lg_u64 s[38:39], 0
	s_cselect_b32 s4, s56, s4
	s_cselect_b32 s5, s57, s5
	s_cselect_b32 s8, s64, s8
	s_cselect_b32 s9, s65, s9
	v_lshlrev_b32_e32 v1, 6, v1
	v_lshlrev_b32_e32 v67, 2, v86
	v_or3_b32 v80, v1, v67, s28
	v_lshlrev_b32_e32 v66, 2, v80
	v_mov_b32_e32 v67, 0
	v_mov_b32_e32 v100, s8
	v_mov_b32_e32 v101, s9
	v_mov_b32_e32 v102, s4
	v_mov_b32_e32 v103, s5
	v_mov_b32_e32 v104, s64
	v_mov_b32_e32 v105, s65
	v_mov_b32_e32 v106, s56
	v_mov_b32_e32 v107, s57
	s_add_u32 s0, s58, 0x2000
	s_addc_u32 s1, s59, 0
	v_mov_b32_e32 v108, s0
	v_mov_b32_e32 v109, s1
	v_mov_b32_e32 v110, 8
	v_mov_b32_e32 v88, v74
	v_mul_hi_i32 v89, v88, s47
	v_lshrrev_b32_e32 v90, 31, v89
	v_ashrrev_i32_e32 v89, 9, v89
	v_add_u32_e32 v91, v89, v90
	v_mul_i32_i24_e32 v89, 0x900, v91
	v_sub_u32_e32 v92, v88, v89
	v_cmp_lt_i32_e32 vcc, s33, v92
	v_lshlrev_b32_e32 v89, 11, v91
	v_add3_u32 v89, v92, v89, s75
	v_lshl_add_u32 v90, v91, 8, v92
	v_cndmask_b32_e32 v94, v90, v89, vcc
	v_ashrrev_i32_e32 v95, 31, v94
	v_lshlrev_b64 v[96:97], 12, v[94:95]
	v_lshl_add_u64 v[96:97], v[96:97], 0, v[66:67]
	v_cndmask_b32_e32 v98, v100, v102, vcc
	v_cndmask_b32_e32 v99, v101, v103, vcc
	v_lshl_add_u64 v[224:225], v[98:99], 0, v[96:97]
	v_cndmask_b32_e32 v98, v104, v106, vcc
	v_cndmask_b32_e32 v99, v105, v107, vcc
	v_lshl_add_u64 v[232:233], v[98:99], 0, v[96:97]
	v_cndmask_b32_e32 v93, v110, v91, vcc
	v_add_u32_e32 v93, s82, v93
	v_mad_i64_i32 v[240:241], s[0:1], v93, s24, v[108:109]
	s_nop 0
	v_lshl_add_u64 v[240:241], v[240:241], 0, v[66:67]
	global_load_dwordx4 v[116:119], v[240:241], off
	global_load_dwordx4 v[120:123], v[240:241], off offset:64
	global_load_dwordx4 v[124:127], v[240:241], off offset:128
	global_load_dwordx4 v[128:131], v[240:241], off offset:192
	global_load_dwordx4 v[160:163], v[224:225], off
	global_load_dwordx4 v[164:167], v[224:225], off offset:64
	global_load_dwordx4 v[168:171], v[224:225], off offset:128
	global_load_dwordx4 v[172:175], v[224:225], off offset:192
	v_or_b32_e32 v88, 16, v74
	v_mul_hi_i32 v89, v88, s47
	v_lshrrev_b32_e32 v90, 31, v89
	v_ashrrev_i32_e32 v89, 9, v89
	v_add_u32_e32 v91, v89, v90
	v_mul_i32_i24_e32 v89, 0x900, v91
	v_sub_u32_e32 v92, v88, v89
	v_cmp_lt_i32_e32 vcc, s33, v92
;   DI void operator()(const f32x4 (&acc)[4][4], int r0, int c0, int fr, int fq) const {
; #pragma unroll
;     for (int m = 0; m < 4; ++m) {
;       const int row = r0 + m * 16 + fr; const int b = row / TB, s = row % TB;
;       const float* src = xsrc_row(*p, from_inputs, b, s);
;       float* dst = xdst_row(*p, b, s);
;       const float* gate = p->MOD + (size_t)(l * 9 + (s < NCTX ? 8 : b)) * 6144 + gate_off;
; #pragma unroll
;       for (int n = 0; n < 4; ++n) {
;         const int col = c0 + n * 16 + fq * 4;
;         f32x4 g = *(const f32x4*)(gate + col), xv = *(const f32x4*)(src + col);
;         *(f32x4*)(dst + col) = xv + g * acc[m][n];
;       }
;     }
	v_lshlrev_b32_e32 v89, 11, v91
	v_add3_u32 v89, v92, v89, s75
	v_lshl_add_u32 v90, v91, 8, v92
	v_cndmask_b32_e32 v94, v90, v89, vcc
	v_ashrrev_i32_e32 v95, 31, v94
	v_lshlrev_b64 v[96:97], 12, v[94:95]
	v_lshl_add_u64 v[96:97], v[96:97], 0, v[66:67]
	v_cndmask_b32_e32 v98, v100, v102, vcc
	v_cndmask_b32_e32 v99, v101, v103, vcc
	v_lshl_add_u64 v[226:227], v[98:99], 0, v[96:97]
	v_cndmask_b32_e32 v98, v104, v106, vcc
	v_cndmask_b32_e32 v99, v105, v107, vcc
	v_lshl_add_u64 v[234:235], v[98:99], 0, v[96:97]
	global_load_dwordx4 v[176:179], v[226:227], off
	global_load_dwordx4 v[180:183], v[226:227], off offset:64
	global_load_dwordx4 v[184:187], v[226:227], off offset:128
	global_load_dwordx4 v[188:191], v[226:227], off offset:192
	v_or_b32_e32 v88, 32, v74
	v_mul_hi_i32 v89, v88, s47
	v_lshrrev_b32_e32 v90, 31, v89
	v_ashrrev_i32_e32 v89, 9, v89
	v_add_u32_e32 v91, v89, v90
	v_mul_i32_i24_e32 v89, 0x900, v91
	v_sub_u32_e32 v92, v88, v89
	v_cmp_lt_i32_e32 vcc, s33, v92
	v_lshlrev_b32_e32 v89, 11, v91
	v_add3_u32 v89, v92, v89, s75
	v_lshl_add_u32 v90, v91, 8, v92
	v_cndmask_b32_e32 v94, v90, v89, vcc
	v_ashrrev_i32_e32 v95, 31, v94
	v_lshlrev_b64 v[96:97], 12, v[94:95]
	v_lshl_add_u64 v[96:97], v[96:97], 0, v[66:67]
	v_cndmask_b32_e32 v98, v100, v102, vcc
	v_cndmask_b32_e32 v99, v101, v103, vcc
	v_lshl_add_u64 v[228:229], v[98:99], 0, v[96:97]
	v_cndmask_b32_e32 v98, v104, v106, vcc
	v_cndmask_b32_e32 v99, v105, v107, vcc
	v_lshl_add_u64 v[236:237], v[98:99], 0, v[96:97]
	global_load_dwordx4 v[192:195], v[228:229], off
	global_load_dwordx4 v[196:199], v[228:229], off offset:64
	global_load_dwordx4 v[200:203], v[228:229], off offset:128
	global_load_dwordx4 v[204:207], v[228:229], off offset:192
	v_or_b32_e32 v88, 48, v74
	v_mul_hi_i32 v89, v88, s47
	v_lshrrev_b32_e32 v90, 31, v89
	v_ashrrev_i32_e32 v89, 9, v89
	v_add_u32_e32 v91, v89, v90
	v_mul_i32_i24_e32 v89, 0x900, v91
	v_sub_u32_e32 v92, v88, v89
	v_cmp_lt_i32_e32 vcc, s33, v92
	v_lshlrev_b32_e32 v89, 11, v91
	v_add3_u32 v89, v92, v89, s75
	v_lshl_add_u32 v90, v91, 8, v92
	v_cndmask_b32_e32 v94, v90, v89, vcc
	v_ashrrev_i32_e32 v95, 31, v94
	v_lshlrev_b64 v[96:97], 12, v[94:95]
	v_lshl_add_u64 v[96:97], v[96:97], 0, v[66:67]
	v_cndmask_b32_e32 v98, v100, v102, vcc
	v_cndmask_b32_e32 v99, v101, v103, vcc
	v_lshl_add_u64 v[230:231], v[98:99], 0, v[96:97]
	v_cndmask_b32_e32 v98, v104, v106, vcc
	v_cndmask_b32_e32 v99, v105, v107, vcc
	v_lshl_add_u64 v[238:239], v[98:99], 0, v[96:97]
	global_load_dwordx4 v[208:211], v[230:231], off
	global_load_dwordx4 v[212:215], v[230:231], off offset:64
	global_load_dwordx4 v[216:219], v[230:231], off offset:128
	global_load_dwordx4 v[220:223], v[230:231], off offset:192
	s_waitcnt vmcnt(15)
	v_pk_fma_f32 v[64:65], v[64:65], v[118:119], v[162:163]
	v_pk_fma_f32 v[62:63], v[62:63], v[116:117], v[160:161]
	global_store_dwordx4 v[232:233], v[62:65], off
	s_waitcnt vmcnt(15)
	v_pk_fma_f32 v[60:61], v[60:61], v[122:123], v[166:167]
	v_pk_fma_f32 v[58:59], v[58:59], v[120:121], v[164:165]
	global_store_dwordx4 v[232:233], v[58:61], off offset:64
	s_waitcnt vmcnt(15)
	v_pk_fma_f32 v[56:57], v[56:57], v[126:127], v[170:171]
	v_pk_fma_f32 v[54:55], v[54:55], v[124:125], v[168:169]
	global_store_dwordx4 v[232:233], v[54:57], off offset:128
	s_waitcnt vmcnt(15)
	v_pk_fma_f32 v[52:53], v[52:53], v[130:131], v[174:175]
	v_pk_fma_f32 v[50:51], v[50:51], v[128:129], v[172:173]
	global_store_dwordx4 v[232:233], v[50:53], off offset:192
	s_waitcnt vmcnt(15)
	v_pk_fma_f32 v[48:49], v[48:49], v[118:119], v[178:179]
	v_pk_fma_f32 v[46:47], v[46:47], v[116:117], v[176:177]
	global_store_dwordx4 v[234:235], v[46:49], off
	s_waitcnt vmcnt(15)
	v_pk_fma_f32 v[44:45], v[44:45], v[122:123], v[182:183]
	v_pk_fma_f32 v[42:43], v[42:43], v[120:121], v[180:181]
	global_store_dwordx4 v[234:235], v[42:45], off offset:64
	s_waitcnt vmcnt(15)
	v_pk_fma_f32 v[40:41], v[40:41], v[126:127], v[186:187]
	v_pk_fma_f32 v[38:39], v[38:39], v[124:125], v[184:185]
	global_store_dwordx4 v[234:235], v[38:41], off offset:128
	s_waitcnt vmcnt(15)
	v_pk_fma_f32 v[36:37], v[36:37], v[130:131], v[190:191]
	v_pk_fma_f32 v[34:35], v[34:35], v[128:129], v[188:189]
	global_store_dwordx4 v[234:235], v[34:37], off offset:192
	s_waitcnt vmcnt(15)
	v_pk_fma_f32 v[32:33], v[32:33], v[118:119], v[194:195]
	v_pk_fma_f32 v[30:31], v[30:31], v[116:117], v[192:193]
	global_store_dwordx4 v[236:237], v[30:33], off
	s_waitcnt vmcnt(15)
	v_pk_fma_f32 v[28:29], v[28:29], v[122:123], v[198:199]
	v_pk_fma_f32 v[26:27], v[26:27], v[120:121], v[196:197]
	global_store_dwordx4 v[236:237], v[26:29], off offset:64
	s_waitcnt vmcnt(15)
	v_pk_fma_f32 v[24:25], v[24:25], v[126:127], v[202:203]
	v_pk_fma_f32 v[22:23], v[22:23], v[124:125], v[200:201]
	global_store_dwordx4 v[236:237], v[22:25], off offset:128
	s_waitcnt vmcnt(15)
	v_pk_fma_f32 v[20:21], v[20:21], v[130:131], v[206:207]
	v_pk_fma_f32 v[18:19], v[18:19], v[128:129], v[204:205]
	global_store_dwordx4 v[236:237], v[18:21], off offset:192
	s_waitcnt vmcnt(15)
	v_pk_fma_f32 v[16:17], v[16:17], v[118:119], v[210:211]
	v_pk_fma_f32 v[14:15], v[14:15], v[116:117], v[208:209]
	global_store_dwordx4 v[238:239], v[14:17], off
	s_waitcnt vmcnt(15)
	v_pk_fma_f32 v[12:13], v[12:13], v[122:123], v[214:215]
	v_pk_fma_f32 v[10:11], v[10:11], v[120:121], v[212:213]
	global_store_dwordx4 v[238:239], v[10:13], off offset:64
	s_waitcnt vmcnt(15)
	v_pk_fma_f32 v[8:9], v[8:9], v[126:127], v[218:219]
	v_pk_fma_f32 v[6:7], v[6:7], v[124:125], v[216:217]
	global_store_dwordx4 v[238:239], v[6:9], off offset:128
	s_waitcnt vmcnt(15)
	v_pk_fma_f32 v[4:5], v[4:5], v[130:131], v[222:223]
	v_pk_fma_f32 v[2:3], v[2:3], v[128:129], v[220:221]
	global_store_dwordx4 v[238:239], v[2:5], off offset:192
	s_add_i32 s41, s41, 1
	s_mov_b64 s[0:1], 0
	s_branch .LBB0_254

; DI void prep_token(const Params& p, int l, int row, int lane) {
;   const int b = row / TB, s = row % TB;
;   const bool hasprev = (s != 0 && s != NCTX), hasnext = (s != NCTX - 1 && s != TB - 1);
;   const float mp = hasprev ? 1.f : 0.f, mn = hasnext ? 1.f : 0.f;
;   const bf16_t* pa = p.PA + (size_t)row * LDPA;
;   const bf16_t* pbc = p.PBC + (size_t)row * LDPBC;
;   const int opa = hasprev ? -LDPA : 0, ona = hasnext ? LDPA : 0, opb = hasprev ? -LDPBC : 0, onb = hasnext ? LDPBC : 0;
;   const int l32 = lane & 31, c8 = l32 * 8, colA = 1152 + c8;
;   const u32x4 la_c = *(const u32x4*)(pa + colA), la_p = *(const u32x4*)(pa + opa + colA), la_n = *(const u32x4*)(pa + ona + colA);
;   const u32x4 lq0 = *(const u32x4*)(pbc + lane * 8), lq1 = *(const u32x4*)(pbc + 512 + c8), lkv = *(const u32x4*)(pbc + 768 + c8);
;   const u32x4 lrp = *(const u32x4*)(pbc + 1024 + (lane & 3) * 8);
;   const u32x4 lbg = *(const u32x4*)(pbc + 1056 + c8), lcc = *(const u32x4*)(pbc + 1312 + c8), lhh = *(const u32x4*)(pbc + 1568 + c8);
;   const u32x4 lcp = *(const u32x4*)(pbc + opb + 1312 + c8), lhp = *(const u32x4*)(pbc + opb + 1568 + c8);
;   const u32x4 lcn = *(const u32x4*)(pbc + onb + 1312 + c8), lhn = *(const u32x4*)(pbc + onb + 1568 + c8);
;     ...
;     const float* g = p.k_rope_g + l * 32;
;     const bool lat = s >= NCTX; const int sp = lat ? s - NCTX : 0;
;     const float* rt = p.ROPE + ((lane & 2) ? (sp & 63) : (sp >> 6)) * 16;
.LBB0_445:
	v_mul_hi_i32 v2, v80, s29
	v_lshrrev_b32_e32 v3, 31, v2
	v_ashrrev_i32_e32 v2, 9, v2
	v_add_u32_e32 v89, v2, v3
	v_mul_i32_i24_e32 v2, 0x900, v89
	v_sub_u32_e32 v90, v80, v2
	v_and_b32_e32 v2, 0xfffffeff, v90
	v_readlane_b32 s4, v253, 26
	v_cmp_eq_u32_e64 s[0:1], 0, v2
	v_and_b32_e32 v2, 0xfffff7ff, v90
	v_readlane_b32 s6, v253, 28
	v_readlane_b32 s7, v253, 29
	v_cmp_eq_u32_e64 s[54:55], s33, v2
	v_readlane_b32 s8, v253, 30
	v_readlane_b32 s9, v253, 31
	v_mov_b64_e32 v[2:3], s[6:7]
	s_movk_i32 s4, 0xb00
	v_mad_i64_i32 v[2:3], s[26:27], v80, s4, v[2:3]
	v_mov_b64_e32 v[4:5], s[8:9]
	s_movk_i32 s4, 0xf00
	v_mad_i64_i32 v[6:7], s[26:27], v80, s4, v[4:5]
	v_cndmask_b32_e64 v5, -1, 0, s[0:1]
	v_cndmask_b32_e64 v4, v150, 0, s[0:1]
	v_cndmask_b32_e64 v110, v151, 0, s[54:55]
	v_mov_b32_e32 v83, v111
	v_mov_b32_e32 v9, v5
	v_lshl_add_u64 v[12:13], v[2:3], 0, v[82:83]
	v_lshl_add_u64 v[4:5], v[2:3], 0, v[4:5]
	v_lshl_add_u64 v[2:3], v[2:3], 0, v[110:111]
	v_lshl_add_u64 v[4:5], v[4:5], 0, v[82:83]
	v_lshl_add_u64 v[2:3], v[2:3], 0, v[82:83]
	v_mov_b32_e32 v85, v111
	v_cndmask_b32_e64 v8, v152, 0, s[0:1]
	v_cndmask_b32_e64 v10, v153, 0, s[54:55]
	v_mov_b32_e32 v11, v111
	v_max_i32_e32 v224, 0x100, v90
	v_add_u32_e32 v225, 0xffffff00, v224
	v_and_b32_e32 v224, 63, v224
	v_lshrrev_b32_e32 v225, 6, v225
	v_cndmask_b32_e64 v224, v224, v225, s[46:47]
	v_lshlrev_b32_e32 v224, 6, v224
	global_load_dwordx4 v[200:203], v[72:73], off
	global_load_dwordx4 v[204:207], v[72:73], off offset:16
	global_load_dwordx4 v[208:211], v224, s[68:69]
	global_load_dwordx4 v[212:215], v224, s[68:69] offset:16
	global_load_dwordx4 v[216:219], v224, s[68:69] offset:32
	global_load_dwordx4 v[220:223], v224, s[68:69] offset:48
	global_load_dwordx4 v[34:37], v[12:13], off offset:2304
	s_waitcnt lgkmcnt(0)
	global_load_dwordx4 v[38:41], v[4:5], off offset:2304
	global_load_dwordx4 v[42:45], v[2:3], off offset:2304
	v_lshl_add_u64 v[2:3], v[6:7], 0, v[84:85]
	global_load_dwordx4 v[30:33], v[2:3], off offset:2048
	v_lshl_add_u64 v[2:3], v[6:7], 0, v[82:83]
	v_lshl_add_u64 v[8:9], v[6:7], 0, v[8:9]
	v_lshl_add_u64 v[6:7], v[6:7], 0, v[10:11]
	v_lshl_add_u64 v[8:9], v[8:9], 0, v[82:83]
	v_lshl_add_u64 v[6:7], v[6:7], 0, v[82:83]
	global_load_dwordx4 v[22:25], v[2:3], off offset:2112
	global_load_dwordx4 v[14:17], v[2:3], off offset:2624
	s_nop 0
	global_load_dwordx4 v[2:5], v[2:3], off offset:3136
	s_nop 0
	global_load_dwordx4 v[26:29], v[8:9], off offset:2624
	global_load_dwordx4 v[18:21], v[8:9], off offset:3136
	global_load_dwordx4 v[10:13], v[6:7], off offset:2624
	s_nop 0
	global_load_dwordx4 v[6:9], v[6:7], off offset:3136
	s_nop 0
	global_load_dwordx4 v[46:49], v[62:63], off offset:16
	global_load_dwordx4 v[54:57], v[62:63], off
	global_load_dwordx4 v[50:53], v[64:65], off offset:16
	global_load_dwordx4 v[58:61], v[64:65], off
	v_cndmask_b32_e64 v88, 1.0, 0, s[0:1]
	v_cndmask_b32_e64 v86, 1.0, 0, s[54:55]
	v_readlane_b32 s5, v253, 27
	v_readlane_b32 s10, v253, 32
	v_readlane_b32 s11, v253, 33
	s_waitcnt vmcnt(14)
	v_lshlrev_b32_e32 v81, 16, v34
	s_waitcnt vmcnt(13)
	v_lshlrev_b32_e32 v83, 16, v38
	s_waitcnt vmcnt(12)
	v_lshlrev_b32_e32 v85, 16, v42
	v_fma_f32 v83, v88, v83, -v81
	v_fma_f32 v85, v86, v85, -v81
	s_waitcnt vmcnt(2)
	v_fmac_f32_e32 v81, v83, v54
	s_waitcnt vmcnt(0)
	v_fmac_f32_e32 v81, v85, v58
	s_and_saveexec_b64 s[0:1], vcc
	s_xor_b64 s[0:1], exec, s[0:1]
	s_cbranch_execz .LBB0_447
	v_mul_f32_e32 v54, 0xbfb8aa3b, v81
	v_exp_f32_e32 v54, v54
	s_nop 0
	v_add_f32_e32 v54, 1.0, v54
	v_rcp_f32_e32 v54, v54
	s_nop 0
	v_cndmask_b32_e64 v54, v81, v54, s[36:37]

; DI void prep_token(const Params& p, int l, int row, int lane) {
;     ...
;   s3 += __shfl_xor(s3, 1); s3 += __shfl_xor(s3, 2);
;   {
;     const float inv = rsqrtf(s3 * (1.f / 32.f) + EPSF);
;     const float* g = p.k_rope_g + l * 32;
;     const bool lat = s >= NCTX; const int sp = lat ? s - NCTX : 0;
;     const float* rt = p.ROPE + ((lane & 2) ? (sp & 63) : (sp >> 6)) * 16;
;     float o[8];
; #pragma unroll
;     for (int j = 0; j < 8; ++j) {
;       float val = fr_[j] * inv * g[(lane & 3) * 8 + j];
;       float partner = __shfl_xor(val, 1);
;       if (lat) {
;         const float cs = rt[2 * j], sn = rt[2 * j + 1];
;         val = (lane & 1) == 0 ? val * cs - partner * sn : val * cs + partner * sn;
;       }
;       o[j] = val;
;     }
.LBB0_489:
	s_or_b64 exec, exec, s[0:1]
	ds_bpermute_b32 v40, v1, v32
	s_waitcnt lgkmcnt(0)
	v_add_f32_e32 v32, v32, v40
	ds_bpermute_b32 v40, v87, v32
	s_waitcnt lgkmcnt(0)
	v_add_f32_e32 v32, v32, v40
	v_fmamk_f32 v32, v32, 0x3d000000, v143
	v_mul_f32_e32 v40, 0x4b800000, v32
	v_cmp_gt_f32_e64 s[0:1], s53, v32
	s_nop 1
	v_cndmask_b32_e64 v32, v32, v40, s[0:1]
	v_rsq_f32_e32 v32, v32
	s_nop 0
	v_mul_f32_e32 v40, 0x45800000, v32
	v_cndmask_b32_e64 v40, v32, v40, s[0:1]
	v_mul_f32_e32 v38, v40, v38
	v_max_i32_e32 v32, 0x100, v90
	v_add_u32_e32 v42, 0xffffff00, v32
	v_and_b32_e32 v32, 63, v32
	v_cmp_lt_i32_e64 s[0:1], s33, v90
	s_nop 0
	v_mul_f32_e32 v38, v200, v38
	ds_bpermute_b32 v41, v1, v38
	v_lshrrev_b32_e32 v33, 6, v42
	v_cndmask_b32_e64 v32, v32, v33, s[46:47]
	v_lshlrev_b32_e32 v110, 6, v32
	v_lshl_add_u64 v[32:33], s[68:69], 0, v[110:111]
	s_and_saveexec_b64 s[54:55], s[0:1]
	s_cbranch_execz .LBB0_491
	s_waitcnt lgkmcnt(0)
	v_mul_f32_e32 v41, v209, v41
	v_cndmask_b32_e64 v41, v41, -v41, s[48:49]
	v_fmac_f32_e32 v41, v38, v208
	v_mov_b32_e32 v38, v41
.LBB0_491:
	s_or_b64 exec, exec, s[54:55]
	s_waitcnt lgkmcnt(0)
	v_mul_f32_e32 v39, v40, v39
	s_nop 0
	v_mul_f32_e32 v39, v39, v201
	ds_bpermute_b32 v41, v1, v39
	s_and_saveexec_b64 s[54:55], s[0:1]
	s_cbranch_execz .LBB0_493
	s_waitcnt lgkmcnt(0)
	v_mul_f32_e32 v41, v211, v41
	v_cndmask_b32_e64 v41, v41, -v41, s[48:49]
	v_fmac_f32_e32 v41, v39, v210
	v_mov_b32_e32 v39, v41
.LBB0_493:
	s_or_b64 exec, exec, s[54:55]
	s_waitcnt lgkmcnt(0)
	v_mul_f32_e32 v37, v40, v37
	s_nop 0
	v_mul_f32_e32 v37, v37, v202
	ds_bpermute_b32 v41, v1, v37
	s_and_saveexec_b64 s[54:55], s[0:1]
	s_cbranch_execz .LBB0_495
	s_waitcnt lgkmcnt(0)
	v_mul_f32_e32 v41, v213, v41
	v_cndmask_b32_e64 v41, v41, -v41, s[48:49]
	v_fmac_f32_e32 v41, v37, v212
	v_mov_b32_e32 v37, v41
.LBB0_495:
	s_or_b64 exec, exec, s[54:55]
	s_waitcnt lgkmcnt(0)
	v_mul_f32_e32 v36, v40, v36
	s_nop 0
	v_mul_f32_e32 v36, v36, v203
	ds_bpermute_b32 v41, v1, v36
	s_and_saveexec_b64 s[54:55], s[0:1]
	s_cbranch_execz .LBB0_497
	s_waitcnt lgkmcnt(0)
	v_mul_f32_e32 v41, v215, v41
	v_cndmask_b32_e64 v41, v41, -v41, s[48:49]
	v_fmac_f32_e32 v41, v36, v214
	v_mov_b32_e32 v36, v41
.LBB0_497:
	s_or_b64 exec, exec, s[54:55]
	s_waitcnt lgkmcnt(0)
	v_mul_f32_e32 v35, v40, v35
	s_nop 0
	v_mul_f32_e32 v35, v35, v204
	ds_bpermute_b32 v41, v1, v35
	s_and_saveexec_b64 s[54:55], s[0:1]
	s_cbranch_execz .LBB0_499
	s_waitcnt lgkmcnt(0)
	v_mul_f32_e32 v41, v217, v41
	v_cndmask_b32_e64 v41, v41, -v41, s[48:49]
	v_fmac_f32_e32 v41, v35, v216
	v_mov_b32_e32 v35, v41
.LBB0_499:
	s_or_b64 exec, exec, s[54:55]
	s_waitcnt lgkmcnt(0)
	v_mul_f32_e32 v34, v40, v34
	s_nop 0
	v_mul_f32_e32 v34, v34, v205
	ds_bpermute_b32 v41, v1, v34
	s_and_saveexec_b64 s[54:55], s[0:1]
	s_cbranch_execz .LBB0_501
	s_waitcnt lgkmcnt(0)
	v_mul_f32_e32 v41, v219, v41
	v_cndmask_b32_e64 v41, v41, -v41, s[48:49]
	v_fmac_f32_e32 v41, v34, v218
	v_mov_b32_e32 v34, v41
.LBB0_501:
	s_or_b64 exec, exec, s[54:55]
	s_waitcnt lgkmcnt(0)
	v_mul_f32_e32 v31, v40, v31
	s_nop 0
	v_mul_f32_e32 v31, v31, v206
	ds_bpermute_b32 v41, v1, v31
	s_and_saveexec_b64 s[54:55], s[0:1]
	s_cbranch_execz .LBB0_503
	s_waitcnt lgkmcnt(0)
	v_mul_f32_e32 v41, v221, v41
	v_cndmask_b32_e64 v41, v41, -v41, s[48:49]
	v_fmac_f32_e32 v41, v31, v220
	v_mov_b32_e32 v31, v41
.LBB0_503:
	s_or_b64 exec, exec, s[54:55]
	v_mul_f32_e32 v30, v40, v30
	s_nop 0
	v_mul_f32_e32 v30, v30, v207
	ds_bpermute_b32 v40, v1, v30
	s_and_saveexec_b64 s[54:55], s[0:1]
	s_cbranch_execz .LBB0_506
	s_waitcnt lgkmcnt(0)
	v_mul_f32_e32 v33, v223, v40
	v_cndmask_b32_e64 v33, v33, -v33, s[48:49]
	v_fmac_f32_e32 v33, v30, v222
	v_mov_b32_e32 v30, v33
	s_or_b64 exec, exec, s[54:55]
	s_and_saveexec_b64 s[0:1], s[44:45]
	s_cbranch_execnz .LBB0_507

; #define LAS __attribute__((address_space(3)))
; DI int opaque_tid() { int t = threadIdx.x; asm volatile("" : "+v"(t)); return t; }
; template <class Epi>
; DI void gemm_tile(const bf16_t* __restrict__ A, int lda, const bf16_t* __restrict__ Bt, int ldb, int K, int row0, int col0, char* lds, const Epi& epi) {
;   const int tid = opaque_tid(), lane = tid & 63, wid = tid >> 6, wr = wid >> 1, wc = wid & 1, fr = lane & 15, fq = lane >> 4;
;   const bf16_t* ag[4];
;   const bf16_t* bg[4];
; #pragma unroll
;   for (int i = 0; i < 4; ++i) {
;     const int id = i * 256 + tid, r = id >> 3, cp = id & 7, c = cp ^ ((r >> 1) & 7);
;     ag[i] = A + (size_t)(row0 + r) * lda + c * 8;
;     bg[i] = Bt + (size_t)(col0 + r) * ldb + c * 8;
;   }
;   f32x4 acc[4][4];
; #pragma unroll
;   for (int m = 0; m < 4; ++m)
; #pragma unroll
;     for (int n = 0; n < 4; ++n) acc[m][n] = (f32x4){0.f, 0.f, 0.f, 0.f};
;   const int KT = K >> 6;
;   auto stage_a = [&](int kt, int buf) {
;     char* sa = lds + buf * 32768;
; #pragma unroll
;     for (int i = 0; i < 4; ++i)
;       __builtin_amdgcn_global_load_lds((const void __attribute__((address_space(1)))*)(ag[i] + kt * 64), (void LAS*)(sa + (i * 256 + tid) * 16), 16, 0, 0);
;   };
;   auto stage_b = [&](int kt, int buf) {
;     char* sb = lds + buf * 32768 + 16384;
; #pragma unroll
;     for (int i = 0; i < 4; ++i)
;       __builtin_amdgcn_global_load_lds((const void __attribute__((address_space(1)))*)(bg[i] + kt * 64), (void LAS*)(sb + (i * 256 + tid) * 16), 16, 0, 0);
;   };
;   __syncthreads();
;   stage_a(0, 0); stage_b(0, 0);
.LBB0_528:
	v_mov_b32_e32 v20, v138
	v_readlane_b32 s4, v253, 26
	v_lshrrev_b32_e32 v21, 4, v20
	v_xor_b32_e32 v2, v21, v20
	v_lshlrev_b32_e32 v2, 4, v2
	v_and_b32_e32 v110, 0x70, v2
	v_readlane_b32 s5, v253, 27
	v_readlane_b32 s6, v253, 28
	v_readlane_b32 s7, v253, 29
	v_readlane_b32 s8, v253, 30
	v_readlane_b32 s9, v253, 31
	v_readlane_b32 s10, v253, 32
	v_readlane_b32 s11, v253, 33
	s_lshl_b32 s0, s0, 7
	v_lshl_add_u64 v[8:9], s[8:9], 0, v[110:111]
	v_readlane_b32 s4, v253, 54
	v_ashrrev_i32_e32 v2, 3, v20
	v_add_u32_e32 v4, 0x100, v20
	v_lshlrev_b32_e32 v33, 4, v20
	s_mul_i32 s1, s1, 5
	v_add_u32_e32 v3, s0, v2
	s_movk_i32 s4, 0xf00
	v_ashrrev_i32_e32 v4, 3, v4
	v_add_u32_e32 v6, 0x200, v20
	v_readfirstlane_b32 s46, v33
	v_add_u32_e32 v34, 0x1000, v33
	s_sub_i32 s1, s2, s1
	v_mad_i64_i32 v[10:11], s[2:3], v3, s4, v[8:9]
	v_add_u32_e32 v5, s0, v4
	v_ashrrev_i32_e32 v6, 3, v6
	v_add_u32_e32 v16, 0x300, v20
	s_mov_b32 m0, s46
	v_readfirstlane_b32 s47, v34
	v_add_u32_e32 v35, 0x2000, v33
	v_mad_i64_i32 v[12:13], s[2:3], v5, s4, v[8:9]
	v_add_u32_e32 v7, s0, v6
	v_ashrrev_i32_e32 v22, 3, v16
	s_barrier
	global_load_lds_dwordx4 v[10:11], off
	s_mov_b32 m0, s47
	v_readfirstlane_b32 s26, v35
	v_add_u32_e32 v36, 0x3000, v33
	s_lshl_b32 s1, s1, 7
	v_readlane_b32 s6, v253, 56
	v_readlane_b32 s7, v253, 57
	v_mad_i64_i32 v[14:15], s[2:3], v7, s4, v[8:9]
	v_add_u32_e32 v16, s0, v22
	global_load_lds_dwordx4 v[12:13], off
	s_mov_b32 m0, s26
	v_readfirstlane_b32 s36, v36
	v_add_u32_e32 v29, 0x4000, v33
	v_lshl_add_u64 v[18:19], s[6:7], 0, v[110:111]
	v_add_u32_e32 v2, s1, v2
	v_mad_i64_i32 v[16:17], s[2:3], v16, s4, v[8:9]
	global_load_lds_dwordx4 v[14:15], off
	s_mov_b32 m0, s36
	v_readfirstlane_b32 s49, v29
	v_add_u32_e32 v30, 0x5000, v33
	v_mad_i64_i32 v[2:3], s[2:3], v2, s50, v[18:19]
	v_add_u32_e32 v4, s1, v4
	global_load_lds_dwordx4 v[16:17], off
	s_mov_b32 m0, s49
	v_readfirstlane_b32 s54, v30
	v_add_u32_e32 v31, 0x6000, v33
	v_mad_i64_i32 v[4:5], s[2:3], v4, s50, v[18:19]
	v_add_u32_e32 v6, s1, v6
	v_add_u32_e32 v8, s1, v22
	global_load_lds_dwordx4 v[2:3], off
	s_mov_b32 m0, s54
	v_readfirstlane_b32 s55, v31
	v_add_u32_e32 v32, 0x7000, v33
	v_mad_i64_i32 v[6:7], s[2:3], v6, s50, v[18:19]
	v_mad_i64_i32 v[8:9], s[2:3], v8, s50, v[18:19]
	global_load_lds_dwordx4 v[4:5], off
	s_mov_b32 m0, s55
	v_readfirstlane_b32 s42, v32
	v_bfe_u32 v25, v20, 1, 3
	v_add_u32_e32 v24, 0x8000, v33
	global_load_lds_dwordx4 v[6:7], off
	s_mov_b32 m0, s42
	v_bitop3_b32 v18, v21, v25, 3 bitop3:0x6c
	v_add_u32_e32 v23, 0x9000, v33
	v_readfirstlane_b32 s2, v24
	global_load_lds_dwordx4 v[8:9], off
	v_lshlrev_b32_e32 v42, 4, v18
	v_lshl_add_u64 v[18:19], v[10:11], 0, s[92:93]
	v_add_u32_e32 v22, 0xa000, v33
	s_mov_b32 m0, s2
	v_readfirstlane_b32 s3, v23
	s_waitcnt vmcnt(0)
	v_and_b32_e32 v66, 15, v20
	s_waitcnt vmcnt(0)
	s_waitcnt lgkmcnt(0)
	s_barrier
	v_lshl_add_u64 v[26:27], v[12:13], 0, s[92:93]
	v_add_u32_e32 v21, 0xb000, v33
	global_load_lds_dwordx4 v[18:19], off
	s_mov_b32 m0, s3
	v_readfirstlane_b32 s28, v22
	v_bfe_u32 v1, v20, 6, 1
	v_lshlrev_b32_e32 v28, 7, v66
	v_lshl_add_u64 v[38:39], v[14:15], 0, s[92:93]
	global_load_lds_dwordx4 v[26:27], off
	s_mov_b32 m0, s28
	v_readfirstlane_b32 s29, v21
	v_lshl_or_b32 v37, v1, 13, v28
	v_lshl_add_u64 v[40:41], v[16:17], 0, s[92:93]
	global_load_lds_dwordx4 v[38:39], off
	s_mov_b32 m0, s29
	v_or_b32_e32 v19, v37, v42
	global_load_lds_dwordx4 v[40:41], off
	ds_read_b128 v[38:41], v19 offset:16384
	ds_read_b128 v[50:53], v19 offset:18432
	ds_read_b128 v[58:61], v19 offset:20480
	ds_read_b128 v[68:71], v19 offset:22528
	v_ashrrev_i32_e32 v67, 7, v20
	v_lshl_or_b32 v110, v67, 13, v28
	v_or_b32_e32 v18, v110, v42
	ds_read_b128 v[42:45], v18
	ds_read_b128 v[72:75], v18 offset:2048
	v_add_u32_e32 v26, 0xc000, v33
	v_add_u32_e32 v27, 0xd000, v33
	v_readfirstlane_b32 s38, v26
	s_waitcnt lgkmcnt(0)
	v_mfma_f32_16x16x32_bf16 v[76:79], v[38:41], v[72:75], 0
	v_add_u32_e32 v28, 0xe000, v33
	s_mov_b32 m0, s38
	v_readfirstlane_b32 s39, v27
	v_mfma_f32_16x16x32_bf16 v[80:83], v[50:53], v[72:75], 0
	ds_read_b128 v[92:95], v18 offset:4096
	ds_read_b128 v[116:119], v18 offset:6144
	v_lshl_add_u64 v[108:109], v[4:5], 0, s[92:93]
	v_mfma_f32_16x16x32_bf16 v[84:87], v[58:61], v[72:75], 0
	v_readfirstlane_b32 s43, v28
	v_lshl_add_u64 v[120:121], v[6:7], 0, s[92:93]
	v_lshl_add_u64 v[122:123], v[8:9], 0, s[92:93]
	v_mfma_f32_16x16x32_bf16 v[88:91], v[68:71], v[72:75], 0
	v_bfe_u32 v73, v20, 4, 2
	v_lshl_add_u64 v[74:75], v[2:3], 0, s[92:93]
	v_bitop3_b32 v20, v73, v25, 4 bitop3:0x36
	v_add_u32_e32 v25, 0xf000, v33
	global_load_lds_dwordx4 v[74:75], off
	s_mov_b32 m0, s39
	v_readfirstlane_b32 s48, v25
	global_load_lds_dwordx4 v[108:109], off
	s_mov_b32 m0, s43
	v_lshlrev_b32_e32 v72, 4, v20
	global_load_lds_dwordx4 v[120:121], off
	s_mov_b32 m0, s48
	v_or_b32_e32 v20, v37, v72
	global_load_lds_dwordx4 v[122:123], off
	ds_read_b128 v[120:123], v20 offset:16384
	ds_read_b128 v[128:131], v20 offset:18432
	ds_read_b128 v[132:135], v20 offset:20480
	ds_read_b128 v[160:163], v20 offset:22528
	v_mfma_f32_16x16x32_bf16 v[46:49], v[38:41], v[42:45], 0
	v_readlane_b32 s5, v253, 55
	s_mov_b64 s[4:5], 0x100
	s_mov_b32 m0, s46
	v_mfma_f32_16x16x32_bf16 v[54:57], v[50:53], v[42:45], 0
	v_lshl_add_u64 v[108:109], v[14:15], 0, s[4:5]
	v_readfirstlane_b32 s27, v29
	v_readfirstlane_b32 s37, v32
	v_mfma_f32_16x16x32_bf16 v[62:65], v[58:61], v[42:45], 0
	v_readlane_b32 s8, v253, 58
	v_readlane_b32 s9, v253, 59
	v_readlane_b32 s10, v253, 60
	v_mfma_f32_16x16x32_bf16 v[42:45], v[68:71], v[42:45], 0
	v_readlane_b32 s11, v253, 61
	v_readlane_b32 s12, v253, 62
	v_readlane_b32 s13, v253, 63
	s_waitcnt lgkmcnt(0)
; template <class Epi>
; DI void gemm_tile(const bf16_t* __restrict__ A, int lda, const bf16_t* __restrict__ Bt, int ldb, int K, int row0, int col0, char* lds, const Epi& epi) {
;     ...
;   for (int kt = 0; kt < KT; ++kt) {
;     asm volatile("s_waitcnt vmcnt(0)" ::: "memory");
;     __syncthreads();
;     const char* sa = lds + (kt & 1) * 32768 + (wr * 64 + fr) * 128;
;     const char* sb = lds + (kt & 1) * 32768 + 16384 + (wc * 64 + fr) * 128;
; #pragma unroll
;     for (int kk = 0; kk < 2; ++kk) {
;       if (kt + 1 < KT) { if (kk == 0) stage_a(kt + 1, (kt + 1) & 1); else stage_b(kt + 1, (kt + 1) & 1); }
;       bf16x8 a[4], b[4];
;       const int co = ((kk * 4 + fq) ^ swz) * 16;
; #pragma unroll
;       for (int m = 0; m < 4; ++m) a[m] = *(const bf16x8*)(sa + m * 2048 + co);
; #pragma unroll
;       for (int n = 0; n < 4; ++n) b[n] = *(const bf16x8*)(sb + n * 2048 + co);
; #pragma unroll
;       for (int m = 0; m < 4; ++m)
; #pragma unroll
;         for (int n = 0; n < 4; ++n) acc[m][n] = __builtin_amdgcn_mfma_f32_16x16x32_bf16(b[n], a[m], acc[m][n], 0, 0, 0);
;     }
;   }
	v_mfma_f32_16x16x32_bf16 v[96:99], v[38:41], v[92:95], 0
	v_readlane_b32 s14, v254, 0
	v_readlane_b32 s15, v254, 1
	v_readlane_b32 s16, v254, 2
	v_mfma_f32_16x16x32_bf16 v[100:103], v[50:53], v[92:95], 0
	v_readlane_b32 s17, v254, 3
	v_readlane_b32 s18, v254, 4
	v_readlane_b32 s19, v254, 5
	v_mfma_f32_16x16x32_bf16 v[104:107], v[58:61], v[92:95], 0
	v_mfma_f32_16x16x32_bf16 v[92:95], v[68:71], v[92:95], 0
	v_mfma_f32_16x16x32_bf16 v[38:41], v[38:41], v[116:119], 0
	v_mfma_f32_16x16x32_bf16 v[50:53], v[50:53], v[116:119], 0
	v_mfma_f32_16x16x32_bf16 v[58:61], v[58:61], v[116:119], 0
	v_mfma_f32_16x16x32_bf16 v[116:119], v[68:71], v[116:119], 0
	v_or_b32_e32 v68, v110, v72
	ds_read_b128 v[124:127], v68
	v_lshl_add_u64 v[70:71], v[10:11], 0, s[4:5]
	s_waitcnt lgkmcnt(0)
	v_mfma_f32_16x16x32_bf16 v[46:49], v[120:123], v[124:127], v[46:49]
	v_mfma_f32_16x16x32_bf16 v[54:57], v[128:131], v[124:127], v[54:57]
	v_mfma_f32_16x16x32_bf16 v[62:65], v[132:135], v[124:127], v[62:65]
	v_mfma_f32_16x16x32_bf16 v[42:45], v[160:163], v[124:127], v[42:45]
	ds_read_b128 v[124:127], v68 offset:2048
	s_waitcnt lgkmcnt(0)
	v_mfma_f32_16x16x32_bf16 v[74:77], v[120:123], v[124:127], v[76:79]
	v_mfma_f32_16x16x32_bf16 v[78:81], v[128:131], v[124:127], v[80:83]
	v_mfma_f32_16x16x32_bf16 v[82:85], v[132:135], v[124:127], v[84:87]
	v_mfma_f32_16x16x32_bf16 v[86:89], v[160:163], v[124:127], v[88:91]
	ds_read_b128 v[124:127], v68 offset:4096
	s_waitcnt lgkmcnt(0)
	v_mfma_f32_16x16x32_bf16 v[96:99], v[120:123], v[124:127], v[96:99]
	v_mfma_f32_16x16x32_bf16 v[100:103], v[128:131], v[124:127], v[100:103]
	v_mfma_f32_16x16x32_bf16 v[104:107], v[132:135], v[124:127], v[104:107]
	v_mfma_f32_16x16x32_bf16 v[90:93], v[160:163], v[124:127], v[92:95]
	ds_read_b128 v[124:127], v68 offset:6144
	s_waitcnt vmcnt(0)
	s_waitcnt vmcnt(0) lgkmcnt(0)
	s_barrier
	v_lshl_add_u64 v[94:95], v[12:13], 0, s[4:5]
	global_load_lds_dwordx4 v[70:71], off
	s_mov_b32 m0, s47
	v_mfma_f32_16x16x32_bf16 v[38:41], v[120:123], v[124:127], v[38:41]
	global_load_lds_dwordx4 v[94:95], off
	s_mov_b32 m0, s26
	v_lshl_add_u64 v[120:121], v[16:17], 0, s[4:5]
	global_load_lds_dwordx4 v[108:109], off
	s_mov_b32 m0, s36
	v_mfma_f32_16x16x32_bf16 v[50:53], v[128:131], v[124:127], v[50:53]
	global_load_lds_dwordx4 v[120:121], off
	ds_read_b128 v[120:123], v19 offset:49152
	v_mfma_f32_16x16x32_bf16 v[58:61], v[132:135], v[124:127], v[58:61]
	ds_read_b128 v[128:131], v19 offset:51200
	ds_read_b128 v[132:135], v19 offset:53248
	v_lshl_add_u64 v[70:71], v[2:3], 0, s[4:5]
	v_mfma_f32_16x16x32_bf16 v[116:119], v[160:163], v[124:127], v[116:119]
	ds_read_b128 v[160:163], v19 offset:55296
	ds_read_b128 v[124:127], v18 offset:32768
	s_mov_b32 m0, s49
	s_waitcnt lgkmcnt(0)
	v_mfma_f32_16x16x32_bf16 v[46:49], v[120:123], v[124:127], v[46:49]
	v_mfma_f32_16x16x32_bf16 v[54:57], v[128:131], v[124:127], v[54:57]
	v_mfma_f32_16x16x32_bf16 v[62:65], v[132:135], v[124:127], v[62:65]
	v_mfma_f32_16x16x32_bf16 v[42:45], v[160:163], v[124:127], v[42:45]
	ds_read_b128 v[124:127], v18 offset:34816
	s_waitcnt lgkmcnt(0)
	v_mfma_f32_16x16x32_bf16 v[74:77], v[120:123], v[124:127], v[74:77]
	v_mfma_f32_16x16x32_bf16 v[78:81], v[128:131], v[124:127], v[78:81]
	v_mfma_f32_16x16x32_bf16 v[82:85], v[132:135], v[124:127], v[82:85]
	v_mfma_f32_16x16x32_bf16 v[86:89], v[160:163], v[124:127], v[86:89]
	ds_read_b128 v[124:127], v18 offset:36864
	s_waitcnt lgkmcnt(0)
	v_mfma_f32_16x16x32_bf16 v[94:97], v[120:123], v[124:127], v[96:99]
	v_mfma_f32_16x16x32_bf16 v[98:101], v[128:131], v[124:127], v[100:103]
	v_mfma_f32_16x16x32_bf16 v[102:105], v[132:135], v[124:127], v[104:107]
	s_nop 2
	ds_read_b128 v[106:109], v18 offset:38912
	s_waitcnt lgkmcnt(0)
	v_mfma_f32_16x16x32_bf16 v[38:41], v[120:123], v[106:109], v[38:41]
	v_lshl_add_u64 v[120:121], v[4:5], 0, s[4:5]
	global_load_lds_dwordx4 v[70:71], off
	s_mov_b32 m0, s54
	v_lshl_add_u64 v[122:123], v[6:7], 0, s[4:5]
	global_load_lds_dwordx4 v[120:121], off
	s_mov_b32 m0, s55
	v_mfma_f32_16x16x32_bf16 v[90:93], v[160:163], v[124:127], v[90:93]
	v_lshl_add_u64 v[124:125], v[8:9], 0, s[4:5]
	global_load_lds_dwordx4 v[122:123], off
	s_mov_b32 m0, s42
	v_mfma_f32_16x16x32_bf16 v[50:53], v[128:131], v[106:109], v[50:53]
	global_load_lds_dwordx4 v[124:125], off
	ds_read_b128 v[120:123], v20 offset:49152
	ds_read_b128 v[124:127], v20 offset:51200
	v_mfma_f32_16x16x32_bf16 v[58:61], v[132:135], v[106:109], v[58:61]
	ds_read_b128 v[128:131], v20 offset:53248
	ds_read_b128 v[132:135], v20 offset:55296
	s_mov_b64 s[4:5], 0x180
	v_mfma_f32_16x16x32_bf16 v[106:109], v[160:163], v[106:109], v[116:119]
	v_lshl_add_u64 v[70:71], v[10:11], 0, s[4:5]
	s_mov_b32 m0, s2
	s_nop 0
	ds_read_b128 v[116:119], v68 offset:32768
	s_waitcnt lgkmcnt(0)
	v_mfma_f32_16x16x32_bf16 v[46:49], v[120:123], v[116:119], v[46:49]
	v_mfma_f32_16x16x32_bf16 v[54:57], v[124:127], v[116:119], v[54:57]
	v_mfma_f32_16x16x32_bf16 v[62:65], v[128:131], v[116:119], v[62:65]
	v_mfma_f32_16x16x32_bf16 v[42:45], v[132:135], v[116:119], v[42:45]
	ds_read_b128 v[116:119], v68 offset:34816
	s_waitcnt lgkmcnt(0)
	v_mfma_f32_16x16x32_bf16 v[74:77], v[120:123], v[116:119], v[74:77]
	v_mfma_f32_16x16x32_bf16 v[78:81], v[124:127], v[116:119], v[78:81]
	v_mfma_f32_16x16x32_bf16 v[82:85], v[128:131], v[116:119], v[82:85]
	v_mfma_f32_16x16x32_bf16 v[86:89], v[132:135], v[116:119], v[86:89]
	ds_read_b128 v[116:119], v68 offset:36864
	s_waitcnt lgkmcnt(0)
	v_mfma_f32_16x16x32_bf16 v[94:97], v[120:123], v[116:119], v[94:97]
	v_mfma_f32_16x16x32_bf16 v[98:101], v[124:127], v[116:119], v[98:101]
	v_mfma_f32_16x16x32_bf16 v[102:105], v[128:131], v[116:119], v[102:105]
	v_mfma_f32_16x16x32_bf16 v[90:93], v[132:135], v[116:119], v[90:93]
	ds_read_b128 v[116:119], v68 offset:38912
	s_waitcnt vmcnt(0)
	s_waitcnt vmcnt(0) lgkmcnt(0)
	v_mfma_f32_16x16x32_bf16 v[38:41], v[120:123], v[116:119], v[38:41]
	s_barrier
; template <class Epi>
; DI void gemm_tile(const bf16_t* __restrict__ A, int lda, const bf16_t* __restrict__ Bt, int ldb, int K, int row0, int col0, char* lds, const Epi& epi) {
;     ...
;   for (int kt = 0; kt < KT; ++kt) {
;     asm volatile("s_waitcnt vmcnt(0)" ::: "memory");
;     __syncthreads();
;     const char* sa = lds + (kt & 1) * 32768 + (wr * 64 + fr) * 128;
;     const char* sb = lds + (kt & 1) * 32768 + 16384 + (wc * 64 + fr) * 128;
; #pragma unroll
;     for (int kk = 0; kk < 2; ++kk) {
;       if (kt + 1 < KT) { if (kk == 0) stage_a(kt + 1, (kt + 1) & 1); else stage_b(kt + 1, (kt + 1) & 1); }
;       bf16x8 a[4], b[4];
;       const int co = ((kk * 4 + fq) ^ swz) * 16;
; #pragma unroll
;       for (int m = 0; m < 4; ++m) a[m] = *(const bf16x8*)(sa + m * 2048 + co);
; #pragma unroll
;       for (int n = 0; n < 4; ++n) b[n] = *(const bf16x8*)(sb + n * 2048 + co);
; #pragma unroll
;       for (int m = 0; m < 4; ++m)
; #pragma unroll
;         for (int n = 0; n < 4; ++n) acc[m][n] = __builtin_amdgcn_mfma_f32_16x16x32_bf16(b[n], a[m], acc[m][n], 0, 0, 0);
;     }
;   }
	v_lshl_add_u64 v[120:121], v[12:13], 0, s[4:5]
	global_load_lds_dwordx4 v[70:71], off
	s_mov_b32 m0, s3
	v_lshl_add_u64 v[122:123], v[14:15], 0, s[4:5]
	global_load_lds_dwordx4 v[120:121], off
	s_mov_b32 m0, s28
	v_mfma_f32_16x16x32_bf16 v[50:53], v[124:127], v[116:119], v[50:53]
	v_lshl_add_u64 v[124:125], v[16:17], 0, s[4:5]
	global_load_lds_dwordx4 v[122:123], off
	s_mov_b32 m0, s29
	v_mfma_f32_16x16x32_bf16 v[58:61], v[128:131], v[116:119], v[58:61]
	global_load_lds_dwordx4 v[124:125], off
	ds_read_b128 v[120:123], v19 offset:16384
	v_mfma_f32_16x16x32_bf16 v[106:109], v[132:135], v[116:119], v[106:109]
	ds_read_b128 v[124:127], v19 offset:18432
	ds_read_b128 v[128:131], v19 offset:20480
	ds_read_b128 v[132:135], v19 offset:22528
	ds_read_b128 v[116:119], v18
	s_waitcnt lgkmcnt(0)
	v_mfma_f32_16x16x32_bf16 v[46:49], v[120:123], v[116:119], v[46:49]
	v_lshl_add_u64 v[70:71], v[2:3], 0, s[4:5]
	s_mov_b32 m0, s38
	v_mfma_f32_16x16x32_bf16 v[54:57], v[124:127], v[116:119], v[54:57]
	v_mfma_f32_16x16x32_bf16 v[62:65], v[128:131], v[116:119], v[62:65]
	v_mfma_f32_16x16x32_bf16 v[42:45], v[132:135], v[116:119], v[42:45]
	ds_read_b128 v[116:119], v18 offset:2048
	s_waitcnt lgkmcnt(0)
	v_mfma_f32_16x16x32_bf16 v[74:77], v[120:123], v[116:119], v[74:77]
	v_mfma_f32_16x16x32_bf16 v[78:81], v[124:127], v[116:119], v[78:81]
	v_mfma_f32_16x16x32_bf16 v[82:85], v[128:131], v[116:119], v[82:85]
	v_mfma_f32_16x16x32_bf16 v[86:89], v[132:135], v[116:119], v[86:89]
	ds_read_b128 v[116:119], v18 offset:4096
	s_waitcnt lgkmcnt(0)
	v_mfma_f32_16x16x32_bf16 v[94:97], v[120:123], v[116:119], v[94:97]
	v_mfma_f32_16x16x32_bf16 v[98:101], v[124:127], v[116:119], v[98:101]
	v_mfma_f32_16x16x32_bf16 v[102:105], v[128:131], v[116:119], v[102:105]
	v_mfma_f32_16x16x32_bf16 v[90:93], v[132:135], v[116:119], v[90:93]
	ds_read_b128 v[116:119], v18 offset:6144
	global_load_lds_dwordx4 v[70:71], off
	s_waitcnt lgkmcnt(0)
	v_mfma_f32_16x16x32_bf16 v[38:41], v[120:123], v[116:119], v[38:41]
	v_lshl_add_u64 v[120:121], v[4:5], 0, s[4:5]
	s_mov_b32 m0, s39
	v_lshl_add_u64 v[122:123], v[6:7], 0, s[4:5]
	global_load_lds_dwordx4 v[120:121], off
	s_mov_b32 m0, s43
	v_mfma_f32_16x16x32_bf16 v[50:53], v[124:127], v[116:119], v[50:53]
	v_lshl_add_u64 v[124:125], v[8:9], 0, s[4:5]
	global_load_lds_dwordx4 v[122:123], off
	s_mov_b32 m0, s48
	v_mfma_f32_16x16x32_bf16 v[58:61], v[128:131], v[116:119], v[58:61]
	global_load_lds_dwordx4 v[124:125], off
	ds_read_b128 v[120:123], v20 offset:16384
	ds_read_b128 v[124:127], v20 offset:18432
	v_mfma_f32_16x16x32_bf16 v[106:109], v[132:135], v[116:119], v[106:109]
	ds_read_b128 v[128:131], v20 offset:20480
	ds_read_b128 v[132:135], v20 offset:22528
	ds_read_b128 v[116:119], v68
	s_waitcnt lgkmcnt(0)
	v_mfma_f32_16x16x32_bf16 v[46:49], v[120:123], v[116:119], v[46:49]
	s_mov_b64 s[4:5], 0x200
	v_lshl_add_u64 v[70:71], v[10:11], 0, s[4:5]
	s_mov_b32 m0, s46
	v_mfma_f32_16x16x32_bf16 v[54:57], v[124:127], v[116:119], v[54:57]
	v_mfma_f32_16x16x32_bf16 v[62:65], v[128:131], v[116:119], v[62:65]
	v_mfma_f32_16x16x32_bf16 v[42:45], v[132:135], v[116:119], v[42:45]
	ds_read_b128 v[116:119], v68 offset:2048
	s_waitcnt lgkmcnt(0)
	v_mfma_f32_16x16x32_bf16 v[74:77], v[120:123], v[116:119], v[74:77]
	v_mfma_f32_16x16x32_bf16 v[78:81], v[124:127], v[116:119], v[78:81]
	v_mfma_f32_16x16x32_bf16 v[82:85], v[128:131], v[116:119], v[82:85]
	v_mfma_f32_16x16x32_bf16 v[86:89], v[132:135], v[116:119], v[86:89]
	ds_read_b128 v[116:119], v68 offset:4096
	s_waitcnt lgkmcnt(0)
	v_mfma_f32_16x16x32_bf16 v[94:97], v[120:123], v[116:119], v[94:97]
	v_mfma_f32_16x16x32_bf16 v[98:101], v[124:127], v[116:119], v[98:101]
	v_mfma_f32_16x16x32_bf16 v[102:105], v[128:131], v[116:119], v[102:105]
	v_mfma_f32_16x16x32_bf16 v[90:93], v[132:135], v[116:119], v[90:93]
	ds_read_b128 v[116:119], v68 offset:6144
	s_waitcnt vmcnt(0)
	s_waitcnt vmcnt(0) lgkmcnt(0)
	v_mfma_f32_16x16x32_bf16 v[38:41], v[120:123], v[116:119], v[38:41]
	s_barrier
	v_lshl_add_u64 v[120:121], v[12:13], 0, s[4:5]
	global_load_lds_dwordx4 v[70:71], off
	s_mov_b32 m0, s47
	v_lshl_add_u64 v[122:123], v[14:15], 0, s[4:5]
	global_load_lds_dwordx4 v[120:121], off
	s_mov_b32 m0, s26
	v_mfma_f32_16x16x32_bf16 v[50:53], v[124:127], v[116:119], v[50:53]
	v_lshl_add_u64 v[124:125], v[16:17], 0, s[4:5]
	global_load_lds_dwordx4 v[122:123], off
	s_mov_b32 m0, s36
	v_mfma_f32_16x16x32_bf16 v[58:61], v[128:131], v[116:119], v[58:61]
	global_load_lds_dwordx4 v[124:125], off
	ds_read_b128 v[120:123], v19 offset:49152
	v_mfma_f32_16x16x32_bf16 v[106:109], v[132:135], v[116:119], v[106:109]
	ds_read_b128 v[124:127], v19 offset:51200
	ds_read_b128 v[128:131], v19 offset:53248
	ds_read_b128 v[132:135], v19 offset:55296
	ds_read_b128 v[116:119], v18 offset:32768
	s_waitcnt lgkmcnt(0)
	v_mfma_f32_16x16x32_bf16 v[46:49], v[120:123], v[116:119], v[46:49]
	v_lshl_add_u64 v[70:71], v[2:3], 0, s[4:5]
	s_mov_b32 m0, s49
	v_mfma_f32_16x16x32_bf16 v[54:57], v[124:127], v[116:119], v[54:57]
	v_mfma_f32_16x16x32_bf16 v[62:65], v[128:131], v[116:119], v[62:65]
	v_mfma_f32_16x16x32_bf16 v[42:45], v[132:135], v[116:119], v[42:45]
	ds_read_b128 v[116:119], v18 offset:34816
	s_waitcnt lgkmcnt(0)
	v_mfma_f32_16x16x32_bf16 v[74:77], v[120:123], v[116:119], v[74:77]
	v_mfma_f32_16x16x32_bf16 v[78:81], v[124:127], v[116:119], v[78:81]
	v_mfma_f32_16x16x32_bf16 v[82:85], v[128:131], v[116:119], v[82:85]
	v_mfma_f32_16x16x32_bf16 v[86:89], v[132:135], v[116:119], v[86:89]
	ds_read_b128 v[116:119], v18 offset:36864
	s_waitcnt lgkmcnt(0)
; template <class Epi>
; DI void gemm_tile(const bf16_t* __restrict__ A, int lda, const bf16_t* __restrict__ Bt, int ldb, int K, int row0, int col0, char* lds, const Epi& epi) {
;     ...
;   for (int kt = 0; kt < KT; ++kt) {
;     asm volatile("s_waitcnt vmcnt(0)" ::: "memory");
;     __syncthreads();
;     const char* sa = lds + (kt & 1) * 32768 + (wr * 64 + fr) * 128;
;     const char* sb = lds + (kt & 1) * 32768 + 16384 + (wc * 64 + fr) * 128;
; #pragma unroll
;     for (int kk = 0; kk < 2; ++kk) {
;       if (kt + 1 < KT) { if (kk == 0) stage_a(kt + 1, (kt + 1) & 1); else stage_b(kt + 1, (kt + 1) & 1); }
;       bf16x8 a[4], b[4];
;       const int co = ((kk * 4 + fq) ^ swz) * 16;
; #pragma unroll
;       for (int m = 0; m < 4; ++m) a[m] = *(const bf16x8*)(sa + m * 2048 + co);
; #pragma unroll
;       for (int n = 0; n < 4; ++n) b[n] = *(const bf16x8*)(sb + n * 2048 + co);
; #pragma unroll
;       for (int m = 0; m < 4; ++m)
; #pragma unroll
;         for (int n = 0; n < 4; ++n) acc[m][n] = __builtin_amdgcn_mfma_f32_16x16x32_bf16(b[n], a[m], acc[m][n], 0, 0, 0);
;     }
;   }
	v_mfma_f32_16x16x32_bf16 v[94:97], v[120:123], v[116:119], v[94:97]
	v_mfma_f32_16x16x32_bf16 v[98:101], v[124:127], v[116:119], v[98:101]
	v_mfma_f32_16x16x32_bf16 v[102:105], v[128:131], v[116:119], v[102:105]
	v_mfma_f32_16x16x32_bf16 v[90:93], v[132:135], v[116:119], v[90:93]
	ds_read_b128 v[116:119], v18 offset:38912
	global_load_lds_dwordx4 v[70:71], off
	s_waitcnt lgkmcnt(0)
	v_mfma_f32_16x16x32_bf16 v[38:41], v[120:123], v[116:119], v[38:41]
	v_lshl_add_u64 v[120:121], v[4:5], 0, s[4:5]
	s_mov_b32 m0, s54
	v_lshl_add_u64 v[122:123], v[6:7], 0, s[4:5]
	global_load_lds_dwordx4 v[120:121], off
	s_mov_b32 m0, s55
	v_mfma_f32_16x16x32_bf16 v[50:53], v[124:127], v[116:119], v[50:53]
	v_lshl_add_u64 v[124:125], v[8:9], 0, s[4:5]
	global_load_lds_dwordx4 v[122:123], off
	s_mov_b32 m0, s42
	v_mfma_f32_16x16x32_bf16 v[58:61], v[128:131], v[116:119], v[58:61]
	global_load_lds_dwordx4 v[124:125], off
	ds_read_b128 v[120:123], v20 offset:49152
	ds_read_b128 v[124:127], v20 offset:51200
	v_mfma_f32_16x16x32_bf16 v[106:109], v[132:135], v[116:119], v[106:109]
	ds_read_b128 v[128:131], v20 offset:53248
	ds_read_b128 v[132:135], v20 offset:55296
	ds_read_b128 v[116:119], v68 offset:32768
	s_waitcnt lgkmcnt(0)
	v_mfma_f32_16x16x32_bf16 v[46:49], v[120:123], v[116:119], v[46:49]
	s_mov_b64 s[4:5], 0x280
	v_lshl_add_u64 v[70:71], v[10:11], 0, s[4:5]
	s_mov_b32 m0, s2
	v_mfma_f32_16x16x32_bf16 v[54:57], v[124:127], v[116:119], v[54:57]
	v_mfma_f32_16x16x32_bf16 v[62:65], v[128:131], v[116:119], v[62:65]
	v_mfma_f32_16x16x32_bf16 v[42:45], v[132:135], v[116:119], v[42:45]
	ds_read_b128 v[116:119], v68 offset:34816
	s_waitcnt lgkmcnt(0)
	v_mfma_f32_16x16x32_bf16 v[74:77], v[120:123], v[116:119], v[74:77]
	v_mfma_f32_16x16x32_bf16 v[78:81], v[124:127], v[116:119], v[78:81]
	v_mfma_f32_16x16x32_bf16 v[82:85], v[128:131], v[116:119], v[82:85]
	v_mfma_f32_16x16x32_bf16 v[86:89], v[132:135], v[116:119], v[86:89]
	ds_read_b128 v[116:119], v68 offset:36864
	s_waitcnt lgkmcnt(0)
	v_mfma_f32_16x16x32_bf16 v[94:97], v[120:123], v[116:119], v[94:97]
	v_mfma_f32_16x16x32_bf16 v[98:101], v[124:127], v[116:119], v[98:101]
	v_mfma_f32_16x16x32_bf16 v[102:105], v[128:131], v[116:119], v[102:105]
	v_mfma_f32_16x16x32_bf16 v[90:93], v[132:135], v[116:119], v[90:93]
	ds_read_b128 v[116:119], v68 offset:38912
	s_waitcnt vmcnt(0)
	s_waitcnt vmcnt(0) lgkmcnt(0)
	v_mfma_f32_16x16x32_bf16 v[38:41], v[120:123], v[116:119], v[38:41]
	s_barrier
	v_lshl_add_u64 v[120:121], v[12:13], 0, s[4:5]
	global_load_lds_dwordx4 v[70:71], off
	s_mov_b32 m0, s3
	v_lshl_add_u64 v[122:123], v[14:15], 0, s[4:5]
	global_load_lds_dwordx4 v[120:121], off
	s_mov_b32 m0, s28
	v_mfma_f32_16x16x32_bf16 v[50:53], v[124:127], v[116:119], v[50:53]
	v_lshl_add_u64 v[124:125], v[16:17], 0, s[4:5]
	global_load_lds_dwordx4 v[122:123], off
	s_mov_b32 m0, s29
	v_mfma_f32_16x16x32_bf16 v[58:61], v[128:131], v[116:119], v[58:61]
	global_load_lds_dwordx4 v[124:125], off
	ds_read_b128 v[120:123], v19 offset:16384
	v_mfma_f32_16x16x32_bf16 v[106:109], v[132:135], v[116:119], v[106:109]
	ds_read_b128 v[124:127], v19 offset:18432
	ds_read_b128 v[128:131], v19 offset:20480
	ds_read_b128 v[132:135], v19 offset:22528
	ds_read_b128 v[116:119], v18
	s_waitcnt lgkmcnt(0)
	v_mfma_f32_16x16x32_bf16 v[46:49], v[120:123], v[116:119], v[46:49]
	v_lshl_add_u64 v[70:71], v[2:3], 0, s[4:5]
	s_mov_b32 m0, s38
	v_mfma_f32_16x16x32_bf16 v[54:57], v[124:127], v[116:119], v[54:57]
	v_mfma_f32_16x16x32_bf16 v[62:65], v[128:131], v[116:119], v[62:65]
	v_mfma_f32_16x16x32_bf16 v[42:45], v[132:135], v[116:119], v[42:45]
	ds_read_b128 v[116:119], v18 offset:2048
	s_waitcnt lgkmcnt(0)
	v_mfma_f32_16x16x32_bf16 v[74:77], v[120:123], v[116:119], v[74:77]
	v_mfma_f32_16x16x32_bf16 v[78:81], v[124:127], v[116:119], v[78:81]
	v_mfma_f32_16x16x32_bf16 v[82:85], v[128:131], v[116:119], v[82:85]
	v_mfma_f32_16x16x32_bf16 v[86:89], v[132:135], v[116:119], v[86:89]
	ds_read_b128 v[116:119], v18 offset:4096
	s_waitcnt lgkmcnt(0)
	v_mfma_f32_16x16x32_bf16 v[94:97], v[120:123], v[116:119], v[94:97]
	v_mfma_f32_16x16x32_bf16 v[98:101], v[124:127], v[116:119], v[98:101]
	v_mfma_f32_16x16x32_bf16 v[102:105], v[128:131], v[116:119], v[102:105]
	v_mfma_f32_16x16x32_bf16 v[90:93], v[132:135], v[116:119], v[90:93]
	ds_read_b128 v[116:119], v18 offset:6144
	global_load_lds_dwordx4 v[70:71], off
	s_waitcnt lgkmcnt(0)
	v_mfma_f32_16x16x32_bf16 v[38:41], v[120:123], v[116:119], v[38:41]
	v_lshl_add_u64 v[120:121], v[4:5], 0, s[4:5]
	s_mov_b32 m0, s39
	v_lshl_add_u64 v[122:123], v[6:7], 0, s[4:5]
	global_load_lds_dwordx4 v[120:121], off
	s_mov_b32 m0, s43
	v_mfma_f32_16x16x32_bf16 v[50:53], v[124:127], v[116:119], v[50:53]
	v_lshl_add_u64 v[124:125], v[8:9], 0, s[4:5]
	global_load_lds_dwordx4 v[122:123], off
	s_mov_b32 m0, s48
	v_mfma_f32_16x16x32_bf16 v[58:61], v[128:131], v[116:119], v[58:61]
	global_load_lds_dwordx4 v[124:125], off
	ds_read_b128 v[120:123], v20 offset:16384
	ds_read_b128 v[124:127], v20 offset:18432
	v_mfma_f32_16x16x32_bf16 v[106:109], v[132:135], v[116:119], v[106:109]
	ds_read_b128 v[128:131], v20 offset:20480
	ds_read_b128 v[132:135], v20 offset:22528
	ds_read_b128 v[116:119], v68
	s_waitcnt lgkmcnt(0)
	v_mfma_f32_16x16x32_bf16 v[46:49], v[120:123], v[116:119], v[46:49]
	s_mov_b64 s[4:5], 0x300
	v_lshl_add_u64 v[70:71], v[10:11], 0, s[4:5]
	s_mov_b32 m0, s46
	v_mfma_f32_16x16x32_bf16 v[54:57], v[124:127], v[116:119], v[54:57]
	v_readfirstlane_b32 s46, v26
	v_mfma_f32_16x16x32_bf16 v[62:65], v[128:131], v[116:119], v[62:65]
	v_mfma_f32_16x16x32_bf16 v[42:45], v[132:135], v[116:119], v[42:45]
	ds_read_b128 v[116:119], v68 offset:2048
	s_waitcnt lgkmcnt(0)
	v_mfma_f32_16x16x32_bf16 v[74:77], v[120:123], v[116:119], v[74:77]
	v_mfma_f32_16x16x32_bf16 v[78:81], v[124:127], v[116:119], v[78:81]
	v_mfma_f32_16x16x32_bf16 v[82:85], v[128:131], v[116:119], v[82:85]
	v_mfma_f32_16x16x32_bf16 v[86:89], v[132:135], v[116:119], v[86:89]
	ds_read_b128 v[116:119], v68 offset:4096
	s_waitcnt lgkmcnt(0)
	v_mfma_f32_16x16x32_bf16 v[94:97], v[120:123], v[116:119], v[94:97]
	v_mfma_f32_16x16x32_bf16 v[98:101], v[124:127], v[116:119], v[98:101]
	v_mfma_f32_16x16x32_bf16 v[102:105], v[128:131], v[116:119], v[102:105]
	v_mfma_f32_16x16x32_bf16 v[90:93], v[132:135], v[116:119], v[90:93]
	ds_read_b128 v[116:119], v68 offset:6144
	s_waitcnt vmcnt(0)
	s_waitcnt vmcnt(0) lgkmcnt(0)
	v_mfma_f32_16x16x32_bf16 v[38:41], v[120:123], v[116:119], v[38:41]
	s_barrier
; template <class Epi>
; DI void gemm_tile(const bf16_t* __restrict__ A, int lda, const bf16_t* __restrict__ Bt, int ldb, int K, int row0, int col0, char* lds, const Epi& epi) {
;     ...
;   for (int kt = 0; kt < KT; ++kt) {
;     asm volatile("s_waitcnt vmcnt(0)" ::: "memory");
;     __syncthreads();
;     const char* sa = lds + (kt & 1) * 32768 + (wr * 64 + fr) * 128;
;     const char* sb = lds + (kt & 1) * 32768 + 16384 + (wc * 64 + fr) * 128;
; #pragma unroll
;     for (int kk = 0; kk < 2; ++kk) {
;       if (kt + 1 < KT) { if (kk == 0) stage_a(kt + 1, (kt + 1) & 1); else stage_b(kt + 1, (kt + 1) & 1); }
;       bf16x8 a[4], b[4];
;       const int co = ((kk * 4 + fq) ^ swz) * 16;
; #pragma unroll
;       for (int m = 0; m < 4; ++m) a[m] = *(const bf16x8*)(sa + m * 2048 + co);
; #pragma unroll
;       for (int n = 0; n < 4; ++n) b[n] = *(const bf16x8*)(sb + n * 2048 + co);
; #pragma unroll
;       for (int m = 0; m < 4; ++m)
; #pragma unroll
;         for (int n = 0; n < 4; ++n) acc[m][n] = __builtin_amdgcn_mfma_f32_16x16x32_bf16(b[n], a[m], acc[m][n], 0, 0, 0);
;     }
;   }
	v_lshl_add_u64 v[120:121], v[12:13], 0, s[4:5]
	global_load_lds_dwordx4 v[70:71], off
	s_mov_b32 m0, s47
	v_lshl_add_u64 v[122:123], v[14:15], 0, s[4:5]
	global_load_lds_dwordx4 v[120:121], off
	s_mov_b32 m0, s26
	v_mfma_f32_16x16x32_bf16 v[50:53], v[124:127], v[116:119], v[50:53]
	v_lshl_add_u64 v[124:125], v[16:17], 0, s[4:5]
	global_load_lds_dwordx4 v[122:123], off
	s_mov_b32 m0, s36
	v_mfma_f32_16x16x32_bf16 v[58:61], v[128:131], v[116:119], v[58:61]
	global_load_lds_dwordx4 v[124:125], off
	ds_read_b128 v[120:123], v19 offset:49152
	v_mfma_f32_16x16x32_bf16 v[106:109], v[132:135], v[116:119], v[106:109]
	ds_read_b128 v[124:127], v19 offset:51200
	ds_read_b128 v[128:131], v19 offset:53248
	ds_read_b128 v[132:135], v19 offset:55296
	ds_read_b128 v[116:119], v18 offset:32768
	s_waitcnt lgkmcnt(0)
	v_mfma_f32_16x16x32_bf16 v[46:49], v[120:123], v[116:119], v[46:49]
	v_lshl_add_u64 v[70:71], v[2:3], 0, s[4:5]
	s_mov_b32 m0, s49
	v_readfirstlane_b32 s26, v35
	v_mfma_f32_16x16x32_bf16 v[54:57], v[124:127], v[116:119], v[54:57]
	v_readfirstlane_b32 s36, v31
	v_readfirstlane_b32 s47, v27
	v_readfirstlane_b32 s49, v25
	v_mfma_f32_16x16x32_bf16 v[62:65], v[128:131], v[116:119], v[62:65]
	v_mfma_f32_16x16x32_bf16 v[42:45], v[132:135], v[116:119], v[42:45]
	ds_read_b128 v[116:119], v18 offset:34816
	s_waitcnt lgkmcnt(0)
	v_mfma_f32_16x16x32_bf16 v[74:77], v[120:123], v[116:119], v[74:77]
	v_mfma_f32_16x16x32_bf16 v[78:81], v[124:127], v[116:119], v[78:81]
	v_mfma_f32_16x16x32_bf16 v[82:85], v[128:131], v[116:119], v[82:85]
	v_mfma_f32_16x16x32_bf16 v[86:89], v[132:135], v[116:119], v[86:89]
	ds_read_b128 v[116:119], v18 offset:36864
	s_waitcnt lgkmcnt(0)
	v_mfma_f32_16x16x32_bf16 v[94:97], v[120:123], v[116:119], v[94:97]
	v_mfma_f32_16x16x32_bf16 v[98:101], v[124:127], v[116:119], v[98:101]
	v_mfma_f32_16x16x32_bf16 v[102:105], v[128:131], v[116:119], v[102:105]
	v_mfma_f32_16x16x32_bf16 v[90:93], v[132:135], v[116:119], v[90:93]
	ds_read_b128 v[116:119], v18 offset:38912
	global_load_lds_dwordx4 v[70:71], off
	s_waitcnt lgkmcnt(0)
	v_mfma_f32_16x16x32_bf16 v[38:41], v[120:123], v[116:119], v[38:41]
	v_lshl_add_u64 v[120:121], v[4:5], 0, s[4:5]
	s_mov_b32 m0, s54
	v_lshl_add_u64 v[122:123], v[6:7], 0, s[4:5]
	global_load_lds_dwordx4 v[120:121], off
	s_mov_b32 m0, s55
	v_mfma_f32_16x16x32_bf16 v[50:53], v[124:127], v[116:119], v[50:53]
	v_lshl_add_u64 v[124:125], v[8:9], 0, s[4:5]
	global_load_lds_dwordx4 v[122:123], off
	s_mov_b32 m0, s42
	v_mfma_f32_16x16x32_bf16 v[58:61], v[128:131], v[116:119], v[58:61]
	global_load_lds_dwordx4 v[124:125], off
	ds_read_b128 v[120:123], v20 offset:49152
	ds_read_b128 v[124:127], v20 offset:51200
	v_mfma_f32_16x16x32_bf16 v[106:109], v[132:135], v[116:119], v[106:109]
	ds_read_b128 v[128:131], v20 offset:53248
	ds_read_b128 v[132:135], v20 offset:55296
	ds_read_b128 v[116:119], v68 offset:32768
	s_waitcnt lgkmcnt(0)
	v_mfma_f32_16x16x32_bf16 v[46:49], v[120:123], v[116:119], v[46:49]
	s_mov_b64 s[4:5], 0x380
	v_lshl_add_u64 v[70:71], v[10:11], 0, s[4:5]
	s_mov_b32 m0, s2
	v_mfma_f32_16x16x32_bf16 v[54:57], v[124:127], v[116:119], v[54:57]
	v_readfirstlane_b32 s2, v33
	v_readfirstlane_b32 s42, v22
	v_mfma_f32_16x16x32_bf16 v[62:65], v[128:131], v[116:119], v[62:65]
	v_mfma_f32_16x16x32_bf16 v[42:45], v[132:135], v[116:119], v[42:45]
	ds_read_b128 v[116:119], v68 offset:34816
	s_waitcnt lgkmcnt(0)
	v_mfma_f32_16x16x32_bf16 v[74:77], v[120:123], v[116:119], v[74:77]
	v_mfma_f32_16x16x32_bf16 v[78:81], v[124:127], v[116:119], v[78:81]
	v_mfma_f32_16x16x32_bf16 v[82:85], v[128:131], v[116:119], v[82:85]
	v_mfma_f32_16x16x32_bf16 v[86:89], v[132:135], v[116:119], v[86:89]
	ds_read_b128 v[116:119], v68 offset:36864
	s_waitcnt lgkmcnt(0)
	v_mfma_f32_16x16x32_bf16 v[94:97], v[120:123], v[116:119], v[94:97]
	v_mfma_f32_16x16x32_bf16 v[98:101], v[124:127], v[116:119], v[98:101]
	v_mfma_f32_16x16x32_bf16 v[102:105], v[128:131], v[116:119], v[102:105]
	v_mfma_f32_16x16x32_bf16 v[90:93], v[132:135], v[116:119], v[90:93]
	ds_read_b128 v[116:119], v68 offset:38912
	s_waitcnt vmcnt(0)
	s_waitcnt vmcnt(0) lgkmcnt(0)
	v_mfma_f32_16x16x32_bf16 v[38:41], v[120:123], v[116:119], v[38:41]
	s_barrier
	v_lshl_add_u64 v[120:121], v[12:13], 0, s[4:5]
	global_load_lds_dwordx4 v[70:71], off
	s_mov_b32 m0, s3
	v_lshl_add_u64 v[122:123], v[14:15], 0, s[4:5]
	global_load_lds_dwordx4 v[120:121], off
	s_mov_b32 m0, s28
	v_mfma_f32_16x16x32_bf16 v[50:53], v[124:127], v[116:119], v[50:53]
	v_lshl_add_u64 v[124:125], v[16:17], 0, s[4:5]
	global_load_lds_dwordx4 v[122:123], off
	s_mov_b32 m0, s29
	v_mfma_f32_16x16x32_bf16 v[58:61], v[128:131], v[116:119], v[58:61]
	global_load_lds_dwordx4 v[124:125], off
	ds_read_b128 v[120:123], v19 offset:16384
	v_mfma_f32_16x16x32_bf16 v[106:109], v[132:135], v[116:119], v[106:109]
	ds_read_b128 v[124:127], v19 offset:18432
	ds_read_b128 v[128:131], v19 offset:20480
	ds_read_b128 v[132:135], v19 offset:22528
	ds_read_b128 v[116:119], v18
	s_waitcnt lgkmcnt(0)
	v_mfma_f32_16x16x32_bf16 v[46:49], v[120:123], v[116:119], v[46:49]
	v_lshl_add_u64 v[70:71], v[2:3], 0, s[4:5]
	s_mov_b32 m0, s38
	v_readfirstlane_b32 s3, v34
	v_mfma_f32_16x16x32_bf16 v[54:57], v[124:127], v[116:119], v[54:57]
	v_readfirstlane_b32 s28, v36
	v_readfirstlane_b32 s29, v30
	v_readfirstlane_b32 s38, v24
	v_mfma_f32_16x16x32_bf16 v[62:65], v[128:131], v[116:119], v[62:65]
	v_mfma_f32_16x16x32_bf16 v[42:45], v[132:135], v[116:119], v[42:45]
	ds_read_b128 v[116:119], v18 offset:2048
	s_waitcnt lgkmcnt(0)
; template <class Epi>
; DI void gemm_tile(const bf16_t* __restrict__ A, int lda, const bf16_t* __restrict__ Bt, int ldb, int K, int row0, int col0, char* lds, const Epi& epi) {
;     ...
;   for (int kt = 0; kt < KT; ++kt) {
;     asm volatile("s_waitcnt vmcnt(0)" ::: "memory");
;     __syncthreads();
;     const char* sa = lds + (kt & 1) * 32768 + (wr * 64 + fr) * 128;
;     const char* sb = lds + (kt & 1) * 32768 + 16384 + (wc * 64 + fr) * 128;
; #pragma unroll
;     for (int kk = 0; kk < 2; ++kk) {
;       if (kt + 1 < KT) { if (kk == 0) stage_a(kt + 1, (kt + 1) & 1); else stage_b(kt + 1, (kt + 1) & 1); }
;       bf16x8 a[4], b[4];
;       const int co = ((kk * 4 + fq) ^ swz) * 16;
; #pragma unroll
;       for (int m = 0; m < 4; ++m) a[m] = *(const bf16x8*)(sa + m * 2048 + co);
; #pragma unroll
;       for (int n = 0; n < 4; ++n) b[n] = *(const bf16x8*)(sb + n * 2048 + co);
; #pragma unroll
;       for (int m = 0; m < 4; ++m)
; #pragma unroll
;         for (int n = 0; n < 4; ++n) acc[m][n] = __builtin_amdgcn_mfma_f32_16x16x32_bf16(b[n], a[m], acc[m][n], 0, 0, 0);
;     }
;   }
	v_mfma_f32_16x16x32_bf16 v[74:77], v[120:123], v[116:119], v[74:77]
	v_mfma_f32_16x16x32_bf16 v[78:81], v[124:127], v[116:119], v[78:81]
	v_mfma_f32_16x16x32_bf16 v[82:85], v[128:131], v[116:119], v[82:85]
	v_mfma_f32_16x16x32_bf16 v[86:89], v[132:135], v[116:119], v[86:89]
	ds_read_b128 v[116:119], v18 offset:4096
	s_waitcnt lgkmcnt(0)
	v_mfma_f32_16x16x32_bf16 v[94:97], v[120:123], v[116:119], v[94:97]
	v_mfma_f32_16x16x32_bf16 v[98:101], v[124:127], v[116:119], v[98:101]
	v_mfma_f32_16x16x32_bf16 v[102:105], v[128:131], v[116:119], v[102:105]
	v_mfma_f32_16x16x32_bf16 v[90:93], v[132:135], v[116:119], v[90:93]
	ds_read_b128 v[116:119], v18 offset:6144
	global_load_lds_dwordx4 v[70:71], off
	s_waitcnt lgkmcnt(0)
	v_mfma_f32_16x16x32_bf16 v[38:41], v[120:123], v[116:119], v[38:41]
	v_lshl_add_u64 v[120:121], v[4:5], 0, s[4:5]
	s_mov_b32 m0, s39
	v_lshl_add_u64 v[122:123], v[6:7], 0, s[4:5]
	global_load_lds_dwordx4 v[120:121], off
	s_mov_b32 m0, s43
	v_mfma_f32_16x16x32_bf16 v[50:53], v[124:127], v[116:119], v[50:53]
	v_lshl_add_u64 v[124:125], v[8:9], 0, s[4:5]
	global_load_lds_dwordx4 v[122:123], off
	s_mov_b32 m0, s48
	v_mfma_f32_16x16x32_bf16 v[58:61], v[128:131], v[116:119], v[58:61]
	global_load_lds_dwordx4 v[124:125], off
	ds_read_b128 v[120:123], v20 offset:16384
	ds_read_b128 v[124:127], v20 offset:18432
	v_mfma_f32_16x16x32_bf16 v[106:109], v[132:135], v[116:119], v[106:109]
	ds_read_b128 v[128:131], v20 offset:20480
	ds_read_b128 v[132:135], v20 offset:22528
	ds_read_b128 v[116:119], v68
	s_waitcnt lgkmcnt(0)
	v_mfma_f32_16x16x32_bf16 v[46:49], v[120:123], v[116:119], v[46:49]
	v_lshl_add_u64 v[70:71], v[10:11], 0, s[30:31]
	s_mov_b32 m0, s2
	s_mov_b64 s[4:5], 0x480
	v_mfma_f32_16x16x32_bf16 v[54:57], v[124:127], v[116:119], v[54:57]
	v_readfirstlane_b32 s39, v23
	v_readfirstlane_b32 s43, v21
	v_lshl_add_u64 v[22:23], v[2:3], 0, s[4:5]
	v_mfma_f32_16x16x32_bf16 v[62:65], v[128:131], v[116:119], v[62:65]
	v_readfirstlane_b32 s48, v28
	v_mfma_f32_16x16x32_bf16 v[42:45], v[132:135], v[116:119], v[42:45]
	ds_read_b128 v[116:119], v68 offset:2048
	s_waitcnt lgkmcnt(0)
	v_mfma_f32_16x16x32_bf16 v[74:77], v[120:123], v[116:119], v[74:77]
	v_mfma_f32_16x16x32_bf16 v[78:81], v[124:127], v[116:119], v[78:81]
	v_mfma_f32_16x16x32_bf16 v[82:85], v[128:131], v[116:119], v[82:85]
	v_mfma_f32_16x16x32_bf16 v[86:89], v[132:135], v[116:119], v[86:89]
	ds_read_b128 v[116:119], v68 offset:4096
	s_waitcnt lgkmcnt(0)
	v_mfma_f32_16x16x32_bf16 v[94:97], v[120:123], v[116:119], v[94:97]
	v_mfma_f32_16x16x32_bf16 v[98:101], v[124:127], v[116:119], v[98:101]
	v_mfma_f32_16x16x32_bf16 v[102:105], v[128:131], v[116:119], v[102:105]
	v_mfma_f32_16x16x32_bf16 v[90:93], v[132:135], v[116:119], v[90:93]
	ds_read_b128 v[116:119], v68 offset:6144
	s_waitcnt vmcnt(0)
	s_waitcnt vmcnt(0) lgkmcnt(0)
	v_mfma_f32_16x16x32_bf16 v[38:41], v[120:123], v[116:119], v[38:41]
	s_barrier
	v_lshl_add_u64 v[120:121], v[12:13], 0, s[30:31]
	global_load_lds_dwordx4 v[70:71], off
	s_mov_b32 m0, s3
	v_lshl_add_u64 v[122:123], v[14:15], 0, s[30:31]
	global_load_lds_dwordx4 v[120:121], off
	s_mov_b32 m0, s26
	v_mfma_f32_16x16x32_bf16 v[50:53], v[124:127], v[116:119], v[50:53]
	v_lshl_add_u64 v[124:125], v[16:17], 0, s[30:31]
	global_load_lds_dwordx4 v[122:123], off
	s_mov_b32 m0, s28
	v_mfma_f32_16x16x32_bf16 v[58:61], v[128:131], v[116:119], v[58:61]
	global_load_lds_dwordx4 v[124:125], off
	ds_read_b128 v[34:37], v19 offset:49152
	ds_read_b128 v[120:123], v19 offset:51200
	ds_read_b128 v[124:127], v19 offset:53248
	ds_read_b128 v[128:131], v19 offset:55296
	v_mfma_f32_16x16x32_bf16 v[106:109], v[132:135], v[116:119], v[106:109]
	ds_read_b128 v[116:119], v18 offset:32768
	v_lshl_add_u64 v[70:71], v[2:3], 0, s[30:31]
	s_mov_b32 m0, s27
	s_waitcnt lgkmcnt(0)
	v_mfma_f32_16x16x32_bf16 v[46:49], v[34:37], v[116:119], v[46:49]
	v_lshl_add_u64 v[132:133], v[8:9], 0, s[30:31]
	v_mfma_f32_16x16x32_bf16 v[54:57], v[120:123], v[116:119], v[54:57]
	v_mfma_f32_16x16x32_bf16 v[62:65], v[124:127], v[116:119], v[62:65]
	v_mfma_f32_16x16x32_bf16 v[42:45], v[128:131], v[116:119], v[42:45]
	ds_read_b128 v[116:119], v18 offset:34816
	s_waitcnt lgkmcnt(0)
	v_mfma_f32_16x16x32_bf16 v[74:77], v[34:37], v[116:119], v[74:77]
	v_mfma_f32_16x16x32_bf16 v[78:81], v[120:123], v[116:119], v[78:81]
	v_mfma_f32_16x16x32_bf16 v[82:85], v[124:127], v[116:119], v[82:85]
	v_mfma_f32_16x16x32_bf16 v[86:89], v[128:131], v[116:119], v[86:89]
	ds_read_b128 v[116:119], v18 offset:36864
	s_waitcnt lgkmcnt(0)
	v_mfma_f32_16x16x32_bf16 v[94:97], v[34:37], v[116:119], v[94:97]
	v_mfma_f32_16x16x32_bf16 v[98:101], v[120:123], v[116:119], v[98:101]
	v_mfma_f32_16x16x32_bf16 v[102:105], v[124:127], v[116:119], v[102:105]
	v_mfma_f32_16x16x32_bf16 v[90:93], v[128:131], v[116:119], v[90:93]
	ds_read_b128 v[116:119], v18 offset:38912
	global_load_lds_dwordx4 v[70:71], off
	s_waitcnt lgkmcnt(0)
	v_mfma_f32_16x16x32_bf16 v[34:37], v[34:37], v[116:119], v[38:41]
	s_mov_b32 m0, s29
	v_lshl_add_u64 v[70:71], v[14:15], 0, s[4:5]
	v_mfma_f32_16x16x32_bf16 v[38:41], v[120:123], v[116:119], v[50:53]
	v_lshl_add_u64 v[120:121], v[4:5], 0, s[30:31]
	v_lshl_add_u64 v[122:123], v[6:7], 0, s[30:31]
	global_load_lds_dwordx4 v[120:121], off
	s_mov_b32 m0, s36
	v_mfma_f32_16x16x32_bf16 v[50:53], v[124:127], v[116:119], v[58:61]
	global_load_lds_dwordx4 v[122:123], off
	s_mov_b32 m0, s37
	v_mfma_f32_16x16x32_bf16 v[58:61], v[128:131], v[116:119], v[106:109]
	global_load_lds_dwordx4 v[132:133], off
	ds_read_b128 v[30:33], v20 offset:49152
	ds_read_b128 v[116:119], v20 offset:51200
	ds_read_b128 v[120:123], v20 offset:53248
	ds_read_b128 v[124:127], v20 offset:55296
	ds_read_b128 v[106:109], v68 offset:32768
	s_waitcnt lgkmcnt(0)
	v_mfma_f32_16x16x32_bf16 v[46:49], v[30:33], v[106:109], v[46:49]
	s_mov_b32 m0, s38
	v_mfma_f32_16x16x32_bf16 v[54:57], v[116:119], v[106:109], v[54:57]
	v_mfma_f32_16x16x32_bf16 v[62:65], v[120:123], v[106:109], v[62:65]
	v_mfma_f32_16x16x32_bf16 v[42:45], v[124:127], v[106:109], v[42:45]
	ds_read_b128 v[106:109], v68 offset:34816
	s_waitcnt lgkmcnt(0)
	v_mfma_f32_16x16x32_bf16 v[74:77], v[30:33], v[106:109], v[74:77]
	v_mfma_f32_16x16x32_bf16 v[78:81], v[116:119], v[106:109], v[78:81]
	v_mfma_f32_16x16x32_bf16 v[82:85], v[120:123], v[106:109], v[82:85]
	v_mfma_f32_16x16x32_bf16 v[86:89], v[124:127], v[106:109], v[86:89]
	ds_read_b128 v[106:109], v68 offset:36864
	s_waitcnt lgkmcnt(0)
	v_mfma_f32_16x16x32_bf16 v[94:97], v[30:33], v[106:109], v[94:97]
	v_mfma_f32_16x16x32_bf16 v[98:101], v[116:119], v[106:109], v[98:101]
	v_mfma_f32_16x16x32_bf16 v[102:105], v[120:123], v[106:109], v[102:105]
	v_mfma_f32_16x16x32_bf16 v[90:93], v[124:127], v[106:109], v[90:93]
	ds_read_b128 v[106:109], v68 offset:38912
	s_waitcnt vmcnt(0)
	s_waitcnt vmcnt(0) lgkmcnt(0)
	v_mfma_f32_16x16x32_bf16 v[30:33], v[30:33], v[106:109], v[34:37]
	s_barrier
; template <class Epi>
; DI void gemm_tile(const bf16_t* __restrict__ A, int lda, const bf16_t* __restrict__ Bt, int ldb, int K, int row0, int col0, char* lds, const Epi& epi) {
;     ...
;   for (int kt = 0; kt < KT; ++kt) {
;     asm volatile("s_waitcnt vmcnt(0)" ::: "memory");
;     __syncthreads();
;     const char* sa = lds + (kt & 1) * 32768 + (wr * 64 + fr) * 128;
;     const char* sb = lds + (kt & 1) * 32768 + 16384 + (wc * 64 + fr) * 128;
; #pragma unroll
;     for (int kk = 0; kk < 2; ++kk) {
;       if (kt + 1 < KT) { if (kk == 0) stage_a(kt + 1, (kt + 1) & 1); else stage_b(kt + 1, (kt + 1) & 1); }
;       bf16x8 a[4], b[4];
;       const int co = ((kk * 4 + fq) ^ swz) * 16;
; #pragma unroll
;       for (int m = 0; m < 4; ++m) a[m] = *(const bf16x8*)(sa + m * 2048 + co);
; #pragma unroll
;       for (int n = 0; n < 4; ++n) b[n] = *(const bf16x8*)(sb + n * 2048 + co);
; #pragma unroll
;       for (int m = 0; m < 4; ++m)
; #pragma unroll
;         for (int n = 0; n < 4; ++n) acc[m][n] = __builtin_amdgcn_mfma_f32_16x16x32_bf16(b[n], a[m], acc[m][n], 0, 0, 0);
;     }
;   }
	v_mfma_f32_16x16x32_bf16 v[34:37], v[116:119], v[106:109], v[38:41]
	v_lshl_add_u64 v[116:117], v[16:17], 0, s[4:5]
	v_mfma_f32_16x16x32_bf16 v[38:41], v[120:123], v[106:109], v[50:53]
	s_nop 2
	v_lshl_add_u64 v[50:51], v[10:11], 0, s[4:5]
	v_lshl_add_u64 v[52:53], v[12:13], 0, s[4:5]
	global_load_lds_dwordx4 v[50:51], off
	s_mov_b32 m0, s39
	v_mfma_f32_16x16x32_bf16 v[58:61], v[124:127], v[106:109], v[58:61]
	global_load_lds_dwordx4 v[52:53], off
	s_mov_b32 m0, s42
	s_nop 0
	global_load_lds_dwordx4 v[70:71], off
	s_mov_b32 m0, s43
	v_lshl_add_u64 v[70:71], v[8:9], 0, s[4:5]
	global_load_lds_dwordx4 v[116:117], off
	ds_read_b128 v[50:53], v19 offset:16384
	ds_read_b128 v[106:109], v18
	ds_read_b128 v[116:119], v19 offset:18432
	ds_read_b128 v[120:123], v19 offset:20480
	ds_read_b128 v[124:127], v19 offset:22528
	s_waitcnt lgkmcnt(0)
	v_mfma_f32_16x16x32_bf16 v[46:49], v[50:53], v[106:109], v[46:49]
	s_mov_b32 m0, s46
	v_mfma_f32_16x16x32_bf16 v[54:57], v[116:119], v[106:109], v[54:57]
	v_mfma_f32_16x16x32_bf16 v[62:65], v[120:123], v[106:109], v[62:65]
	v_mfma_f32_16x16x32_bf16 v[42:45], v[124:127], v[106:109], v[42:45]
	ds_read_b128 v[106:109], v18 offset:2048
	s_waitcnt lgkmcnt(0)
	v_mfma_f32_16x16x32_bf16 v[74:77], v[50:53], v[106:109], v[74:77]
	v_mfma_f32_16x16x32_bf16 v[78:81], v[116:119], v[106:109], v[78:81]
	v_mfma_f32_16x16x32_bf16 v[82:85], v[120:123], v[106:109], v[82:85]
	v_mfma_f32_16x16x32_bf16 v[86:89], v[124:127], v[106:109], v[86:89]
	ds_read_b128 v[106:109], v18 offset:4096
	s_waitcnt lgkmcnt(0)
	v_mfma_f32_16x16x32_bf16 v[94:97], v[50:53], v[106:109], v[94:97]
	v_mfma_f32_16x16x32_bf16 v[98:101], v[116:119], v[106:109], v[98:101]
	v_mfma_f32_16x16x32_bf16 v[102:105], v[120:123], v[106:109], v[102:105]
	v_mfma_f32_16x16x32_bf16 v[90:93], v[124:127], v[106:109], v[90:93]
	ds_read_b128 v[106:109], v18 offset:6144
	global_load_lds_dwordx4 v[22:23], off
	s_waitcnt lgkmcnt(0)
	v_mfma_f32_16x16x32_bf16 v[30:33], v[50:53], v[106:109], v[30:33]
	v_lshl_add_u64 v[50:51], v[4:5], 0, s[4:5]
	s_mov_b32 m0, s47
	v_lshl_add_u64 v[52:53], v[6:7], 0, s[4:5]
	global_load_lds_dwordx4 v[50:51], off
	s_mov_b32 m0, s48
	v_mfma_f32_16x16x32_bf16 v[34:37], v[116:119], v[106:109], v[34:37]
	global_load_lds_dwordx4 v[52:53], off
	s_mov_b32 m0, s49
	v_mfma_f32_16x16x32_bf16 v[38:41], v[120:123], v[106:109], v[38:41]
	global_load_lds_dwordx4 v[70:71], off
	ds_read_b128 v[22:25], v20 offset:16384
	v_mfma_f32_16x16x32_bf16 v[26:29], v[124:127], v[106:109], v[58:61]
	ds_read_b128 v[106:109], v20 offset:20480
	ds_read_b128 v[116:119], v20 offset:22528
	ds_read_b128 v[50:53], v68
	ds_read_b128 v[58:61], v20 offset:18432
	s_waitcnt lgkmcnt(0)
	v_mfma_f32_16x16x32_bf16 v[46:49], v[22:25], v[50:53], v[46:49]
	s_mov_b64 s[4:5], 0x500
	s_mov_b32 m0, s2
	v_lshl_add_u64 v[70:71], v[6:7], 0, s[4:5]
	v_mfma_f32_16x16x32_bf16 v[54:57], v[58:61], v[50:53], v[54:57]
	v_mfma_f32_16x16x32_bf16 v[62:65], v[106:109], v[50:53], v[62:65]
	v_mfma_f32_16x16x32_bf16 v[42:45], v[116:119], v[50:53], v[42:45]
	ds_read_b128 v[50:53], v68 offset:2048
	s_waitcnt lgkmcnt(0)
	v_mfma_f32_16x16x32_bf16 v[74:77], v[22:25], v[50:53], v[74:77]
	v_mfma_f32_16x16x32_bf16 v[78:81], v[58:61], v[50:53], v[78:81]
	v_mfma_f32_16x16x32_bf16 v[82:85], v[106:109], v[50:53], v[82:85]
	v_mfma_f32_16x16x32_bf16 v[50:53], v[116:119], v[50:53], v[86:89]
	s_nop 2
	ds_read_b128 v[86:89], v68 offset:4096
	s_waitcnt lgkmcnt(0)
	v_mfma_f32_16x16x32_bf16 v[94:97], v[22:25], v[86:89], v[94:97]
	v_mfma_f32_16x16x32_bf16 v[98:101], v[58:61], v[86:89], v[98:101]
	v_mfma_f32_16x16x32_bf16 v[102:105], v[106:109], v[86:89], v[102:105]
	v_mfma_f32_16x16x32_bf16 v[86:89], v[116:119], v[86:89], v[90:93]
	s_nop 2
	ds_read_b128 v[90:93], v68 offset:6144
	s_waitcnt lgkmcnt(0)
	v_mfma_f32_16x16x32_bf16 v[22:25], v[22:25], v[90:93], v[30:33]
	s_waitcnt vmcnt(0)
	s_waitcnt vmcnt(0)
	s_barrier
	v_mfma_f32_16x16x32_bf16 v[30:33], v[58:61], v[90:93], v[34:37]
	v_lshl_add_u64 v[58:59], v[14:15], 0, s[4:5]
	v_lshl_add_u64 v[60:61], v[16:17], 0, s[4:5]
	v_mfma_f32_16x16x32_bf16 v[34:37], v[106:109], v[90:93], v[38:41]
	s_nop 2
	v_lshl_add_u64 v[38:39], v[10:11], 0, s[4:5]
	v_lshl_add_u64 v[40:41], v[12:13], 0, s[4:5]
	global_load_lds_dwordx4 v[38:39], off
	s_mov_b32 m0, s3
	v_mfma_f32_16x16x32_bf16 v[26:29], v[116:119], v[90:93], v[26:29]
	global_load_lds_dwordx4 v[40:41], off
	s_mov_b32 m0, s26
	s_mov_b64 s[2:3], 0x580
	global_load_lds_dwordx4 v[58:59], off
	s_mov_b32 m0, s28
	v_lshl_add_u64 v[10:11], v[10:11], 0, s[2:3]
	global_load_lds_dwordx4 v[60:61], off
	ds_read_b128 v[38:41], v19 offset:49152
	ds_read_b128 v[58:61], v18 offset:32768
	ds_read_b128 v[90:93], v19 offset:51200
	ds_read_b128 v[106:109], v19 offset:53248
	ds_read_b128 v[116:119], v19 offset:55296
	s_waitcnt lgkmcnt(0)
	v_mfma_f32_16x16x32_bf16 v[46:49], v[38:41], v[58:61], v[46:49]
	s_mov_b32 m0, s27
	v_lshl_add_u64 v[12:13], v[12:13], 0, s[2:3]
	v_lshl_add_u64 v[14:15], v[14:15], 0, s[2:3]
	v_mfma_f32_16x16x32_bf16 v[54:57], v[90:93], v[58:61], v[54:57]
	v_lshl_add_u64 v[16:17], v[16:17], 0, s[2:3]
	v_lshl_add_u64 v[6:7], v[6:7], 0, s[2:3]
	v_mfma_f32_16x16x32_bf16 v[62:65], v[106:109], v[58:61], v[62:65]
	v_mfma_f32_16x16x32_bf16 v[42:45], v[116:119], v[58:61], v[42:45]
	ds_read_b128 v[58:61], v18 offset:34816
	s_waitcnt lgkmcnt(0)
	v_mfma_f32_16x16x32_bf16 v[74:77], v[38:41], v[58:61], v[74:77]
	v_mfma_f32_16x16x32_bf16 v[78:81], v[90:93], v[58:61], v[78:81]
	v_mfma_f32_16x16x32_bf16 v[82:85], v[106:109], v[58:61], v[82:85]
	v_mfma_f32_16x16x32_bf16 v[50:53], v[116:119], v[58:61], v[50:53]
	ds_read_b128 v[58:61], v18 offset:36864
	s_waitcnt lgkmcnt(0)
; template <class Epi>
; DI void gemm_tile(const bf16_t* __restrict__ A, int lda, const bf16_t* __restrict__ Bt, int ldb, int K, int row0, int col0, char* lds, const Epi& epi) {
;     ...
;   for (int kt = 0; kt < KT; ++kt) {
;     asm volatile("s_waitcnt vmcnt(0)" ::: "memory");
;     __syncthreads();
;     const char* sa = lds + (kt & 1) * 32768 + (wr * 64 + fr) * 128;
;     const char* sb = lds + (kt & 1) * 32768 + 16384 + (wc * 64 + fr) * 128;
; #pragma unroll
;     for (int kk = 0; kk < 2; ++kk) {
;       if (kt + 1 < KT) { if (kk == 0) stage_a(kt + 1, (kt + 1) & 1); else stage_b(kt + 1, (kt + 1) & 1); }
;       bf16x8 a[4], b[4];
;       const int co = ((kk * 4 + fq) ^ swz) * 16;
; #pragma unroll
;       for (int m = 0; m < 4; ++m) a[m] = *(const bf16x8*)(sa + m * 2048 + co);
; #pragma unroll
;       for (int n = 0; n < 4; ++n) b[n] = *(const bf16x8*)(sb + n * 2048 + co);
; #pragma unroll
;       for (int m = 0; m < 4; ++m)
; #pragma unroll
;         for (int n = 0; n < 4; ++n) acc[m][n] = __builtin_amdgcn_mfma_f32_16x16x32_bf16(b[n], a[m], acc[m][n], 0, 0, 0);
;     }
;   }
	v_mfma_f32_16x16x32_bf16 v[94:97], v[38:41], v[58:61], v[94:97]
	v_mfma_f32_16x16x32_bf16 v[98:101], v[90:93], v[58:61], v[98:101]
	v_mfma_f32_16x16x32_bf16 v[102:105], v[106:109], v[58:61], v[102:105]
	v_mfma_f32_16x16x32_bf16 v[58:61], v[116:119], v[58:61], v[86:89]
	s_nop 2
	ds_read_b128 v[86:89], v18 offset:38912
	s_waitcnt lgkmcnt(0)
	v_mfma_f32_16x16x32_bf16 v[22:25], v[38:41], v[86:89], v[22:25]
	v_lshl_add_u64 v[38:39], v[2:3], 0, s[4:5]
	v_lshl_add_u64 v[40:41], v[4:5], 0, s[4:5]
	global_load_lds_dwordx4 v[38:39], off
	s_mov_b32 m0, s29
	v_mfma_f32_16x16x32_bf16 v[30:33], v[90:93], v[86:89], v[30:33]
	global_load_lds_dwordx4 v[40:41], off
	s_mov_b32 m0, s36
	v_lshl_add_u64 v[90:91], v[8:9], 0, s[4:5]
	global_load_lds_dwordx4 v[70:71], off
	s_mov_b32 m0, s37
	v_mfma_f32_16x16x32_bf16 v[34:37], v[106:109], v[86:89], v[34:37]
	global_load_lds_dwordx4 v[90:91], off
	ds_read_b128 v[38:41], v20 offset:49152
	ds_read_b128 v[90:93], v20 offset:51200
	v_mfma_f32_16x16x32_bf16 v[26:29], v[116:119], v[86:89], v[26:29]
	ds_read_b128 v[106:109], v20 offset:53248
	ds_read_b128 v[116:119], v20 offset:55296
	ds_read_b128 v[86:89], v68 offset:32768
	s_waitcnt lgkmcnt(0)
	v_mfma_f32_16x16x32_bf16 v[46:49], v[38:41], v[86:89], v[46:49]
	s_mov_b32 m0, s38
	v_lshl_add_u64 v[70:71], v[2:3], 0, s[2:3]
	v_lshl_add_u64 v[8:9], v[8:9], 0, s[2:3]
	v_mfma_f32_16x16x32_bf16 v[54:57], v[90:93], v[86:89], v[54:57]
	v_mfma_f32_16x16x32_bf16 v[62:65], v[106:109], v[86:89], v[62:65]
	v_mfma_f32_16x16x32_bf16 v[42:45], v[116:119], v[86:89], v[42:45]
	ds_read_b128 v[86:89], v68 offset:34816
	s_waitcnt lgkmcnt(0)
	v_mfma_f32_16x16x32_bf16 v[74:77], v[38:41], v[86:89], v[74:77]
	v_mfma_f32_16x16x32_bf16 v[78:81], v[90:93], v[86:89], v[78:81]
	v_mfma_f32_16x16x32_bf16 v[82:85], v[106:109], v[86:89], v[82:85]
	v_mfma_f32_16x16x32_bf16 v[50:53], v[116:119], v[86:89], v[50:53]
	ds_read_b128 v[86:89], v68 offset:36864
	s_waitcnt lgkmcnt(0)
	v_mfma_f32_16x16x32_bf16 v[94:97], v[38:41], v[86:89], v[94:97]
	v_mfma_f32_16x16x32_bf16 v[98:101], v[90:93], v[86:89], v[98:101]
	v_mfma_f32_16x16x32_bf16 v[102:105], v[106:109], v[86:89], v[102:105]
	v_mfma_f32_16x16x32_bf16 v[58:61], v[116:119], v[86:89], v[58:61]
	ds_read_b128 v[86:89], v68 offset:38912
	s_waitcnt vmcnt(0)
	s_waitcnt vmcnt(0) lgkmcnt(0)
	s_barrier
	global_load_lds_dwordx4 v[10:11], off
	s_mov_b32 m0, s39
	v_mfma_f32_16x16x32_bf16 v[22:25], v[38:41], v[86:89], v[22:25]
	global_load_lds_dwordx4 v[12:13], off
	s_mov_b32 m0, s42
	v_mfma_f32_16x16x32_bf16 v[30:33], v[90:93], v[86:89], v[30:33]
	global_load_lds_dwordx4 v[14:15], off
	s_mov_b32 m0, s43
	v_mfma_f32_16x16x32_bf16 v[34:37], v[106:109], v[86:89], v[34:37]
	global_load_lds_dwordx4 v[16:17], off
	ds_read_b128 v[10:13], v19 offset:16384
	v_mfma_f32_16x16x32_bf16 v[14:17], v[116:119], v[86:89], v[26:29]
	ds_read_b128 v[86:89], v19 offset:20480
	ds_read_b128 v[90:93], v19 offset:22528
	s_mov_b32 m0, s46
	ds_read_b128 v[26:29], v18
	s_waitcnt lgkmcnt(0)
	v_mfma_f32_16x16x32_bf16 v[38:41], v[10:13], v[26:29], v[46:49]
	s_nop 2
	ds_read_b128 v[46:49], v19 offset:18432
	s_waitcnt lgkmcnt(0)
	v_mfma_f32_16x16x32_bf16 v[54:57], v[46:49], v[26:29], v[54:57]
	v_mfma_f32_16x16x32_bf16 v[62:65], v[86:89], v[26:29], v[62:65]
	v_mfma_f32_16x16x32_bf16 v[26:29], v[90:93], v[26:29], v[42:45]
	s_nop 2
	ds_read_b128 v[42:45], v18 offset:2048
	s_waitcnt lgkmcnt(0)
	v_mfma_f32_16x16x32_bf16 v[74:77], v[10:13], v[42:45], v[74:77]
	v_mfma_f32_16x16x32_bf16 v[78:81], v[46:49], v[42:45], v[78:81]
	v_mfma_f32_16x16x32_bf16 v[82:85], v[86:89], v[42:45], v[82:85]
	v_mfma_f32_16x16x32_bf16 v[42:45], v[90:93], v[42:45], v[50:53]
	s_nop 2
	ds_read_b128 v[50:53], v18 offset:4096
	s_waitcnt lgkmcnt(0)
	v_mfma_f32_16x16x32_bf16 v[94:97], v[10:13], v[50:53], v[94:97]
	v_mfma_f32_16x16x32_bf16 v[98:101], v[46:49], v[50:53], v[98:101]
	v_mfma_f32_16x16x32_bf16 v[102:105], v[86:89], v[50:53], v[102:105]
	v_mfma_f32_16x16x32_bf16 v[50:53], v[90:93], v[50:53], v[58:61]
	s_nop 2
	ds_read_b128 v[58:61], v18 offset:6144
	s_waitcnt lgkmcnt(0)
	v_mfma_f32_16x16x32_bf16 v[10:13], v[10:13], v[58:61], v[22:25]
	global_load_lds_dwordx4 v[70:71], off
	s_mov_b32 m0, s47
	v_mfma_f32_16x16x32_bf16 v[22:25], v[46:49], v[58:61], v[30:33]
	s_nop 2
	v_lshl_add_u64 v[30:31], v[4:5], 0, s[2:3]
	global_load_lds_dwordx4 v[30:31], off
	s_mov_b32 m0, s48
	v_mfma_f32_16x16x32_bf16 v[2:5], v[86:89], v[58:61], v[34:37]
	global_load_lds_dwordx4 v[6:7], off
	s_mov_b32 m0, s49
	v_mfma_f32_16x16x32_bf16 v[14:17], v[90:93], v[58:61], v[14:17]
	global_load_lds_dwordx4 v[8:9], off
	ds_read_b128 v[6:9], v20 offset:16384
	ds_read_b128 v[30:33], v68
	s_waitcnt lgkmcnt(0)
	v_mfma_f32_16x16x32_bf16 v[34:37], v[6:9], v[30:33], v[38:41]
	s_nop 2
	ds_read_b128 v[38:41], v20 offset:18432
	s_waitcnt lgkmcnt(0)
	v_mfma_f32_16x16x32_bf16 v[46:49], v[38:41], v[30:33], v[54:57]
	s_nop 2
	ds_read_b128 v[54:57], v20 offset:20480
	s_waitcnt lgkmcnt(0)
	v_mfma_f32_16x16x32_bf16 v[58:61], v[54:57], v[30:33], v[62:65]
	s_nop 2
	ds_read_b128 v[62:65], v20 offset:22528
	s_waitcnt lgkmcnt(0)
	v_mfma_f32_16x16x32_bf16 v[26:29], v[62:65], v[30:33], v[26:29]
	ds_read_b128 v[30:33], v68 offset:2048
	s_waitcnt lgkmcnt(0)
	v_mfma_f32_16x16x32_bf16 v[74:77], v[6:9], v[30:33], v[74:77]
	v_mfma_f32_16x16x32_bf16 v[78:81], v[38:41], v[30:33], v[78:81]
	v_mfma_f32_16x16x32_bf16 v[82:85], v[54:57], v[30:33], v[82:85]
	v_mfma_f32_16x16x32_bf16 v[30:33], v[62:65], v[30:33], v[42:45]
	s_nop 2
	ds_read_b128 v[42:45], v68 offset:4096
	s_waitcnt lgkmcnt(0)
	v_mfma_f32_16x16x32_bf16 v[86:89], v[6:9], v[42:45], v[94:97]
	v_mfma_f32_16x16x32_bf16 v[90:93], v[38:41], v[42:45], v[98:101]
	v_mfma_f32_16x16x32_bf16 v[94:97], v[54:57], v[42:45], v[102:105]
	v_mfma_f32_16x16x32_bf16 v[42:45], v[62:65], v[42:45], v[50:53]
	s_nop 2
	ds_read_b128 v[50:53], v68 offset:6144
	s_waitcnt lgkmcnt(0)
	v_mfma_f32_16x16x32_bf16 v[6:9], v[6:9], v[50:53], v[10:13]
	s_waitcnt vmcnt(0)
	s_waitcnt vmcnt(0)
	s_barrier
;   DI void operator()(const f32x4 (&acc)[4][4], int r0, int c0, int fr, int fq) const {
;     ...
; #pragma unroll
;       for (int m = 0; m < 4; ++m) {
;         const int row = r0 + m * 16 + fr; const float rs = rsqrtf(rstd[row] * (1.f / 768.f) + EPSF);
;         const int b = row / TB, s = row % TB; const bool lat = s >= NCTX; const int sp = s - NCTX;
; #pragma unroll
;         for (int hh = 0; hh < 2; ++hh) {
;           const int h = ((c0 - 384) >> 5) + hh;
;           float ss = 0.f;
; #pragma unroll
;           for (int nn = 0; nn < 2; ++nn)
; #pragma unroll
;             for (int j = 0; j < 4; ++j) { float v = acc[m][hh * 2 + nn][j] * rs; ss += v * v; }
;           ss += __shfl_xor(ss, 16); ss += __shfl_xor(ss, 32);
;           const float inv = rsqrtf(ss * (1.f / 32.f) + EPSF) * rs;
;           bf16_t* dst = Q + ((size_t)(b * 6 + h) * TB + s) * 96 + 64;
; #pragma unroll
;           for (int nn = 0; nn < 2; ++nn) {
;             const int d = nn * 16 + fq * 4; f32x4 g = *(const f32x4*)(gr + d);
;             float o[4];
; #pragma unroll
;             for (int j = 0; j < 4; ++j) {
;               float val = acc[m][hh * 2 + nn][j] * inv * g[j];
;               float partner = __shfl_xor(val, 32);
;               if (lat) {
;                 const float* rt = rope + ((nn == 0 ? (sp >> 6) : (sp & 63)) * 8 + ((fq * 4 + j) & 7)) * 2; const float cs = rt[0], sn = rt[1];
;                 val = fq < 2 ? val * cs - partner * sn : val * cs + partner * sn;
	v_mfma_f32_16x16x32_bf16 v[10:13], v[38:41], v[50:53], v[22:25]
	ds_read_b128 v[38:41], v18 offset:32768
	ds_read_b128 v[106:109], v20 offset:49152
	v_mfma_f32_16x16x32_bf16 v[2:5], v[54:57], v[50:53], v[2:5]
	ds_read_b128 v[54:57], v19 offset:53248
	ds_read_b128 v[22:25], v19 offset:49152
	ds_read_b128 v[120:123], v20 offset:51200
	v_mfma_f32_16x16x32_bf16 v[14:17], v[62:65], v[50:53], v[14:17]
	ds_read_b128 v[50:53], v19 offset:51200
	ds_read_b128 v[124:127], v20 offset:53248
	s_waitcnt lgkmcnt(4)
	v_mfma_f32_16x16x32_bf16 v[98:101], v[54:57], v[38:41], v[58:61]
	s_nop 2
	ds_read_b128 v[58:61], v19 offset:55296
	s_waitcnt lgkmcnt(4)
	v_mfma_f32_16x16x32_bf16 v[34:37], v[22:25], v[38:41], v[34:37]
	s_waitcnt lgkmcnt(2)
	v_mfma_f32_16x16x32_bf16 v[46:49], v[50:53], v[38:41], v[46:49]
	s_waitcnt lgkmcnt(0)
	v_mfma_f32_16x16x32_bf16 v[26:29], v[58:61], v[38:41], v[26:29]
	ds_read_b128 v[38:41], v18 offset:34816
	s_waitcnt lgkmcnt(0)
	v_mfma_f32_16x16x32_bf16 v[74:77], v[22:25], v[38:41], v[74:77]
	v_mfma_f32_16x16x32_bf16 v[78:81], v[50:53], v[38:41], v[78:81]
	v_mfma_f32_16x16x32_bf16 v[82:85], v[54:57], v[38:41], v[82:85]
	v_mfma_f32_16x16x32_bf16 v[30:33], v[58:61], v[38:41], v[30:33]
	ds_read_b128 v[38:41], v18 offset:36864
	s_waitcnt lgkmcnt(0)
	v_mfma_f32_16x16x32_bf16 v[86:89], v[22:25], v[38:41], v[86:89]
	v_mfma_f32_16x16x32_bf16 v[90:93], v[50:53], v[38:41], v[90:93]
	v_mfma_f32_16x16x32_bf16 v[94:97], v[54:57], v[38:41], v[94:97]
	v_mfma_f32_16x16x32_bf16 v[102:105], v[58:61], v[38:41], v[42:45]
	ds_read_b128 v[38:41], v18 offset:38912
	s_waitcnt lgkmcnt(0)
	v_mfma_f32_16x16x32_bf16 v[116:119], v[58:61], v[38:41], v[14:17]
	s_nop 2
	ds_read_b128 v[14:17], v68 offset:32768
	v_mfma_f32_16x16x32_bf16 v[2:5], v[54:57], v[38:41], v[2:5]
	s_waitcnt lgkmcnt(0)
	v_mfma_f32_16x16x32_bf16 v[54:57], v[124:127], v[14:17], v[98:101]
	s_nop 2
	ds_read_b128 v[98:101], v20 offset:55296
	v_mfma_f32_16x16x32_bf16 v[10:13], v[50:53], v[38:41], v[10:13]
	v_mfma_f32_16x16x32_bf16 v[62:65], v[106:109], v[14:17], v[34:37]
	v_mfma_f32_16x16x32_bf16 v[58:61], v[120:123], v[14:17], v[46:49]
	s_waitcnt lgkmcnt(0)
	v_mfma_f32_16x16x32_bf16 v[50:53], v[98:101], v[14:17], v[26:29]
	ds_read_b128 v[14:17], v68 offset:34816
	v_mfma_f32_16x16x32_bf16 v[6:9], v[22:25], v[38:41], v[6:9]
	s_waitcnt lgkmcnt(0)
	v_mfma_f32_16x16x32_bf16 v[46:49], v[106:109], v[14:17], v[74:77]
	v_mfma_f32_16x16x32_bf16 v[42:45], v[120:123], v[14:17], v[78:81]
	s_nop 1
	v_lshl_or_b32 v75, v1, 6, s1
	s_movk_i32 s1, 0x240
	v_cmp_gt_i32_e32 vcc, s1, v75
	v_mfma_f32_16x16x32_bf16 v[38:41], v[124:127], v[14:17], v[82:85]
	v_mfma_f32_16x16x32_bf16 v[34:37], v[98:101], v[14:17], v[30:33]
	ds_read_b128 v[14:17], v68 offset:36864
	ds_read_b128 v[68:71], v68 offset:38912
	s_waitcnt lgkmcnt(1)
	v_mfma_f32_16x16x32_bf16 v[30:33], v[106:109], v[14:17], v[86:89]
	v_mfma_f32_16x16x32_bf16 v[26:29], v[120:123], v[14:17], v[90:93]
	v_mfma_f32_16x16x32_bf16 v[22:25], v[124:127], v[14:17], v[94:97]
	v_mfma_f32_16x16x32_bf16 v[18:21], v[98:101], v[14:17], v[102:105]
	s_waitcnt lgkmcnt(0)
	v_mfma_f32_16x16x32_bf16 v[14:17], v[106:109], v[68:71], v[6:9]
	v_mfma_f32_16x16x32_bf16 v[10:13], v[120:123], v[68:71], v[10:13]
	v_mfma_f32_16x16x32_bf16 v[6:9], v[124:127], v[68:71], v[2:5]
	v_mfma_f32_16x16x32_bf16 v[2:5], v[98:101], v[68:71], v[116:119]
	s_and_saveexec_b64 s[2:3], vcc
	s_xor_b64 s[48:49], exec, s[2:3]
	v_readlane_b32 s95, v254, 48
	s_mov_b32 s47, 0x38e38e39
	s_mov_b64 s[26:27], s[72:73]
	s_mov_b32 s28, s94
	s_cbranch_execz .LBB0_511
	v_lshl_add_u32 v1, v67, 6, s0
	s_movk_i32 s0, 0x17f
	v_cmp_lt_i32_e32 vcc, s0, v75
	v_lshlrev_b32_e32 v110, 4, v73
	v_or_b32_e32 v70, v1, v66
	s_and_saveexec_b64 s[0:1], vcc
	s_xor_b64 s[54:55], exec, s[0:1]
	s_cbranch_execz .LBB0_659
	v_and_b32_e32 v66, 64, v147
	v_xor_b32_e32 v1, 16, v147
	v_add_u32_e32 v66, 64, v66
	v_cmp_lt_i32_e32 vcc, v1, v66
	v_ashrrev_i32_e32 v71, 31, v70
	v_lshlrev_b32_e32 v77, 2, v73
	v_cndmask_b32_e32 v1, v147, v1, vcc
	v_lshlrev_b32_e32 v78, 2, v1
	v_xor_b32_e32 v1, 32, v147
	v_cmp_lt_i32_e32 vcc, v1, v66
	v_and_b32_e32 v79, 4, v77
	s_nop 0
	v_cndmask_b32_e32 v1, v147, v1, vcc
	v_cmp_gt_u32_e32 vcc, 2, v73
	v_lshl_add_u64 v[72:73], v[70:71], 2, s[60:61]
	global_load_dword v66, v[72:73], off
	v_lshlrev_b32_e32 v1, 2, v1
	s_waitcnt vmcnt(0)
	v_fmamk_f32 v66, v66, 0x3aaaaaab, v143
	v_cmp_gt_f32_e64 s[0:1], s53, v66
	v_mul_f32_e32 v67, 0x4b800000, v66
	s_nop 0
	v_cndmask_b32_e64 v66, v66, v67, s[0:1]
	v_rsq_f32_e32 v66, v66
	s_nop 0
	v_mul_f32_e32 v67, 0x45800000, v66
	v_cndmask_b32_e64 v76, v66, v67, s[0:1]
	v_mul_hi_i32 v66, v70, s47
	v_lshrrev_b32_e32 v67, 31, v66
	v_ashrrev_i32_e32 v66, 9, v66
	v_add_u32_e32 v82, v66, v67
	v_mul_i32_i24_e32 v66, 0x900, v82
	v_sub_u32_e32 v74, v70, v66
	v_pk_mul_f32 v[66:67], v[62:63], v[76:77] op_sel_hi:[1,0]
	v_pk_mul_f32 v[68:69], v[64:65], v[76:77] op_sel_hi:[1,0]
	v_pk_mul_f32 v[66:67], v[66:67], v[66:67]
	v_pk_mul_f32 v[68:69], v[68:69], v[68:69]
	v_add_f32_e32 v66, v66, v67
	v_pk_mul_f32 v[80:81], v[58:59], v[76:77] op_sel_hi:[1,0]
	v_add_f32_e32 v66, v68, v66
	v_pk_mul_f32 v[80:81], v[80:81], v[80:81]
	v_add_f32_e32 v66, v69, v66
	v_pk_mul_f32 v[84:85], v[60:61], v[76:77] op_sel_hi:[1,0]
	v_add_f32_e32 v66, v80, v66
	v_pk_mul_f32 v[84:85], v[84:85], v[84:85]
	v_add_f32_e32 v66, v81, v66
	v_add_f32_e32 v66, v84, v66
	v_add_f32_e32 v66, v85, v66
	ds_bpermute_b32 v67, v78, v66
	v_add_u32_e32 v71, 0xffffff00, v74
	v_lshrrev_b32_e32 v71, 3, v71
	v_cmp_lt_i32_e64 s[38:39], s33, v74
	s_waitcnt lgkmcnt(0)
	v_add_f32_e32 v66, v66, v67
	ds_bpermute_b32 v67, v1, v66
	s_waitcnt lgkmcnt(0)
	v_add_f32_e32 v66, v66, v67
	v_fmamk_f32 v66, v66, 0x3d000000, v143
	v_cmp_gt_f32_e64 s[0:1], s53, v66
	v_mul_f32_e32 v67, 0x4b800000, v66
	s_nop 0
	v_cndmask_b32_e64 v66, v66, v67, s[0:1]
	v_rsq_f32_e32 v66, v66
	s_nop 0
	v_mul_f32_e32 v67, 0x45800000, v66
	v_cndmask_b32_e64 v66, v66, v67, s[0:1]
	v_readlane_b32 s0, v250, 8
	v_readlane_b32 s1, v250, 9
	v_mul_f32_e32 v80, v76, v66
	v_mul_f32_e32 v62, v62, v80
	s_nop 2
	global_load_dwordx4 v[66:69], v110, s[0:1]
	s_mov_b32 s0, 0x1ffffff8
	v_and_or_b32 v71, v71, s0, v79
	v_lshlrev_b32_e32 v81, 3, v71
	s_waitcnt vmcnt(0)
	v_mul_f32_e32 v62, v66, v62
	ds_bpermute_b32 v66, v1, v62
	s_and_saveexec_b64 s[98:99], s[38:39]
	s_cbranch_execz .Lrope_pf_0
	global_load_dwordx4 v[200:203], v81, s[68:69]
	global_load_dwordx4 v[204:207], v81, s[68:69] offset:16
; DI unsigned pk_bf16(float lo, float hi) { f32x2 v = {lo, hi}; bf16v2 b = __builtin_convertvector(v, bf16v2); return __builtin_bit_cast(unsigned, b); }
;   DI void operator()(const f32x4 (&acc)[4][4], int r0, int c0, int fr, int fq) const {
;     ...
;         for (int hh = 0; hh < 2; ++hh) {
;           const int h = ((c0 - 384) >> 5) + hh;
;           float ss = 0.f;
; #pragma unroll
;           for (int nn = 0; nn < 2; ++nn)
; #pragma unroll
;             for (int j = 0; j < 4; ++j) { float v = acc[m][hh * 2 + nn][j] * rs; ss += v * v; }
;           ss += __shfl_xor(ss, 16); ss += __shfl_xor(ss, 32);
;           const float inv = rsqrtf(ss * (1.f / 32.f) + EPSF) * rs;
;           bf16_t* dst = Q + ((size_t)(b * 6 + h) * TB + s) * 96 + 64;
; #pragma unroll
;           for (int nn = 0; nn < 2; ++nn) {
;             const int d = nn * 16 + fq * 4; f32x4 g = *(const f32x4*)(gr + d);
;             float o[4];
; #pragma unroll
;             for (int j = 0; j < 4; ++j) {
;               float val = acc[m][hh * 2 + nn][j] * inv * g[j];
;               float partner = __shfl_xor(val, 32);
;               if (lat) {
;                 const float* rt = rope + ((nn == 0 ? (sp >> 6) : (sp & 63)) * 8 + ((fq * 4 + j) & 7)) * 2; const float cs = rt[0], sn = rt[1];
;                 val = fq < 2 ? val * cs - partner * sn : val * cs + partner * sn;
;               }
;               o[j] = val * QSCALE;
;             }
;             u32x2 v = {pk_bf16(o[0], o[1]), pk_bf16(o[2], o[3])};
;             *(u32x2*)(dst + d) = v;
;           }
.Lrope_pf_0:
	s_or_b64 exec, exec, s[98:99]
	s_and_saveexec_b64 s[0:1], s[38:39]
	s_cbranch_execz .LBB0_532
	s_waitcnt vmcnt(0) lgkmcnt(0)
	v_mul_f32_e32 v66, v201, v66
	v_cndmask_b32_e64 v66, v66, -v66, vcc
	v_fmac_f32_e32 v66, v62, v200
	v_mov_b32_e32 v62, v66
.LBB0_532:
	s_or_b64 exec, exec, s[0:1]
	v_mul_f32_e32 v63, v63, v80
	v_mul_f32_e32 v63, v67, v63
	s_waitcnt lgkmcnt(0)
	ds_bpermute_b32 v66, v1, v63
	s_and_saveexec_b64 s[0:1], s[38:39]
	s_cbranch_execz .LBB0_534
	s_waitcnt vmcnt(0) lgkmcnt(0)
	v_mul_f32_e32 v66, v203, v66
	v_cndmask_b32_e64 v66, v66, -v66, vcc
	v_fmac_f32_e32 v66, v63, v202
	v_mov_b32_e32 v63, v66
.LBB0_534:
	s_or_b64 exec, exec, s[0:1]
	v_mul_f32_e32 v64, v64, v80
	v_mul_f32_e32 v68, v68, v64
	ds_bpermute_b32 v64, v1, v68
	s_and_saveexec_b64 s[0:1], s[38:39]
	s_cbranch_execz .LBB0_536
	s_waitcnt lgkmcnt(1)
	s_waitcnt vmcnt(0) lgkmcnt(0)
	v_mul_f32_e32 v64, v205, v64
	v_cndmask_b32_e64 v64, v64, -v64, vcc
	v_fmac_f32_e32 v64, v68, v204
	v_mov_b32_e32 v68, v64
.LBB0_536:
	s_or_b64 exec, exec, s[0:1]
	s_waitcnt lgkmcnt(0)
	v_mul_f32_e32 v64, v65, v80
	v_mul_f32_e32 v64, v69, v64
	ds_bpermute_b32 v65, v1, v64
	s_and_saveexec_b64 s[0:1], s[38:39]
	s_cbranch_execz .LBB0_538
	s_waitcnt vmcnt(0) lgkmcnt(0)
	v_mul_f32_e32 v65, v207, v65
	v_cndmask_b32_e64 v65, v65, -v65, vcc
	v_fmac_f32_e32 v65, v64, v206
	v_mov_b32_e32 v64, v65
.LBB0_538:
	s_or_b64 exec, exec, s[0:1]
	v_readlane_b32 s0, v250, 8
	v_mul_f32_e32 v83, 0x3e16c740, v62
	v_add_u32_e32 v62, 0xfffffe80, v75
	v_readlane_b32 s1, v250, 9
	v_lshrrev_b32_e32 v71, 5, v62
	v_mad_i32_i24 v82, v82, 6, v71
	v_lshl_add_u64 v[66:67], s[0:1], 0, v[110:111]
	v_ashrrev_i32_e32 v75, 31, v74
	s_movk_i32 s0, 0x900
	v_mul_f32_e32 v84, 0x3e16c740, v63
	v_mad_i64_i32 v[62:63], s[0:1], v82, s0, v[74:75]
	v_readlane_b32 s0, v253, 36
	v_readlane_b32 s2, v253, 38
	v_readlane_b32 s12, v253, 48
	v_readlane_b32 s13, v253, 49
	s_waitcnt lgkmcnt(0)
	v_mul_f32_e32 v65, 0x3e16c740, v68
	v_readlane_b32 s1, v253, 37
	v_mov_b64_e32 v[68:69], s[12:13]
	s_movk_i32 s2, 0xc0
	v_mad_u64_u32 v[68:69], s[0:1], v62, s2, v[68:69]
	v_mad_i32_i24 v69, v63, s2, v69
	v_mul_f32_e32 v63, 0x3e16c740, v64
	v_lshlrev_b32_e32 v110, 1, v77
	v_cvt_pk_bf16_f32 v62, v83, v84
	v_cvt_pk_bf16_f32 v63, v65, v63
	v_lshl_add_u64 v[68:69], v[68:69], 0, v[110:111]
	global_store_dwordx2 v[68:69], v[62:63], off offset:128
	global_load_dwordx4 v[62:65], v[66:67], off offset:64
	v_mul_f32_e32 v58, v58, v80
	s_movk_i32 s0, 0x78
	v_readlane_b32 s3, v253, 39
	v_readlane_b32 s4, v253, 40
	v_readlane_b32 s5, v253, 41
	v_readlane_b32 s6, v253, 42
	v_readlane_b32 s7, v253, 43
	v_readlane_b32 s8, v253, 44
	v_readlane_b32 s9, v253, 45
	v_readlane_b32 s10, v253, 46
	v_readlane_b32 s11, v253, 47
	v_readlane_b32 s14, v253, 50
	v_readlane_b32 s15, v253, 51
	s_waitcnt vmcnt(0)
	v_mul_f32_e32 v58, v58, v62
	ds_bpermute_b32 v77, v1, v58
	v_lshlrev_b32_e32 v62, 3, v74
	v_and_or_b32 v62, v62, s0, v79
	v_lshlrev_b32_e32 v62, 3, v62
	s_and_saveexec_b64 s[98:99], s[38:39]
	s_cbranch_execz .Lrope_pf_1
	global_load_dwordx4 v[200:203], v62, s[68:69]
	global_load_dwordx4 v[204:207], v62, s[68:69] offset:16
.Lrope_pf_1:
	s_or_b64 exec, exec, s[98:99]
	s_and_saveexec_b64 s[0:1], s[38:39]
	s_cbranch_execz .LBB0_540
	s_waitcnt vmcnt(0) lgkmcnt(0)
	v_mul_f32_e32 v77, v201, v77
	v_cndmask_b32_e64 v77, v77, -v77, vcc
	v_fmac_f32_e32 v77, v58, v200
	v_mov_b32_e32 v58, v77
.LBB0_540:
	s_or_b64 exec, exec, s[0:1]
	v_mul_f32_e32 v59, v59, v80
	v_mul_f32_e32 v59, v59, v63
	ds_bpermute_b32 v63, v1, v59
	s_and_saveexec_b64 s[0:1], s[38:39]
	s_cbranch_execz .LBB0_542
	s_waitcnt vmcnt(0) lgkmcnt(0)
	v_mul_f32_e32 v63, v203, v63
	v_cndmask_b32_e64 v63, v63, -v63, vcc
	v_fmac_f32_e32 v63, v59, v202
	v_mov_b32_e32 v59, v63
.LBB0_542:
	s_or_b64 exec, exec, s[0:1]
	v_mul_f32_e32 v60, v60, v80
	v_mul_f32_e32 v60, v60, v64
	s_waitcnt lgkmcnt(0)
	ds_bpermute_b32 v63, v1, v60
	s_and_saveexec_b64 s[0:1], s[38:39]
	s_cbranch_execz .LBB0_544
	s_waitcnt vmcnt(0) lgkmcnt(0)
	v_mul_f32_e32 v63, v205, v63
	v_cndmask_b32_e64 v63, v63, -v63, vcc
	v_fmac_f32_e32 v63, v60, v204
	v_mov_b32_e32 v60, v63
.LBB0_544:
	s_or_b64 exec, exec, s[0:1]
	v_mul_f32_e32 v61, v61, v80
	v_mul_f32_e32 v61, v61, v65
	s_waitcnt lgkmcnt(0)
	ds_bpermute_b32 v63, v1, v61
	s_and_saveexec_b64 s[0:1], s[38:39]
	s_cbranch_execz .LBB0_546
	s_waitcnt vmcnt(0) lgkmcnt(0)
	v_mul_f32_e32 v63, v207, v63
	v_cndmask_b32_e64 v63, v63, -v63, vcc
	v_fmac_f32_e32 v63, v61, v206
	v_mov_b32_e32 v61, v63
.LBB0_546:
	s_or_b64 exec, exec, s[0:1]
	v_mul_f32_e32 v60, 0x3e16c740, v60
	v_mul_f32_e32 v58, 0x3e16c740, v58
	v_mul_f32_e32 v59, 0x3e16c740, v59
	v_mul_f32_e32 v61, 0x3e16c740, v61
	v_mov_b32_e32 v77, v76
	v_cvt_pk_bf16_f32 v58, v58, v59
	v_cvt_pk_bf16_f32 v59, v60, v61
	global_store_dwordx2 v[68:69], v[58:59], off offset:160
	v_pk_mul_f32 v[58:59], v[54:55], v[76:77]
	v_pk_mul_f32 v[60:61], v[56:57], v[76:77]
	v_pk_mul_f32 v[58:59], v[58:59], v[58:59]
	v_pk_mul_f32 v[60:61], v[60:61], v[60:61]
	v_add_f32_e32 v58, v58, v59
	v_pk_mul_f32 v[64:65], v[50:51], v[76:77]
	v_add_f32_e32 v58, v60, v58
	v_pk_mul_f32 v[64:65], v[64:65], v[64:65]
	v_add_f32_e32 v58, v61, v58
	v_pk_mul_f32 v[68:69], v[52:53], v[76:77]
	v_add_f32_e32 v58, v64, v58
	v_pk_mul_f32 v[68:69], v[68:69], v[68:69]
	v_add_f32_e32 v58, v65, v58
	v_add_f32_e32 v58, v68, v58
	v_add_f32_e32 v58, v69, v58
	ds_bpermute_b32 v59, v78, v58
	s_waitcnt lgkmcnt(0)
	v_add_f32_e32 v58, v58, v59
	ds_bpermute_b32 v59, v1, v58
	s_waitcnt lgkmcnt(0)
	v_add_f32_e32 v58, v58, v59
	v_fmamk_f32 v58, v58, 0x3d000000, v143
	v_cmp_gt_f32_e64 s[0:1], s53, v58
	v_mul_f32_e32 v59, 0x4b800000, v58
	s_nop 0
	v_cndmask_b32_e64 v58, v58, v59, s[0:1]
	v_rsq_f32_e32 v58, v58
	s_nop 0
	v_mul_f32_e32 v59, 0x45800000, v58
	v_cndmask_b32_e64 v58, v58, v59, s[0:1]
	v_mul_f32_e32 v63, v76, v58
	global_load_dwordx4 v[58:61], v[66:67], off
	v_mul_f32_e32 v54, v54, v63
	s_waitcnt vmcnt(0)
	v_mul_f32_e32 v54, v58, v54
	ds_bpermute_b32 v58, v1, v54
	s_and_saveexec_b64 s[98:99], s[38:39]
	s_cbranch_execz .Lrope_pf_2
	global_load_dwordx4 v[200:203], v81, s[68:69]
	global_load_dwordx4 v[204:207], v81, s[68:69] offset:16
; DI unsigned pk_bf16(float lo, float hi) { f32x2 v = {lo, hi}; bf16v2 b = __builtin_convertvector(v, bf16v2); return __builtin_bit_cast(unsigned, b); }
;   DI void operator()(const f32x4 (&acc)[4][4], int r0, int c0, int fr, int fq) const {
;     ...
;       for (int m = 0; m < 4; ++m) {
;         const int row = r0 + m * 16 + fr; const float rs = rsqrtf(rstd[row] * (1.f / 768.f) + EPSF);
;         const int b = row / TB, s = row % TB; const bool lat = s >= NCTX; const int sp = s - NCTX;
; #pragma unroll
;         for (int hh = 0; hh < 2; ++hh) {
;           const int h = ((c0 - 384) >> 5) + hh;
;           float ss = 0.f;
; #pragma unroll
;           for (int nn = 0; nn < 2; ++nn)
; #pragma unroll
;             for (int j = 0; j < 4; ++j) { float v = acc[m][hh * 2 + nn][j] * rs; ss += v * v; }
;           ss += __shfl_xor(ss, 16); ss += __shfl_xor(ss, 32);
;           const float inv = rsqrtf(ss * (1.f / 32.f) + EPSF) * rs;
;           bf16_t* dst = Q + ((size_t)(b * 6 + h) * TB + s) * 96 + 64;
; #pragma unroll
;           for (int nn = 0; nn < 2; ++nn) {
;             const int d = nn * 16 + fq * 4; f32x4 g = *(const f32x4*)(gr + d);
;             float o[4];
; #pragma unroll
;             for (int j = 0; j < 4; ++j) {
;               float val = acc[m][hh * 2 + nn][j] * inv * g[j];
;               float partner = __shfl_xor(val, 32);
;               if (lat) {
;                 const float* rt = rope + ((nn == 0 ? (sp >> 6) : (sp & 63)) * 8 + ((fq * 4 + j) & 7)) * 2; const float cs = rt[0], sn = rt[1];
;                 val = fq < 2 ? val * cs - partner * sn : val * cs + partner * sn;
;               }
;               o[j] = val * QSCALE;
;             }
;             u32x2 v = {pk_bf16(o[0], o[1]), pk_bf16(o[2], o[3])};
;             *(u32x2*)(dst + d) = v;
;           }
.Lrope_pf_2:
	s_or_b64 exec, exec, s[98:99]
	s_and_saveexec_b64 s[0:1], s[38:39]
	s_cbranch_execz .LBB0_548
	s_waitcnt vmcnt(0) lgkmcnt(0)
	v_mul_f32_e32 v58, v201, v58
	v_cndmask_b32_e64 v58, v58, -v58, vcc
	v_fmac_f32_e32 v58, v54, v200
	v_mov_b32_e32 v54, v58
.LBB0_548:
	s_or_b64 exec, exec, s[0:1]
	v_mul_f32_e32 v55, v55, v63
	v_mul_f32_e32 v55, v59, v55
	s_waitcnt lgkmcnt(0)
	ds_bpermute_b32 v58, v1, v55
	s_and_saveexec_b64 s[0:1], s[38:39]
	s_cbranch_execz .LBB0_550
	s_waitcnt vmcnt(0) lgkmcnt(0)
	v_mul_f32_e32 v58, v203, v58
	v_cndmask_b32_e64 v58, v58, -v58, vcc
	v_fmac_f32_e32 v58, v55, v202
	v_mov_b32_e32 v55, v58
.LBB0_550:
	s_or_b64 exec, exec, s[0:1]
	v_mul_f32_e32 v56, v56, v63
	s_waitcnt lgkmcnt(0)
	v_mul_f32_e32 v58, v60, v56
	ds_bpermute_b32 v56, v1, v58
	s_and_saveexec_b64 s[0:1], s[38:39]
	s_cbranch_execz .LBB0_552
	s_waitcnt vmcnt(0) lgkmcnt(0)
	v_mul_f32_e32 v56, v205, v56
	v_cndmask_b32_e64 v56, v56, -v56, vcc
	v_fmac_f32_e32 v56, v58, v204
	v_mov_b32_e32 v58, v56
.LBB0_552:
	s_or_b64 exec, exec, s[0:1]
	s_waitcnt lgkmcnt(0)
	v_mul_f32_e32 v56, v57, v63
	v_mul_f32_e32 v56, v61, v56
	ds_bpermute_b32 v57, v1, v56
	s_and_saveexec_b64 s[0:1], s[38:39]
	s_cbranch_execz .LBB0_554
	s_waitcnt vmcnt(0) lgkmcnt(0)
	v_mul_f32_e32 v57, v207, v57
	v_cndmask_b32_e64 v57, v57, -v57, vcc
	v_fmac_f32_e32 v57, v56, v206
	v_mov_b32_e32 v56, v57
.LBB0_554:
	s_or_b64 exec, exec, s[0:1]
	v_mul_f32_e32 v60, 0x3e16c740, v54
	v_or_b32_e32 v54, 1, v82
	s_movk_i32 s0, 0x900
	v_mul_f32_e32 v61, 0x3e16c740, v55
	v_mad_i64_i32 v[54:55], s[0:1], v54, s0, v[74:75]
	v_readlane_b32 s0, v253, 36
	v_readlane_b32 s2, v253, 38
	v_readlane_b32 s12, v253, 48
	v_readlane_b32 s13, v253, 49
	s_waitcnt lgkmcnt(0)
	v_mul_f32_e32 v57, 0x3e16c740, v58
	v_readlane_b32 s1, v253, 37
	v_mov_b64_e32 v[58:59], s[12:13]
	s_movk_i32 s2, 0xc0
	v_mad_u64_u32 v[58:59], s[0:1], v54, s2, v[58:59]
	v_mad_i32_i24 v59, v55, s2, v59
	v_mul_f32_e32 v55, 0x3e16c740, v56
	v_cvt_pk_bf16_f32 v54, v60, v61
	v_cvt_pk_bf16_f32 v55, v57, v55
	v_lshl_add_u64 v[58:59], v[58:59], 0, v[110:111]
	global_store_dwordx2 v[58:59], v[54:55], off offset:128
	global_load_dwordx4 v[54:57], v[66:67], off offset:64
	v_mul_f32_e32 v50, v50, v63
	v_readlane_b32 s3, v253, 39
	v_readlane_b32 s4, v253, 40
	v_readlane_b32 s5, v253, 41
	v_readlane_b32 s6, v253, 42
	v_readlane_b32 s7, v253, 43
	v_readlane_b32 s8, v253, 44
	v_readlane_b32 s9, v253, 45
	v_readlane_b32 s10, v253, 46
	v_readlane_b32 s11, v253, 47
	v_readlane_b32 s14, v253, 50
	v_readlane_b32 s15, v253, 51
	s_waitcnt vmcnt(0)
	v_mul_f32_e32 v50, v50, v54
	ds_bpermute_b32 v54, v1, v50
	s_and_saveexec_b64 s[98:99], s[38:39]
	s_cbranch_execz .Lrope_pf_3
	global_load_dwordx4 v[200:203], v62, s[68:69]
	global_load_dwordx4 v[204:207], v62, s[68:69] offset:16
.Lrope_pf_3:
	s_or_b64 exec, exec, s[98:99]
	s_and_saveexec_b64 s[0:1], s[38:39]
	s_cbranch_execz .LBB0_556
	s_waitcnt vmcnt(0) lgkmcnt(0)
	v_mul_f32_e32 v54, v201, v54
	v_cndmask_b32_e64 v54, v54, -v54, vcc
	v_fmac_f32_e32 v54, v50, v200
	v_mov_b32_e32 v50, v54
.LBB0_556:
	s_or_b64 exec, exec, s[0:1]
	v_mul_f32_e32 v51, v51, v63
	v_mul_f32_e32 v51, v51, v55
	s_waitcnt lgkmcnt(0)
	ds_bpermute_b32 v54, v1, v51
	s_and_saveexec_b64 s[0:1], s[38:39]
	s_cbranch_execz .LBB0_558
	s_waitcnt vmcnt(0) lgkmcnt(0)
	v_mul_f32_e32 v54, v203, v54
	v_cndmask_b32_e64 v54, v54, -v54, vcc
	v_fmac_f32_e32 v54, v51, v202
	v_mov_b32_e32 v51, v54
.LBB0_558:
	s_or_b64 exec, exec, s[0:1]
	v_mul_f32_e32 v52, v52, v63
	v_mul_f32_e32 v52, v52, v56
	s_waitcnt lgkmcnt(0)
	ds_bpermute_b32 v54, v1, v52
	s_and_saveexec_b64 s[0:1], s[38:39]
	s_cbranch_execz .LBB0_560
	s_waitcnt vmcnt(0) lgkmcnt(0)
	v_mul_f32_e32 v54, v205, v54
	v_cndmask_b32_e64 v54, v54, -v54, vcc
	v_fmac_f32_e32 v54, v52, v204
	v_mov_b32_e32 v52, v54
.LBB0_560:
	s_or_b64 exec, exec, s[0:1]
	v_mul_f32_e32 v53, v53, v63
	v_mul_f32_e32 v53, v53, v57
	s_waitcnt lgkmcnt(0)
	ds_bpermute_b32 v54, v1, v53
	s_and_saveexec_b64 s[0:1], s[38:39]
	s_cbranch_execz .LBB0_562
	s_waitcnt vmcnt(0) lgkmcnt(0)
	v_mul_f32_e32 v54, v207, v54
	v_cndmask_b32_e64 v54, v54, -v54, vcc
	v_fmac_f32_e32 v54, v53, v206
	v_mov_b32_e32 v53, v54
.LBB0_562:
	s_or_b64 exec, exec, s[0:1]
	v_mul_f32_e32 v52, 0x3e16c740, v52
	v_mul_f32_e32 v50, 0x3e16c740, v50
	v_mul_f32_e32 v51, 0x3e16c740, v51
	v_mul_f32_e32 v53, 0x3e16c740, v53
	v_cvt_pk_bf16_f32 v50, v50, v51
	v_cvt_pk_bf16_f32 v51, v52, v53
	global_store_dwordx2 v[58:59], v[50:51], off offset:160
	global_load_dword v51, v[72:73], off offset:64
	v_or_b32_e32 v50, 16, v70
	s_waitcnt vmcnt(0)
	v_fmamk_f32 v51, v51, 0x3aaaaaab, v143
	v_cmp_gt_f32_e64 s[0:1], s53, v51
	v_mul_f32_e32 v52, 0x4b800000, v51
	s_nop 0
	v_cndmask_b32_e64 v51, v51, v52, s[0:1]
	v_rsq_f32_e32 v51, v51
	s_nop 0
	v_mul_f32_e32 v52, 0x45800000, v51
	v_cndmask_b32_e64 v56, v51, v52, s[0:1]
	v_mul_hi_i32 v51, v50, s47
	v_lshrrev_b32_e32 v52, 31, v51
	v_ashrrev_i32_e32 v51, 9, v51
	v_add_u32_e32 v55, v51, v52
	v_mul_i32_i24_e32 v51, 0x900, v55
	s_waitcnt lgkmcnt(0)
	v_sub_u32_e32 v54, v50, v51
	v_pk_mul_f32 v[50:51], v[46:47], v[56:57] op_sel_hi:[1,0]
	v_pk_mul_f32 v[52:53], v[48:49], v[56:57] op_sel_hi:[1,0]
	v_pk_mul_f32 v[50:51], v[50:51], v[50:51]
	v_pk_mul_f32 v[52:53], v[52:53], v[52:53]
	v_add_f32_e32 v50, v50, v51
	v_pk_mul_f32 v[58:59], v[42:43], v[56:57] op_sel_hi:[1,0]
	v_add_f32_e32 v50, v52, v50
	v_pk_mul_f32 v[58:59], v[58:59], v[58:59]
	v_add_f32_e32 v50, v53, v50
	v_pk_mul_f32 v[60:61], v[44:45], v[56:57] op_sel_hi:[1,0]
	v_add_f32_e32 v50, v58, v50
	v_pk_mul_f32 v[60:61], v[60:61], v[60:61]
	v_add_f32_e32 v50, v59, v50
	v_add_f32_e32 v50, v60, v50
	v_add_f32_e32 v50, v61, v50
	ds_bpermute_b32 v51, v78, v50
	v_add_u32_e32 v62, 0xffffff00, v54
	v_lshrrev_b32_e32 v58, 3, v62
	v_cmp_lt_i32_e64 s[38:39], s33, v54
	s_waitcnt lgkmcnt(0)
	v_add_f32_e32 v50, v50, v51
	ds_bpermute_b32 v51, v1, v50
	s_waitcnt lgkmcnt(0)
	v_add_f32_e32 v50, v50, v51
	v_fmamk_f32 v50, v50, 0x3d000000, v143
	v_cmp_gt_f32_e64 s[0:1], s53, v50
	v_mul_f32_e32 v51, 0x4b800000, v50
	s_nop 0
	v_cndmask_b32_e64 v50, v50, v51, s[0:1]
	v_rsq_f32_e32 v50, v50
	s_nop 0
	v_mul_f32_e32 v51, 0x45800000, v50
	v_cndmask_b32_e64 v50, v50, v51, s[0:1]
	v_mul_f32_e32 v57, v56, v50
	global_load_dwordx4 v[50:53], v[66:67], off
	v_mul_f32_e32 v46, v46, v57
	s_mov_b32 s0, 0x1ffffff8
	v_and_or_b32 v58, v58, s0, v79
	v_lshlrev_b32_e32 v58, 3, v58
	s_waitcnt vmcnt(0)
	v_mul_f32_e32 v46, v50, v46
	ds_bpermute_b32 v50, v1, v46
	s_and_saveexec_b64 s[98:99], s[38:39]
	s_cbranch_execz .Lrope_pf_4
	global_load_dwordx4 v[200:203], v58, s[68:69]
	global_load_dwordx4 v[204:207], v58, s[68:69] offset:16
; DI unsigned pk_bf16(float lo, float hi) { f32x2 v = {lo, hi}; bf16v2 b = __builtin_convertvector(v, bf16v2); return __builtin_bit_cast(unsigned, b); }
;   DI void operator()(const f32x4 (&acc)[4][4], int r0, int c0, int fr, int fq) const {
;     ...
;       for (int m = 0; m < 4; ++m) {
;         const int row = r0 + m * 16 + fr; const float rs = rsqrtf(rstd[row] * (1.f / 768.f) + EPSF);
;         const int b = row / TB, s = row % TB; const bool lat = s >= NCTX; const int sp = s - NCTX;
; #pragma unroll
;         for (int hh = 0; hh < 2; ++hh) {
;           const int h = ((c0 - 384) >> 5) + hh;
;           float ss = 0.f;
; #pragma unroll
;           for (int nn = 0; nn < 2; ++nn)
; #pragma unroll
;             for (int j = 0; j < 4; ++j) { float v = acc[m][hh * 2 + nn][j] * rs; ss += v * v; }
;           ss += __shfl_xor(ss, 16); ss += __shfl_xor(ss, 32);
;           const float inv = rsqrtf(ss * (1.f / 32.f) + EPSF) * rs;
;           bf16_t* dst = Q + ((size_t)(b * 6 + h) * TB + s) * 96 + 64;
; #pragma unroll
;           for (int nn = 0; nn < 2; ++nn) {
;             const int d = nn * 16 + fq * 4; f32x4 g = *(const f32x4*)(gr + d);
;             float o[4];
; #pragma unroll
;             for (int j = 0; j < 4; ++j) {
;               float val = acc[m][hh * 2 + nn][j] * inv * g[j];
;               float partner = __shfl_xor(val, 32);
;               if (lat) {
;                 const float* rt = rope + ((nn == 0 ? (sp >> 6) : (sp & 63)) * 8 + ((fq * 4 + j) & 7)) * 2; const float cs = rt[0], sn = rt[1];
;                 val = fq < 2 ? val * cs - partner * sn : val * cs + partner * sn;
;               }
;               o[j] = val * QSCALE;
;             }
;             u32x2 v = {pk_bf16(o[0], o[1]), pk_bf16(o[2], o[3])};
;             *(u32x2*)(dst + d) = v;
;           }
.Lrope_pf_4:
	s_or_b64 exec, exec, s[98:99]
	s_and_saveexec_b64 s[0:1], s[38:39]
	s_cbranch_execz .LBB0_564
	s_waitcnt vmcnt(0) lgkmcnt(0)
	v_mul_f32_e32 v50, v201, v50
	v_cndmask_b32_e64 v50, v50, -v50, vcc
	v_fmac_f32_e32 v50, v46, v200
	v_mov_b32_e32 v46, v50
.LBB0_564:
	s_or_b64 exec, exec, s[0:1]
	v_mul_f32_e32 v47, v47, v57
	v_mul_f32_e32 v47, v51, v47
	s_waitcnt lgkmcnt(0)
	ds_bpermute_b32 v50, v1, v47
	s_and_saveexec_b64 s[0:1], s[38:39]
	s_cbranch_execz .LBB0_566
	s_waitcnt vmcnt(0) lgkmcnt(0)
	v_mul_f32_e32 v50, v203, v50
	v_cndmask_b32_e64 v50, v50, -v50, vcc
	v_fmac_f32_e32 v50, v47, v202
	v_mov_b32_e32 v47, v50
.LBB0_566:
	s_or_b64 exec, exec, s[0:1]
	v_mul_f32_e32 v48, v48, v57
	s_waitcnt lgkmcnt(0)
	v_mul_f32_e32 v50, v52, v48
	ds_bpermute_b32 v48, v1, v50
	s_and_saveexec_b64 s[0:1], s[38:39]
	s_cbranch_execz .LBB0_568
	s_waitcnt vmcnt(0) lgkmcnt(0)
	v_mul_f32_e32 v48, v205, v48
	v_cndmask_b32_e64 v48, v48, -v48, vcc
	v_fmac_f32_e32 v48, v50, v204
	v_mov_b32_e32 v50, v48
.LBB0_568:
	s_or_b64 exec, exec, s[0:1]
	s_waitcnt lgkmcnt(0)
	v_mul_f32_e32 v48, v49, v57
	v_mul_f32_e32 v48, v53, v48
	ds_bpermute_b32 v49, v1, v48
	s_and_saveexec_b64 s[0:1], s[38:39]
	s_cbranch_execz .LBB0_570
	s_waitcnt vmcnt(0) lgkmcnt(0)
	v_mul_f32_e32 v49, v207, v49
	v_cndmask_b32_e64 v49, v49, -v49, vcc
	v_fmac_f32_e32 v49, v48, v206
	v_mov_b32_e32 v48, v49
.LBB0_570:
	s_or_b64 exec, exec, s[0:1]
	v_mad_i32_i24 v52, v55, 6, v71
	v_ashrrev_i32_e32 v55, 31, v54
	s_movk_i32 s0, 0x900
	v_mul_f32_e32 v53, 0x3e16c740, v46
	v_mul_f32_e32 v59, 0x3e16c740, v47
	v_mad_i64_i32 v[46:47], s[0:1], v52, s0, v[54:55]
	v_readlane_b32 s0, v253, 36
	v_readlane_b32 s2, v253, 38
	v_readlane_b32 s12, v253, 48
	v_readlane_b32 s13, v253, 49
	s_waitcnt lgkmcnt(0)
	v_mul_f32_e32 v49, 0x3e16c740, v50
	v_readlane_b32 s1, v253, 37
	v_mov_b64_e32 v[50:51], s[12:13]
	s_movk_i32 s2, 0xc0
	v_mad_u64_u32 v[50:51], s[0:1], v46, s2, v[50:51]
	v_mad_i32_i24 v51, v47, s2, v51
	v_mul_f32_e32 v47, 0x3e16c740, v48
	v_cvt_pk_bf16_f32 v46, v53, v59
	v_cvt_pk_bf16_f32 v47, v49, v47
	v_lshl_add_u64 v[50:51], v[50:51], 0, v[110:111]
	global_store_dwordx2 v[50:51], v[46:47], off offset:128
	global_load_dwordx4 v[46:49], v[66:67], off offset:64
	v_mul_f32_e32 v42, v42, v57
	s_movk_i32 s0, 0x1f8
	v_readlane_b32 s3, v253, 39
	v_readlane_b32 s4, v253, 40
	v_readlane_b32 s5, v253, 41
	v_readlane_b32 s6, v253, 42
	v_readlane_b32 s7, v253, 43
	v_readlane_b32 s8, v253, 44
	v_readlane_b32 s9, v253, 45
	v_readlane_b32 s10, v253, 46
	v_readlane_b32 s11, v253, 47
	v_readlane_b32 s14, v253, 50
	v_readlane_b32 s15, v253, 51
	s_waitcnt vmcnt(0)
	v_mul_f32_e32 v42, v42, v46
	ds_bpermute_b32 v53, v1, v42
	v_lshlrev_b32_e32 v46, 3, v54
	v_and_or_b32 v46, v46, s0, v79
	v_lshlrev_b32_e32 v46, 3, v46
	s_and_saveexec_b64 s[98:99], s[38:39]
	s_cbranch_execz .Lrope_pf_5
	global_load_dwordx4 v[200:203], v46, s[68:69]
	global_load_dwordx4 v[204:207], v46, s[68:69] offset:16
.Lrope_pf_5:
	s_or_b64 exec, exec, s[98:99]
	s_and_saveexec_b64 s[0:1], s[38:39]
	s_cbranch_execz .LBB0_572
	s_waitcnt vmcnt(0) lgkmcnt(0)
	v_mul_f32_e32 v53, v201, v53
	v_cndmask_b32_e64 v53, v53, -v53, vcc
	v_fmac_f32_e32 v53, v42, v200
	v_mov_b32_e32 v42, v53
.LBB0_572:
	s_or_b64 exec, exec, s[0:1]
	v_mul_f32_e32 v43, v43, v57
	v_mul_f32_e32 v43, v43, v47
	ds_bpermute_b32 v47, v1, v43
	s_and_saveexec_b64 s[0:1], s[38:39]
	s_cbranch_execz .LBB0_574
	s_waitcnt vmcnt(0) lgkmcnt(0)
	v_mul_f32_e32 v47, v203, v47
	v_cndmask_b32_e64 v47, v47, -v47, vcc
	v_fmac_f32_e32 v47, v43, v202
	v_mov_b32_e32 v43, v47
.LBB0_574:
	s_or_b64 exec, exec, s[0:1]
	v_mul_f32_e32 v44, v44, v57
	v_mul_f32_e32 v44, v44, v48
	s_waitcnt lgkmcnt(0)
	ds_bpermute_b32 v47, v1, v44
	s_and_saveexec_b64 s[0:1], s[38:39]
	s_cbranch_execz .LBB0_576
	s_waitcnt vmcnt(0) lgkmcnt(0)
	v_mul_f32_e32 v47, v205, v47
	v_cndmask_b32_e64 v47, v47, -v47, vcc
	v_fmac_f32_e32 v47, v44, v204
	v_mov_b32_e32 v44, v47
.LBB0_576:
	s_or_b64 exec, exec, s[0:1]
	v_mul_f32_e32 v45, v45, v57
	v_mul_f32_e32 v45, v45, v49
	s_waitcnt lgkmcnt(0)
	ds_bpermute_b32 v47, v1, v45
	s_and_saveexec_b64 s[0:1], s[38:39]
	s_cbranch_execz .LBB0_578
	s_waitcnt vmcnt(0) lgkmcnt(0)
	v_mul_f32_e32 v47, v207, v47
	v_cndmask_b32_e64 v47, v47, -v47, vcc
	v_fmac_f32_e32 v47, v45, v206
	v_mov_b32_e32 v45, v47
.LBB0_578:
	s_or_b64 exec, exec, s[0:1]
	v_mul_f32_e32 v44, 0x3e16c740, v44
	v_mul_f32_e32 v42, 0x3e16c740, v42
	v_mul_f32_e32 v43, 0x3e16c740, v43
	v_mul_f32_e32 v45, 0x3e16c740, v45
	v_mov_b32_e32 v57, v56
	v_cvt_pk_bf16_f32 v42, v42, v43
	v_cvt_pk_bf16_f32 v43, v44, v45
	global_store_dwordx2 v[50:51], v[42:43], off offset:160
	v_pk_mul_f32 v[42:43], v[38:39], v[56:57]
	v_pk_mul_f32 v[44:45], v[40:41], v[56:57]
	v_pk_mul_f32 v[42:43], v[42:43], v[42:43]
	v_pk_mul_f32 v[44:45], v[44:45], v[44:45]
	v_add_f32_e32 v42, v42, v43
	v_pk_mul_f32 v[48:49], v[34:35], v[56:57]
	v_add_f32_e32 v42, v44, v42
	v_pk_mul_f32 v[48:49], v[48:49], v[48:49]
	v_add_f32_e32 v42, v45, v42
	v_pk_mul_f32 v[50:51], v[36:37], v[56:57]
	v_add_f32_e32 v42, v48, v42
	v_pk_mul_f32 v[50:51], v[50:51], v[50:51]
	v_add_f32_e32 v42, v49, v42
	v_add_f32_e32 v42, v50, v42
	v_add_f32_e32 v42, v51, v42
	ds_bpermute_b32 v43, v78, v42
	s_waitcnt lgkmcnt(0)
	v_add_f32_e32 v42, v42, v43
	ds_bpermute_b32 v43, v1, v42
	s_waitcnt lgkmcnt(0)
	v_add_f32_e32 v42, v42, v43
	v_fmamk_f32 v42, v42, 0x3d000000, v143
	v_cmp_gt_f32_e64 s[0:1], s53, v42
	v_mul_f32_e32 v43, 0x4b800000, v42
	s_nop 0
	v_cndmask_b32_e64 v42, v42, v43, s[0:1]
	v_rsq_f32_e32 v42, v42
	s_nop 0
	v_mul_f32_e32 v43, 0x45800000, v42
	v_cndmask_b32_e64 v42, v42, v43, s[0:1]
	v_mul_f32_e32 v47, v56, v42
	global_load_dwordx4 v[42:45], v[66:67], off
	v_mul_f32_e32 v38, v38, v47
	s_waitcnt vmcnt(0)
	v_mul_f32_e32 v38, v42, v38
	ds_bpermute_b32 v42, v1, v38
	s_and_saveexec_b64 s[98:99], s[38:39]
	s_cbranch_execz .Lrope_pf_6
	global_load_dwordx4 v[200:203], v58, s[68:69]
	global_load_dwordx4 v[204:207], v58, s[68:69] offset:16
; DI unsigned pk_bf16(float lo, float hi) { f32x2 v = {lo, hi}; bf16v2 b = __builtin_convertvector(v, bf16v2); return __builtin_bit_cast(unsigned, b); }
;   DI void operator()(const f32x4 (&acc)[4][4], int r0, int c0, int fr, int fq) const {
;     ...
;       for (int m = 0; m < 4; ++m) {
;         const int row = r0 + m * 16 + fr; const float rs = rsqrtf(rstd[row] * (1.f / 768.f) + EPSF);
;         const int b = row / TB, s = row % TB; const bool lat = s >= NCTX; const int sp = s - NCTX;
; #pragma unroll
;         for (int hh = 0; hh < 2; ++hh) {
;           const int h = ((c0 - 384) >> 5) + hh;
;           float ss = 0.f;
; #pragma unroll
;           for (int nn = 0; nn < 2; ++nn)
; #pragma unroll
;             for (int j = 0; j < 4; ++j) { float v = acc[m][hh * 2 + nn][j] * rs; ss += v * v; }
;           ss += __shfl_xor(ss, 16); ss += __shfl_xor(ss, 32);
;           const float inv = rsqrtf(ss * (1.f / 32.f) + EPSF) * rs;
;           bf16_t* dst = Q + ((size_t)(b * 6 + h) * TB + s) * 96 + 64;
; #pragma unroll
;           for (int nn = 0; nn < 2; ++nn) {
;             const int d = nn * 16 + fq * 4; f32x4 g = *(const f32x4*)(gr + d);
;             float o[4];
; #pragma unroll
;             for (int j = 0; j < 4; ++j) {
;               float val = acc[m][hh * 2 + nn][j] * inv * g[j];
;               float partner = __shfl_xor(val, 32);
;               if (lat) {
;                 const float* rt = rope + ((nn == 0 ? (sp >> 6) : (sp & 63)) * 8 + ((fq * 4 + j) & 7)) * 2; const float cs = rt[0], sn = rt[1];
;                 val = fq < 2 ? val * cs - partner * sn : val * cs + partner * sn;
;               }
;               o[j] = val * QSCALE;
;             }
;             u32x2 v = {pk_bf16(o[0], o[1]), pk_bf16(o[2], o[3])};
;             *(u32x2*)(dst + d) = v;
;           }
.Lrope_pf_6:
	s_or_b64 exec, exec, s[98:99]
	s_and_saveexec_b64 s[0:1], s[38:39]
	s_cbranch_execz .LBB0_580
	s_waitcnt vmcnt(0) lgkmcnt(0)
	v_mul_f32_e32 v42, v201, v42
	v_cndmask_b32_e64 v42, v42, -v42, vcc
	v_fmac_f32_e32 v42, v38, v200
	v_mov_b32_e32 v38, v42
.LBB0_580:
	s_or_b64 exec, exec, s[0:1]
	v_mul_f32_e32 v39, v39, v47
	v_mul_f32_e32 v39, v43, v39
	s_waitcnt lgkmcnt(0)
	ds_bpermute_b32 v42, v1, v39
	s_and_saveexec_b64 s[0:1], s[38:39]
	s_cbranch_execz .LBB0_582
	s_waitcnt vmcnt(0) lgkmcnt(0)
	v_mul_f32_e32 v42, v203, v42
	v_cndmask_b32_e64 v42, v42, -v42, vcc
	v_fmac_f32_e32 v42, v39, v202
	v_mov_b32_e32 v39, v42
.LBB0_582:
	s_or_b64 exec, exec, s[0:1]
	v_mul_f32_e32 v40, v40, v47
	s_waitcnt lgkmcnt(0)
	v_mul_f32_e32 v42, v44, v40
	ds_bpermute_b32 v40, v1, v42
	s_and_saveexec_b64 s[0:1], s[38:39]
	s_cbranch_execz .LBB0_584
	s_waitcnt vmcnt(0) lgkmcnt(0)
	v_mul_f32_e32 v40, v205, v40
	v_cndmask_b32_e64 v40, v40, -v40, vcc
	v_fmac_f32_e32 v40, v42, v204
	v_mov_b32_e32 v42, v40
.LBB0_584:
	s_or_b64 exec, exec, s[0:1]
	s_waitcnt lgkmcnt(0)
	v_mul_f32_e32 v40, v41, v47
	v_mul_f32_e32 v40, v45, v40
	ds_bpermute_b32 v41, v1, v40
	s_and_saveexec_b64 s[0:1], s[38:39]
	s_cbranch_execz .LBB0_586
	s_waitcnt vmcnt(0) lgkmcnt(0)
	v_mul_f32_e32 v41, v207, v41
	v_cndmask_b32_e64 v41, v41, -v41, vcc
	v_fmac_f32_e32 v41, v40, v206
	v_mov_b32_e32 v40, v41
.LBB0_586:
	s_or_b64 exec, exec, s[0:1]
	v_mul_f32_e32 v44, 0x3e16c740, v38
	v_or_b32_e32 v38, 1, v52
	s_movk_i32 s0, 0x900
	v_mul_f32_e32 v45, 0x3e16c740, v39
	v_mad_i64_i32 v[38:39], s[0:1], v38, s0, v[54:55]
	v_readlane_b32 s0, v253, 36
	v_readlane_b32 s2, v253, 38
	v_readlane_b32 s12, v253, 48
	v_readlane_b32 s13, v253, 49
	s_waitcnt lgkmcnt(0)
	v_mul_f32_e32 v41, 0x3e16c740, v42
	v_readlane_b32 s1, v253, 37
	v_mov_b64_e32 v[42:43], s[12:13]
	s_movk_i32 s2, 0xc0
	v_mad_u64_u32 v[42:43], s[0:1], v38, s2, v[42:43]
	v_mad_i32_i24 v43, v39, s2, v43
	v_mul_f32_e32 v39, 0x3e16c740, v40
	v_cvt_pk_bf16_f32 v38, v44, v45
	v_cvt_pk_bf16_f32 v39, v41, v39
	v_lshl_add_u64 v[42:43], v[42:43], 0, v[110:111]
	global_store_dwordx2 v[42:43], v[38:39], off offset:128
	global_load_dwordx4 v[38:41], v[66:67], off offset:64
	v_mul_f32_e32 v34, v34, v47
	v_readlane_b32 s3, v253, 39
	v_readlane_b32 s4, v253, 40
	v_readlane_b32 s5, v253, 41
	v_readlane_b32 s6, v253, 42
	v_readlane_b32 s7, v253, 43
	v_readlane_b32 s8, v253, 44
	v_readlane_b32 s9, v253, 45
	v_readlane_b32 s10, v253, 46
	v_readlane_b32 s11, v253, 47
	v_readlane_b32 s14, v253, 50
	v_readlane_b32 s15, v253, 51
	s_waitcnt vmcnt(0)
	v_mul_f32_e32 v34, v34, v38
	ds_bpermute_b32 v38, v1, v34
	s_and_saveexec_b64 s[98:99], s[38:39]
	s_cbranch_execz .Lrope_pf_7
	global_load_dwordx4 v[200:203], v46, s[68:69]
	global_load_dwordx4 v[204:207], v46, s[68:69] offset:16
.Lrope_pf_7:
	s_or_b64 exec, exec, s[98:99]
	s_and_saveexec_b64 s[0:1], s[38:39]
	s_cbranch_execz .LBB0_588
	s_waitcnt vmcnt(0) lgkmcnt(0)
	v_mul_f32_e32 v38, v201, v38
	v_cndmask_b32_e64 v38, v38, -v38, vcc
	v_fmac_f32_e32 v38, v34, v200
	v_mov_b32_e32 v34, v38
.LBB0_588:
	s_or_b64 exec, exec, s[0:1]
	v_mul_f32_e32 v35, v35, v47
	v_mul_f32_e32 v35, v35, v39
	s_waitcnt lgkmcnt(0)
	ds_bpermute_b32 v38, v1, v35
	s_and_saveexec_b64 s[0:1], s[38:39]
	s_cbranch_execz .LBB0_590
	s_waitcnt vmcnt(0) lgkmcnt(0)
	v_mul_f32_e32 v38, v203, v38
	v_cndmask_b32_e64 v38, v38, -v38, vcc
	v_fmac_f32_e32 v38, v35, v202
	v_mov_b32_e32 v35, v38
.LBB0_590:
	s_or_b64 exec, exec, s[0:1]
	v_mul_f32_e32 v36, v36, v47
	v_mul_f32_e32 v36, v36, v40
	s_waitcnt lgkmcnt(0)
	ds_bpermute_b32 v38, v1, v36
	s_and_saveexec_b64 s[0:1], s[38:39]
	s_cbranch_execz .LBB0_592
	s_waitcnt vmcnt(0) lgkmcnt(0)
	v_mul_f32_e32 v38, v205, v38
	v_cndmask_b32_e64 v38, v38, -v38, vcc
	v_fmac_f32_e32 v38, v36, v204
	v_mov_b32_e32 v36, v38
.LBB0_592:
	s_or_b64 exec, exec, s[0:1]
	v_mul_f32_e32 v37, v37, v47
	v_mul_f32_e32 v37, v37, v41
	s_waitcnt lgkmcnt(0)
	ds_bpermute_b32 v38, v1, v37
	s_and_saveexec_b64 s[0:1], s[38:39]
	s_cbranch_execz .LBB0_594
	s_waitcnt vmcnt(0) lgkmcnt(0)
	v_mul_f32_e32 v38, v207, v38
	v_cndmask_b32_e64 v38, v38, -v38, vcc
	v_fmac_f32_e32 v38, v37, v206
	v_mov_b32_e32 v37, v38
.LBB0_594:
	s_or_b64 exec, exec, s[0:1]
	v_mul_f32_e32 v36, 0x3e16c740, v36
	v_mul_f32_e32 v34, 0x3e16c740, v34
	v_mul_f32_e32 v35, 0x3e16c740, v35
	v_mul_f32_e32 v37, 0x3e16c740, v37
	v_cvt_pk_bf16_f32 v34, v34, v35
	v_cvt_pk_bf16_f32 v35, v36, v37
	global_store_dwordx2 v[42:43], v[34:35], off offset:160
	global_load_dword v35, v[72:73], off offset:128
	v_or_b32_e32 v34, 32, v70
	s_waitcnt vmcnt(0)
	v_fmamk_f32 v35, v35, 0x3aaaaaab, v143
	v_cmp_gt_f32_e64 s[0:1], s53, v35
	v_mul_f32_e32 v36, 0x4b800000, v35
	s_nop 0
	v_cndmask_b32_e64 v35, v35, v36, s[0:1]
	v_rsq_f32_e32 v35, v35
	s_nop 0
	v_mul_f32_e32 v36, 0x45800000, v35
	v_cndmask_b32_e64 v40, v35, v36, s[0:1]
	v_mul_hi_i32 v35, v34, s47
	v_lshrrev_b32_e32 v36, 31, v35
	v_ashrrev_i32_e32 v35, 9, v35
	v_add_u32_e32 v39, v35, v36
	v_mul_i32_i24_e32 v35, 0x900, v39
	s_waitcnt lgkmcnt(0)
	v_sub_u32_e32 v38, v34, v35
	v_pk_mul_f32 v[34:35], v[30:31], v[40:41] op_sel_hi:[1,0]
	v_pk_mul_f32 v[36:37], v[32:33], v[40:41] op_sel_hi:[1,0]
	v_pk_mul_f32 v[34:35], v[34:35], v[34:35]
	v_pk_mul_f32 v[36:37], v[36:37], v[36:37]
	v_add_f32_e32 v34, v34, v35
	v_pk_mul_f32 v[42:43], v[26:27], v[40:41] op_sel_hi:[1,0]
	v_add_f32_e32 v34, v36, v34
	v_pk_mul_f32 v[42:43], v[42:43], v[42:43]
	v_add_f32_e32 v34, v37, v34
	v_pk_mul_f32 v[44:45], v[28:29], v[40:41] op_sel_hi:[1,0]
	v_add_f32_e32 v34, v42, v34
	v_pk_mul_f32 v[44:45], v[44:45], v[44:45]
	v_add_f32_e32 v34, v43, v34
	v_add_f32_e32 v34, v44, v34
	v_add_f32_e32 v34, v45, v34
	ds_bpermute_b32 v35, v78, v34
	v_add_u32_e32 v46, 0xffffff00, v38
	v_lshrrev_b32_e32 v42, 3, v46
	v_cmp_lt_i32_e64 s[38:39], s33, v38
	s_waitcnt lgkmcnt(0)
	v_add_f32_e32 v34, v34, v35
	ds_bpermute_b32 v35, v1, v34
	s_waitcnt lgkmcnt(0)
	v_add_f32_e32 v34, v34, v35
	v_fmamk_f32 v34, v34, 0x3d000000, v143
	v_cmp_gt_f32_e64 s[0:1], s53, v34
	v_mul_f32_e32 v35, 0x4b800000, v34
	s_nop 0
	v_cndmask_b32_e64 v34, v34, v35, s[0:1]
	v_rsq_f32_e32 v34, v34
	s_nop 0
	v_mul_f32_e32 v35, 0x45800000, v34
	v_cndmask_b32_e64 v34, v34, v35, s[0:1]
	v_mul_f32_e32 v41, v40, v34
	global_load_dwordx4 v[34:37], v[66:67], off
	v_mul_f32_e32 v30, v30, v41
	s_mov_b32 s0, 0x1ffffff8
	v_and_or_b32 v42, v42, s0, v79
	v_lshlrev_b32_e32 v42, 3, v42
	s_waitcnt vmcnt(0)
	v_mul_f32_e32 v30, v34, v30
	ds_bpermute_b32 v34, v1, v30
	s_and_saveexec_b64 s[98:99], s[38:39]
	s_cbranch_execz .Lrope_pf_8
	global_load_dwordx4 v[200:203], v42, s[68:69]
	global_load_dwordx4 v[204:207], v42, s[68:69] offset:16
; DI unsigned pk_bf16(float lo, float hi) { f32x2 v = {lo, hi}; bf16v2 b = __builtin_convertvector(v, bf16v2); return __builtin_bit_cast(unsigned, b); }
;   DI void operator()(const f32x4 (&acc)[4][4], int r0, int c0, int fr, int fq) const {
;     ...
;       for (int m = 0; m < 4; ++m) {
;         const int row = r0 + m * 16 + fr; const float rs = rsqrtf(rstd[row] * (1.f / 768.f) + EPSF);
;         const int b = row / TB, s = row % TB; const bool lat = s >= NCTX; const int sp = s - NCTX;
; #pragma unroll
;         for (int hh = 0; hh < 2; ++hh) {
;           const int h = ((c0 - 384) >> 5) + hh;
;           float ss = 0.f;
; #pragma unroll
;           for (int nn = 0; nn < 2; ++nn)
; #pragma unroll
;             for (int j = 0; j < 4; ++j) { float v = acc[m][hh * 2 + nn][j] * rs; ss += v * v; }
;           ss += __shfl_xor(ss, 16); ss += __shfl_xor(ss, 32);
;           const float inv = rsqrtf(ss * (1.f / 32.f) + EPSF) * rs;
;           bf16_t* dst = Q + ((size_t)(b * 6 + h) * TB + s) * 96 + 64;
; #pragma unroll
;           for (int nn = 0; nn < 2; ++nn) {
;             const int d = nn * 16 + fq * 4; f32x4 g = *(const f32x4*)(gr + d);
;             float o[4];
; #pragma unroll
;             for (int j = 0; j < 4; ++j) {
;               float val = acc[m][hh * 2 + nn][j] * inv * g[j];
;               float partner = __shfl_xor(val, 32);
;               if (lat) {
;                 const float* rt = rope + ((nn == 0 ? (sp >> 6) : (sp & 63)) * 8 + ((fq * 4 + j) & 7)) * 2; const float cs = rt[0], sn = rt[1];
;                 val = fq < 2 ? val * cs - partner * sn : val * cs + partner * sn;
;               }
;               o[j] = val * QSCALE;
;             }
;             u32x2 v = {pk_bf16(o[0], o[1]), pk_bf16(o[2], o[3])};
;             *(u32x2*)(dst + d) = v;
;           }
.Lrope_pf_8:
	s_or_b64 exec, exec, s[98:99]
	s_and_saveexec_b64 s[0:1], s[38:39]
	s_cbranch_execz .LBB0_596
	s_waitcnt vmcnt(0) lgkmcnt(0)
	v_mul_f32_e32 v34, v201, v34
	v_cndmask_b32_e64 v34, v34, -v34, vcc
	v_fmac_f32_e32 v34, v30, v200
	v_mov_b32_e32 v30, v34
.LBB0_596:
	s_or_b64 exec, exec, s[0:1]
	v_mul_f32_e32 v31, v31, v41
	v_mul_f32_e32 v31, v35, v31
	s_waitcnt lgkmcnt(0)
	ds_bpermute_b32 v34, v1, v31
	s_and_saveexec_b64 s[0:1], s[38:39]
	s_cbranch_execz .LBB0_598
	s_waitcnt vmcnt(0) lgkmcnt(0)
	v_mul_f32_e32 v34, v203, v34
	v_cndmask_b32_e64 v34, v34, -v34, vcc
	v_fmac_f32_e32 v34, v31, v202
	v_mov_b32_e32 v31, v34
.LBB0_598:
	s_or_b64 exec, exec, s[0:1]
	v_mul_f32_e32 v32, v32, v41
	s_waitcnt lgkmcnt(0)
	v_mul_f32_e32 v34, v36, v32
	ds_bpermute_b32 v32, v1, v34
	s_and_saveexec_b64 s[0:1], s[38:39]
	s_cbranch_execz .LBB0_600
	s_waitcnt vmcnt(0) lgkmcnt(0)
	v_mul_f32_e32 v32, v205, v32
	v_cndmask_b32_e64 v32, v32, -v32, vcc
	v_fmac_f32_e32 v32, v34, v204
	v_mov_b32_e32 v34, v32
.LBB0_600:
	s_or_b64 exec, exec, s[0:1]
	s_waitcnt lgkmcnt(0)
	v_mul_f32_e32 v32, v33, v41
	v_mul_f32_e32 v32, v37, v32
	ds_bpermute_b32 v33, v1, v32
	s_and_saveexec_b64 s[0:1], s[38:39]
	s_cbranch_execz .LBB0_602
	s_waitcnt vmcnt(0) lgkmcnt(0)
	v_mul_f32_e32 v33, v207, v33
	v_cndmask_b32_e64 v33, v33, -v33, vcc
	v_fmac_f32_e32 v33, v32, v206
	v_mov_b32_e32 v32, v33
.LBB0_602:
	s_or_b64 exec, exec, s[0:1]
	v_mad_i32_i24 v36, v39, 6, v71
	v_ashrrev_i32_e32 v39, 31, v38
	s_movk_i32 s0, 0x900
	v_mul_f32_e32 v37, 0x3e16c740, v30
	v_mul_f32_e32 v43, 0x3e16c740, v31
	v_mad_i64_i32 v[30:31], s[0:1], v36, s0, v[38:39]
	v_readlane_b32 s0, v253, 36
	v_readlane_b32 s2, v253, 38
	v_readlane_b32 s12, v253, 48
	v_readlane_b32 s13, v253, 49
	s_waitcnt lgkmcnt(0)
	v_mul_f32_e32 v33, 0x3e16c740, v34
	v_readlane_b32 s1, v253, 37
	v_mov_b64_e32 v[34:35], s[12:13]
	s_movk_i32 s2, 0xc0
	v_mad_u64_u32 v[34:35], s[0:1], v30, s2, v[34:35]
	v_mad_i32_i24 v35, v31, s2, v35
	v_mul_f32_e32 v31, 0x3e16c740, v32
	v_cvt_pk_bf16_f32 v30, v37, v43
	v_cvt_pk_bf16_f32 v31, v33, v31
	v_lshl_add_u64 v[34:35], v[34:35], 0, v[110:111]
	global_store_dwordx2 v[34:35], v[30:31], off offset:128
	global_load_dwordx4 v[30:33], v[66:67], off offset:64
	v_mul_f32_e32 v26, v26, v41
	s_movk_i32 s0, 0x1f8
	v_readlane_b32 s3, v253, 39
	v_readlane_b32 s4, v253, 40
	v_readlane_b32 s5, v253, 41
	v_readlane_b32 s6, v253, 42
	v_readlane_b32 s7, v253, 43
	v_readlane_b32 s8, v253, 44
	v_readlane_b32 s9, v253, 45
	v_readlane_b32 s10, v253, 46
	v_readlane_b32 s11, v253, 47
	v_readlane_b32 s14, v253, 50
	v_readlane_b32 s15, v253, 51
	s_waitcnt vmcnt(0)
	v_mul_f32_e32 v26, v26, v30
	ds_bpermute_b32 v37, v1, v26
	v_lshlrev_b32_e32 v30, 3, v38
	v_and_or_b32 v30, v30, s0, v79
	v_lshlrev_b32_e32 v30, 3, v30
	s_and_saveexec_b64 s[98:99], s[38:39]
	s_cbranch_execz .Lrope_pf_9
	global_load_dwordx4 v[200:203], v30, s[68:69]
	global_load_dwordx4 v[204:207], v30, s[68:69] offset:16
.Lrope_pf_9:
	s_or_b64 exec, exec, s[98:99]
	s_and_saveexec_b64 s[0:1], s[38:39]
	s_cbranch_execz .LBB0_604
	s_waitcnt vmcnt(0) lgkmcnt(0)
	v_mul_f32_e32 v37, v201, v37
	v_cndmask_b32_e64 v37, v37, -v37, vcc
	v_fmac_f32_e32 v37, v26, v200
	v_mov_b32_e32 v26, v37
.LBB0_604:
	s_or_b64 exec, exec, s[0:1]
	v_mul_f32_e32 v27, v27, v41
	v_mul_f32_e32 v27, v27, v31
	ds_bpermute_b32 v31, v1, v27
	s_and_saveexec_b64 s[0:1], s[38:39]
	s_cbranch_execz .LBB0_606
	s_waitcnt vmcnt(0) lgkmcnt(0)
	v_mul_f32_e32 v31, v203, v31
	v_cndmask_b32_e64 v31, v31, -v31, vcc
	v_fmac_f32_e32 v31, v27, v202
	v_mov_b32_e32 v27, v31
.LBB0_606:
	s_or_b64 exec, exec, s[0:1]
	v_mul_f32_e32 v28, v28, v41
	v_mul_f32_e32 v28, v28, v32
	s_waitcnt lgkmcnt(0)
	ds_bpermute_b32 v31, v1, v28
	s_and_saveexec_b64 s[0:1], s[38:39]
	s_cbranch_execz .LBB0_608
	s_waitcnt vmcnt(0) lgkmcnt(0)
	v_mul_f32_e32 v31, v205, v31
	v_cndmask_b32_e64 v31, v31, -v31, vcc
	v_fmac_f32_e32 v31, v28, v204
	v_mov_b32_e32 v28, v31
.LBB0_608:
	s_or_b64 exec, exec, s[0:1]
	v_mul_f32_e32 v29, v29, v41
	v_mul_f32_e32 v29, v29, v33
	s_waitcnt lgkmcnt(0)
	ds_bpermute_b32 v31, v1, v29
	s_and_saveexec_b64 s[0:1], s[38:39]
	s_cbranch_execz .LBB0_610
	s_waitcnt vmcnt(0) lgkmcnt(0)
	v_mul_f32_e32 v31, v207, v31
	v_cndmask_b32_e64 v31, v31, -v31, vcc
	v_fmac_f32_e32 v31, v29, v206
	v_mov_b32_e32 v29, v31
.LBB0_610:
	s_or_b64 exec, exec, s[0:1]
	v_mul_f32_e32 v28, 0x3e16c740, v28
	v_mul_f32_e32 v26, 0x3e16c740, v26
	v_mul_f32_e32 v27, 0x3e16c740, v27
	v_mul_f32_e32 v29, 0x3e16c740, v29
	v_mov_b32_e32 v41, v40
	v_cvt_pk_bf16_f32 v26, v26, v27
	v_cvt_pk_bf16_f32 v27, v28, v29
	global_store_dwordx2 v[34:35], v[26:27], off offset:160
	v_pk_mul_f32 v[26:27], v[22:23], v[40:41]
	v_pk_mul_f32 v[28:29], v[24:25], v[40:41]
	v_pk_mul_f32 v[26:27], v[26:27], v[26:27]
	v_pk_mul_f32 v[28:29], v[28:29], v[28:29]
	v_add_f32_e32 v26, v26, v27
	v_pk_mul_f32 v[32:33], v[18:19], v[40:41]
	v_add_f32_e32 v26, v28, v26
	v_pk_mul_f32 v[32:33], v[32:33], v[32:33]
	v_add_f32_e32 v26, v29, v26
	v_pk_mul_f32 v[34:35], v[20:21], v[40:41]
	v_add_f32_e32 v26, v32, v26
	v_pk_mul_f32 v[34:35], v[34:35], v[34:35]
	v_add_f32_e32 v26, v33, v26
	v_add_f32_e32 v26, v34, v26
	v_add_f32_e32 v26, v35, v26
	ds_bpermute_b32 v27, v78, v26
	s_waitcnt lgkmcnt(0)
	v_add_f32_e32 v26, v26, v27
	ds_bpermute_b32 v27, v1, v26
	s_waitcnt lgkmcnt(0)
	v_add_f32_e32 v26, v26, v27
	v_fmamk_f32 v26, v26, 0x3d000000, v143
	v_cmp_gt_f32_e64 s[0:1], s53, v26
	v_mul_f32_e32 v27, 0x4b800000, v26
	s_nop 0
	v_cndmask_b32_e64 v26, v26, v27, s[0:1]
	v_rsq_f32_e32 v26, v26
	s_nop 0
	v_mul_f32_e32 v27, 0x45800000, v26
	v_cndmask_b32_e64 v26, v26, v27, s[0:1]
	v_mul_f32_e32 v31, v40, v26
	global_load_dwordx4 v[26:29], v[66:67], off
	v_mul_f32_e32 v22, v22, v31
	s_waitcnt vmcnt(0)
	v_mul_f32_e32 v22, v26, v22
	ds_bpermute_b32 v26, v1, v22
	s_and_saveexec_b64 s[98:99], s[38:39]
	s_cbranch_execz .Lrope_pf_10
	global_load_dwordx4 v[200:203], v42, s[68:69]
	global_load_dwordx4 v[204:207], v42, s[68:69] offset:16
; DI unsigned pk_bf16(float lo, float hi) { f32x2 v = {lo, hi}; bf16v2 b = __builtin_convertvector(v, bf16v2); return __builtin_bit_cast(unsigned, b); }
;   DI void operator()(const f32x4 (&acc)[4][4], int r0, int c0, int fr, int fq) const {
;     ...
;       for (int m = 0; m < 4; ++m) {
;         const int row = r0 + m * 16 + fr; const float rs = rsqrtf(rstd[row] * (1.f / 768.f) + EPSF);
;         const int b = row / TB, s = row % TB; const bool lat = s >= NCTX; const int sp = s - NCTX;
; #pragma unroll
;         for (int hh = 0; hh < 2; ++hh) {
;           const int h = ((c0 - 384) >> 5) + hh;
;           float ss = 0.f;
; #pragma unroll
;           for (int nn = 0; nn < 2; ++nn)
; #pragma unroll
;             for (int j = 0; j < 4; ++j) { float v = acc[m][hh * 2 + nn][j] * rs; ss += v * v; }
;           ss += __shfl_xor(ss, 16); ss += __shfl_xor(ss, 32);
;           const float inv = rsqrtf(ss * (1.f / 32.f) + EPSF) * rs;
;           bf16_t* dst = Q + ((size_t)(b * 6 + h) * TB + s) * 96 + 64;
; #pragma unroll
;           for (int nn = 0; nn < 2; ++nn) {
;             const int d = nn * 16 + fq * 4; f32x4 g = *(const f32x4*)(gr + d);
;             float o[4];
; #pragma unroll
;             for (int j = 0; j < 4; ++j) {
;               float val = acc[m][hh * 2 + nn][j] * inv * g[j];
;               float partner = __shfl_xor(val, 32);
;               if (lat) {
;                 const float* rt = rope + ((nn == 0 ? (sp >> 6) : (sp & 63)) * 8 + ((fq * 4 + j) & 7)) * 2; const float cs = rt[0], sn = rt[1];
;                 val = fq < 2 ? val * cs - partner * sn : val * cs + partner * sn;
;               }
;               o[j] = val * QSCALE;
;             }
;             u32x2 v = {pk_bf16(o[0], o[1]), pk_bf16(o[2], o[3])};
;             *(u32x2*)(dst + d) = v;
;           }
.Lrope_pf_10:
	s_or_b64 exec, exec, s[98:99]
	s_and_saveexec_b64 s[0:1], s[38:39]
	s_cbranch_execz .LBB0_612
	s_waitcnt vmcnt(0) lgkmcnt(0)
	v_mul_f32_e32 v26, v201, v26
	v_cndmask_b32_e64 v26, v26, -v26, vcc
	v_fmac_f32_e32 v26, v22, v200
	v_mov_b32_e32 v22, v26
.LBB0_612:
	s_or_b64 exec, exec, s[0:1]
	v_mul_f32_e32 v23, v23, v31
	v_mul_f32_e32 v23, v27, v23
	s_waitcnt lgkmcnt(0)
	ds_bpermute_b32 v26, v1, v23
	s_and_saveexec_b64 s[0:1], s[38:39]
	s_cbranch_execz .LBB0_614
	s_waitcnt vmcnt(0) lgkmcnt(0)
	v_mul_f32_e32 v26, v203, v26
	v_cndmask_b32_e64 v26, v26, -v26, vcc
	v_fmac_f32_e32 v26, v23, v202
	v_mov_b32_e32 v23, v26
.LBB0_614:
	s_or_b64 exec, exec, s[0:1]
	v_mul_f32_e32 v24, v24, v31
	s_waitcnt lgkmcnt(0)
	v_mul_f32_e32 v26, v28, v24
	ds_bpermute_b32 v24, v1, v26
	s_and_saveexec_b64 s[0:1], s[38:39]
	s_cbranch_execz .LBB0_616
	s_waitcnt vmcnt(0) lgkmcnt(0)
	v_mul_f32_e32 v24, v205, v24
	v_cndmask_b32_e64 v24, v24, -v24, vcc
	v_fmac_f32_e32 v24, v26, v204
	v_mov_b32_e32 v26, v24
.LBB0_616:
	s_or_b64 exec, exec, s[0:1]
	s_waitcnt lgkmcnt(0)
	v_mul_f32_e32 v24, v25, v31
	v_mul_f32_e32 v24, v29, v24
	ds_bpermute_b32 v25, v1, v24
	s_and_saveexec_b64 s[0:1], s[38:39]
	s_cbranch_execz .LBB0_618
	s_waitcnt vmcnt(0) lgkmcnt(0)
	v_mul_f32_e32 v25, v207, v25
	v_cndmask_b32_e64 v25, v25, -v25, vcc
	v_fmac_f32_e32 v25, v24, v206
	v_mov_b32_e32 v24, v25
.LBB0_618:
	s_or_b64 exec, exec, s[0:1]
	v_mul_f32_e32 v28, 0x3e16c740, v22
	v_or_b32_e32 v22, 1, v36
	s_movk_i32 s0, 0x900
	v_mul_f32_e32 v29, 0x3e16c740, v23
	v_mad_i64_i32 v[22:23], s[0:1], v22, s0, v[38:39]
	v_readlane_b32 s0, v253, 36
	v_readlane_b32 s2, v253, 38
	v_readlane_b32 s12, v253, 48
	v_readlane_b32 s13, v253, 49
	s_waitcnt lgkmcnt(0)
	v_mul_f32_e32 v25, 0x3e16c740, v26
	v_readlane_b32 s1, v253, 37
	v_mov_b64_e32 v[26:27], s[12:13]
	s_movk_i32 s2, 0xc0
	v_mad_u64_u32 v[26:27], s[0:1], v22, s2, v[26:27]
	v_mad_i32_i24 v27, v23, s2, v27
	v_mul_f32_e32 v23, 0x3e16c740, v24
	v_cvt_pk_bf16_f32 v22, v28, v29
	v_cvt_pk_bf16_f32 v23, v25, v23
	v_lshl_add_u64 v[26:27], v[26:27], 0, v[110:111]
	global_store_dwordx2 v[26:27], v[22:23], off offset:128
	global_load_dwordx4 v[22:25], v[66:67], off offset:64
	v_mul_f32_e32 v18, v18, v31
	v_readlane_b32 s3, v253, 39
	v_readlane_b32 s4, v253, 40
	v_readlane_b32 s5, v253, 41
	v_readlane_b32 s6, v253, 42
	v_readlane_b32 s7, v253, 43
	v_readlane_b32 s8, v253, 44
	v_readlane_b32 s9, v253, 45
	v_readlane_b32 s10, v253, 46
	v_readlane_b32 s11, v253, 47
	v_readlane_b32 s14, v253, 50
	v_readlane_b32 s15, v253, 51
	s_waitcnt vmcnt(0)
	v_mul_f32_e32 v18, v18, v22
	ds_bpermute_b32 v22, v1, v18
	s_and_saveexec_b64 s[98:99], s[38:39]
	s_cbranch_execz .Lrope_pf_11
	global_load_dwordx4 v[200:203], v30, s[68:69]
	global_load_dwordx4 v[204:207], v30, s[68:69] offset:16
.Lrope_pf_11:
	s_or_b64 exec, exec, s[98:99]
	s_and_saveexec_b64 s[0:1], s[38:39]
	s_cbranch_execz .LBB0_620
	s_waitcnt vmcnt(0) lgkmcnt(0)
	v_mul_f32_e32 v22, v201, v22
	v_cndmask_b32_e64 v22, v22, -v22, vcc
	v_fmac_f32_e32 v22, v18, v200
	v_mov_b32_e32 v18, v22
.LBB0_620:
	s_or_b64 exec, exec, s[0:1]
	v_mul_f32_e32 v19, v19, v31
	v_mul_f32_e32 v19, v19, v23
	s_waitcnt lgkmcnt(0)
	ds_bpermute_b32 v22, v1, v19
	s_and_saveexec_b64 s[0:1], s[38:39]
	s_cbranch_execz .LBB0_622
	s_waitcnt vmcnt(0) lgkmcnt(0)
	v_mul_f32_e32 v22, v203, v22
	v_cndmask_b32_e64 v22, v22, -v22, vcc
	v_fmac_f32_e32 v22, v19, v202
	v_mov_b32_e32 v19, v22
.LBB0_622:
	s_or_b64 exec, exec, s[0:1]
	v_mul_f32_e32 v20, v20, v31
	v_mul_f32_e32 v20, v20, v24
	s_waitcnt lgkmcnt(0)
	ds_bpermute_b32 v22, v1, v20
	s_and_saveexec_b64 s[0:1], s[38:39]
	s_cbranch_execz .LBB0_624
	s_waitcnt vmcnt(0) lgkmcnt(0)
	v_mul_f32_e32 v22, v205, v22
	v_cndmask_b32_e64 v22, v22, -v22, vcc
	v_fmac_f32_e32 v22, v20, v204
	v_mov_b32_e32 v20, v22
.LBB0_624:
	s_or_b64 exec, exec, s[0:1]
	v_mul_f32_e32 v21, v21, v31
	v_mul_f32_e32 v21, v21, v25
	s_waitcnt lgkmcnt(0)
	ds_bpermute_b32 v22, v1, v21
	s_and_saveexec_b64 s[0:1], s[38:39]
	s_cbranch_execz .LBB0_626
	s_waitcnt vmcnt(0) lgkmcnt(0)
	v_mul_f32_e32 v22, v207, v22
	v_cndmask_b32_e64 v22, v22, -v22, vcc
	v_fmac_f32_e32 v22, v21, v206
	v_mov_b32_e32 v21, v22
.LBB0_626:
	s_or_b64 exec, exec, s[0:1]
	v_mul_f32_e32 v20, 0x3e16c740, v20
	v_mul_f32_e32 v18, 0x3e16c740, v18
	v_mul_f32_e32 v19, 0x3e16c740, v19
	v_mul_f32_e32 v21, 0x3e16c740, v21
	v_cvt_pk_bf16_f32 v18, v18, v19
	v_cvt_pk_bf16_f32 v19, v20, v21
	global_store_dwordx2 v[26:27], v[18:19], off offset:160
	global_load_dword v19, v[72:73], off offset:192
	v_or_b32_e32 v18, 48, v70
	s_waitcnt vmcnt(0)
	v_fmamk_f32 v19, v19, 0x3aaaaaab, v143
	v_cmp_gt_f32_e64 s[0:1], s53, v19
	v_mul_f32_e32 v20, 0x4b800000, v19
	s_nop 0
	v_cndmask_b32_e64 v19, v19, v20, s[0:1]
	v_rsq_f32_e32 v19, v19
	s_nop 0
	v_mul_f32_e32 v20, 0x45800000, v19
	v_cndmask_b32_e64 v24, v19, v20, s[0:1]
	v_mul_hi_i32 v19, v18, s47
	v_lshrrev_b32_e32 v20, 31, v19
	v_ashrrev_i32_e32 v19, 9, v19
	v_add_u32_e32 v23, v19, v20
	v_mul_i32_i24_e32 v19, 0x900, v23
	s_waitcnt lgkmcnt(0)
	v_sub_u32_e32 v22, v18, v19
	v_pk_mul_f32 v[18:19], v[14:15], v[24:25] op_sel_hi:[1,0]
	v_pk_mul_f32 v[20:21], v[16:17], v[24:25] op_sel_hi:[1,0]
	v_pk_mul_f32 v[18:19], v[18:19], v[18:19]
	v_pk_mul_f32 v[20:21], v[20:21], v[20:21]
	v_add_f32_e32 v18, v18, v19
	v_pk_mul_f32 v[26:27], v[10:11], v[24:25] op_sel_hi:[1,0]
	v_add_f32_e32 v18, v20, v18
	v_pk_mul_f32 v[26:27], v[26:27], v[26:27]
	v_add_f32_e32 v18, v21, v18
	v_pk_mul_f32 v[28:29], v[12:13], v[24:25] op_sel_hi:[1,0]
	v_add_f32_e32 v18, v26, v18
	v_pk_mul_f32 v[28:29], v[28:29], v[28:29]
	v_add_f32_e32 v18, v27, v18
	v_add_f32_e32 v18, v28, v18
	v_add_f32_e32 v18, v29, v18
	ds_bpermute_b32 v19, v78, v18
	v_add_u32_e32 v30, 0xffffff00, v22
	v_lshrrev_b32_e32 v26, 3, v30
	v_cmp_lt_i32_e64 s[38:39], s33, v22
	s_waitcnt lgkmcnt(0)
	v_add_f32_e32 v18, v18, v19
	ds_bpermute_b32 v19, v1, v18
	s_waitcnt lgkmcnt(0)
	v_add_f32_e32 v18, v18, v19
	v_fmamk_f32 v18, v18, 0x3d000000, v143
	v_cmp_gt_f32_e64 s[0:1], s53, v18
	v_mul_f32_e32 v19, 0x4b800000, v18
	s_nop 0
	v_cndmask_b32_e64 v18, v18, v19, s[0:1]
	v_rsq_f32_e32 v18, v18
	s_nop 0
	v_mul_f32_e32 v19, 0x45800000, v18
	v_cndmask_b32_e64 v18, v18, v19, s[0:1]
	v_mul_f32_e32 v25, v24, v18
	global_load_dwordx4 v[18:21], v[66:67], off
	v_mul_f32_e32 v14, v14, v25
	s_mov_b32 s0, 0x1ffffff8
	v_and_or_b32 v26, v26, s0, v79
	v_lshlrev_b32_e32 v26, 3, v26
	s_waitcnt vmcnt(0)
	v_mul_f32_e32 v14, v18, v14
	ds_bpermute_b32 v18, v1, v14
	s_and_saveexec_b64 s[98:99], s[38:39]
	s_cbranch_execz .Lrope_pf_12
	global_load_dwordx4 v[200:203], v26, s[68:69]
	global_load_dwordx4 v[204:207], v26, s[68:69] offset:16
; DI unsigned pk_bf16(float lo, float hi) { f32x2 v = {lo, hi}; bf16v2 b = __builtin_convertvector(v, bf16v2); return __builtin_bit_cast(unsigned, b); }
;   DI void operator()(const f32x4 (&acc)[4][4], int r0, int c0, int fr, int fq) const {
;     ...
;       for (int m = 0; m < 4; ++m) {
;         const int row = r0 + m * 16 + fr; const float rs = rsqrtf(rstd[row] * (1.f / 768.f) + EPSF);
;         const int b = row / TB, s = row % TB; const bool lat = s >= NCTX; const int sp = s - NCTX;
; #pragma unroll
;         for (int hh = 0; hh < 2; ++hh) {
;           const int h = ((c0 - 384) >> 5) + hh;
;           float ss = 0.f;
; #pragma unroll
;           for (int nn = 0; nn < 2; ++nn)
; #pragma unroll
;             for (int j = 0; j < 4; ++j) { float v = acc[m][hh * 2 + nn][j] * rs; ss += v * v; }
;           ss += __shfl_xor(ss, 16); ss += __shfl_xor(ss, 32);
;           const float inv = rsqrtf(ss * (1.f / 32.f) + EPSF) * rs;
;           bf16_t* dst = Q + ((size_t)(b * 6 + h) * TB + s) * 96 + 64;
; #pragma unroll
;           for (int nn = 0; nn < 2; ++nn) {
;             const int d = nn * 16 + fq * 4; f32x4 g = *(const f32x4*)(gr + d);
;             float o[4];
; #pragma unroll
;             for (int j = 0; j < 4; ++j) {
;               float val = acc[m][hh * 2 + nn][j] * inv * g[j];
;               float partner = __shfl_xor(val, 32);
;               if (lat) {
;                 const float* rt = rope + ((nn == 0 ? (sp >> 6) : (sp & 63)) * 8 + ((fq * 4 + j) & 7)) * 2; const float cs = rt[0], sn = rt[1];
;                 val = fq < 2 ? val * cs - partner * sn : val * cs + partner * sn;
;               }
;               o[j] = val * QSCALE;
;             }
;             u32x2 v = {pk_bf16(o[0], o[1]), pk_bf16(o[2], o[3])};
;             *(u32x2*)(dst + d) = v;
;           }
.Lrope_pf_12:
	s_or_b64 exec, exec, s[98:99]
	s_and_saveexec_b64 s[0:1], s[38:39]
	s_cbranch_execz .LBB0_628
	s_waitcnt vmcnt(0) lgkmcnt(0)
	v_mul_f32_e32 v18, v201, v18
	v_cndmask_b32_e64 v18, v18, -v18, vcc
	v_fmac_f32_e32 v18, v14, v200
	v_mov_b32_e32 v14, v18
.LBB0_628:
	s_or_b64 exec, exec, s[0:1]
	v_mul_f32_e32 v15, v15, v25
	v_mul_f32_e32 v15, v19, v15
	s_waitcnt lgkmcnt(0)
	ds_bpermute_b32 v18, v1, v15
	s_and_saveexec_b64 s[0:1], s[38:39]
	s_cbranch_execz .LBB0_630
	s_waitcnt vmcnt(0) lgkmcnt(0)
	v_mul_f32_e32 v18, v203, v18
	v_cndmask_b32_e64 v18, v18, -v18, vcc
	v_fmac_f32_e32 v18, v15, v202
	v_mov_b32_e32 v15, v18
.LBB0_630:
	s_or_b64 exec, exec, s[0:1]
	v_mul_f32_e32 v16, v16, v25
	s_waitcnt lgkmcnt(0)
	v_mul_f32_e32 v18, v20, v16
	ds_bpermute_b32 v16, v1, v18
	s_and_saveexec_b64 s[0:1], s[38:39]
	s_cbranch_execz .LBB0_632
	s_waitcnt vmcnt(0) lgkmcnt(0)
	v_mul_f32_e32 v16, v205, v16
	v_cndmask_b32_e64 v16, v16, -v16, vcc
	v_fmac_f32_e32 v16, v18, v204
	v_mov_b32_e32 v18, v16
.LBB0_632:
	s_or_b64 exec, exec, s[0:1]
	s_waitcnt lgkmcnt(0)
	v_mul_f32_e32 v16, v17, v25
	v_mul_f32_e32 v16, v21, v16
	ds_bpermute_b32 v17, v1, v16
	s_and_saveexec_b64 s[0:1], s[38:39]
	s_cbranch_execz .LBB0_634
	s_waitcnt vmcnt(0) lgkmcnt(0)
	v_mul_f32_e32 v17, v207, v17
	v_cndmask_b32_e64 v17, v17, -v17, vcc
	v_fmac_f32_e32 v17, v16, v206
	v_mov_b32_e32 v16, v17
.LBB0_634:
	s_or_b64 exec, exec, s[0:1]
	v_mad_i32_i24 v20, v23, 6, v71
	v_ashrrev_i32_e32 v23, 31, v22
	s_movk_i32 s0, 0x900
	v_mul_f32_e32 v21, 0x3e16c740, v14
	v_mul_f32_e32 v27, 0x3e16c740, v15
	v_mad_i64_i32 v[14:15], s[0:1], v20, s0, v[22:23]
	v_readlane_b32 s0, v253, 36
	v_readlane_b32 s2, v253, 38
	v_readlane_b32 s12, v253, 48
	v_readlane_b32 s13, v253, 49
	s_waitcnt lgkmcnt(0)
	v_mul_f32_e32 v17, 0x3e16c740, v18
	v_readlane_b32 s1, v253, 37
	v_mov_b64_e32 v[18:19], s[12:13]
	s_movk_i32 s2, 0xc0
	v_mad_u64_u32 v[18:19], s[0:1], v14, s2, v[18:19]
	v_mad_i32_i24 v19, v15, s2, v19
	v_mul_f32_e32 v15, 0x3e16c740, v16
	v_cvt_pk_bf16_f32 v14, v21, v27
	v_cvt_pk_bf16_f32 v15, v17, v15
	v_lshl_add_u64 v[18:19], v[18:19], 0, v[110:111]
	global_store_dwordx2 v[18:19], v[14:15], off offset:128
	global_load_dwordx4 v[14:17], v[66:67], off offset:64
	v_mul_f32_e32 v10, v10, v25
	s_movk_i32 s0, 0x1f8
	v_readlane_b32 s3, v253, 39
	v_readlane_b32 s4, v253, 40
	v_readlane_b32 s5, v253, 41
	v_readlane_b32 s6, v253, 42
	v_readlane_b32 s7, v253, 43
	v_readlane_b32 s8, v253, 44
	v_readlane_b32 s9, v253, 45
	v_readlane_b32 s10, v253, 46
	v_readlane_b32 s11, v253, 47
	v_readlane_b32 s14, v253, 50
	v_readlane_b32 s15, v253, 51
	s_waitcnt vmcnt(0)
	v_mul_f32_e32 v10, v10, v14
	ds_bpermute_b32 v21, v1, v10
	v_lshlrev_b32_e32 v14, 3, v22
	v_and_or_b32 v14, v14, s0, v79
	v_lshlrev_b32_e32 v14, 3, v14
	s_and_saveexec_b64 s[98:99], s[38:39]
	s_cbranch_execz .Lrope_pf_13
	global_load_dwordx4 v[200:203], v14, s[68:69]
	global_load_dwordx4 v[204:207], v14, s[68:69] offset:16
.Lrope_pf_13:
	s_or_b64 exec, exec, s[98:99]
	s_and_saveexec_b64 s[0:1], s[38:39]
	s_cbranch_execz .LBB0_636
	s_waitcnt vmcnt(0) lgkmcnt(0)
	v_mul_f32_e32 v21, v201, v21
	v_cndmask_b32_e64 v21, v21, -v21, vcc
	v_fmac_f32_e32 v21, v10, v200
	v_mov_b32_e32 v10, v21
.LBB0_636:
	s_or_b64 exec, exec, s[0:1]
	v_mul_f32_e32 v11, v11, v25
	v_mul_f32_e32 v11, v11, v15
	ds_bpermute_b32 v15, v1, v11
	s_and_saveexec_b64 s[0:1], s[38:39]
	s_cbranch_execz .LBB0_638
	s_waitcnt vmcnt(0) lgkmcnt(0)
	v_mul_f32_e32 v15, v203, v15
	v_cndmask_b32_e64 v15, v15, -v15, vcc
	v_fmac_f32_e32 v15, v11, v202
	v_mov_b32_e32 v11, v15
.LBB0_638:
	s_or_b64 exec, exec, s[0:1]
	v_mul_f32_e32 v12, v12, v25
	v_mul_f32_e32 v12, v12, v16
	s_waitcnt lgkmcnt(0)
	ds_bpermute_b32 v15, v1, v12
	s_and_saveexec_b64 s[0:1], s[38:39]
	s_cbranch_execz .LBB0_640
	s_waitcnt vmcnt(0) lgkmcnt(0)
	v_mul_f32_e32 v15, v205, v15
	v_cndmask_b32_e64 v15, v15, -v15, vcc
	v_fmac_f32_e32 v15, v12, v204
	v_mov_b32_e32 v12, v15
.LBB0_640:
	s_or_b64 exec, exec, s[0:1]
	v_mul_f32_e32 v13, v13, v25
	v_mul_f32_e32 v13, v13, v17
	s_waitcnt lgkmcnt(0)
	ds_bpermute_b32 v15, v1, v13
	s_and_saveexec_b64 s[0:1], s[38:39]
	s_cbranch_execz .LBB0_642
	s_waitcnt vmcnt(0) lgkmcnt(0)
	v_mul_f32_e32 v15, v207, v15
	v_cndmask_b32_e64 v15, v15, -v15, vcc
	v_fmac_f32_e32 v15, v13, v206
	v_mov_b32_e32 v13, v15
; DI unsigned pk_bf16(float lo, float hi) { f32x2 v = {lo, hi}; bf16v2 b = __builtin_convertvector(v, bf16v2); return __builtin_bit_cast(unsigned, b); }
;   DI void operator()(const f32x4 (&acc)[4][4], int r0, int c0, int fr, int fq) const {
;     ...
;       for (int m = 0; m < 4; ++m) {
;         const int row = r0 + m * 16 + fr; const float rs = rsqrtf(rstd[row] * (1.f / 768.f) + EPSF);
;         const int b = row / TB, s = row % TB; const bool lat = s >= NCTX; const int sp = s - NCTX;
; #pragma unroll
;         for (int hh = 0; hh < 2; ++hh) {
;           const int h = ((c0 - 384) >> 5) + hh;
;           float ss = 0.f;
; #pragma unroll
;           for (int nn = 0; nn < 2; ++nn)
; #pragma unroll
;             for (int j = 0; j < 4; ++j) { float v = acc[m][hh * 2 + nn][j] * rs; ss += v * v; }
;           ss += __shfl_xor(ss, 16); ss += __shfl_xor(ss, 32);
;           const float inv = rsqrtf(ss * (1.f / 32.f) + EPSF) * rs;
;           bf16_t* dst = Q + ((size_t)(b * 6 + h) * TB + s) * 96 + 64;
; #pragma unroll
;           for (int nn = 0; nn < 2; ++nn) {
;             const int d = nn * 16 + fq * 4; f32x4 g = *(const f32x4*)(gr + d);
;             float o[4];
; #pragma unroll
;             for (int j = 0; j < 4; ++j) {
;               float val = acc[m][hh * 2 + nn][j] * inv * g[j];
;               float partner = __shfl_xor(val, 32);
;               if (lat) {
;                 const float* rt = rope + ((nn == 0 ? (sp >> 6) : (sp & 63)) * 8 + ((fq * 4 + j) & 7)) * 2; const float cs = rt[0], sn = rt[1];
;                 val = fq < 2 ? val * cs - partner * sn : val * cs + partner * sn;
;               }
;               o[j] = val * QSCALE;
;             }
;             u32x2 v = {pk_bf16(o[0], o[1]), pk_bf16(o[2], o[3])};
;             *(u32x2*)(dst + d) = v;
;           }
.LBB0_642:
	s_or_b64 exec, exec, s[0:1]
	v_mul_f32_e32 v12, 0x3e16c740, v12
	v_mul_f32_e32 v10, 0x3e16c740, v10
	v_mul_f32_e32 v11, 0x3e16c740, v11
	v_mul_f32_e32 v13, 0x3e16c740, v13
	v_mov_b32_e32 v25, v24
	v_cvt_pk_bf16_f32 v10, v10, v11
	v_cvt_pk_bf16_f32 v11, v12, v13
	global_store_dwordx2 v[18:19], v[10:11], off offset:160
	v_pk_mul_f32 v[10:11], v[6:7], v[24:25]
	v_pk_mul_f32 v[12:13], v[8:9], v[24:25]
	v_pk_mul_f32 v[10:11], v[10:11], v[10:11]
	v_pk_mul_f32 v[12:13], v[12:13], v[12:13]
	v_add_f32_e32 v10, v10, v11
	v_pk_mul_f32 v[16:17], v[2:3], v[24:25]
	v_add_f32_e32 v10, v12, v10
	v_pk_mul_f32 v[16:17], v[16:17], v[16:17]
	v_add_f32_e32 v10, v13, v10
	v_pk_mul_f32 v[18:19], v[4:5], v[24:25]
	v_add_f32_e32 v10, v16, v10
	v_pk_mul_f32 v[18:19], v[18:19], v[18:19]
	v_add_f32_e32 v10, v17, v10
	v_add_f32_e32 v10, v18, v10
	v_add_f32_e32 v10, v19, v10
	ds_bpermute_b32 v11, v78, v10
	s_waitcnt lgkmcnt(0)
	v_add_f32_e32 v10, v10, v11
	ds_bpermute_b32 v11, v1, v10
	s_waitcnt lgkmcnt(0)
	v_add_f32_e32 v10, v10, v11
	v_fmamk_f32 v10, v10, 0x3d000000, v143
	v_cmp_gt_f32_e64 s[0:1], s53, v10
	v_mul_f32_e32 v11, 0x4b800000, v10
	s_nop 0
	v_cndmask_b32_e64 v10, v10, v11, s[0:1]
	v_rsq_f32_e32 v10, v10
	s_nop 0
	v_mul_f32_e32 v11, 0x45800000, v10
	v_cndmask_b32_e64 v10, v10, v11, s[0:1]
	v_mul_f32_e32 v15, v24, v10
	global_load_dwordx4 v[10:13], v[66:67], off
	v_mul_f32_e32 v6, v6, v15
	s_waitcnt vmcnt(0)
	v_mul_f32_e32 v6, v10, v6
	ds_bpermute_b32 v10, v1, v6
	s_and_saveexec_b64 s[98:99], s[38:39]
	s_cbranch_execz .Lrope_pf_14
	global_load_dwordx4 v[200:203], v26, s[68:69]
	global_load_dwordx4 v[204:207], v26, s[68:69] offset:16
.Lrope_pf_14:
	s_or_b64 exec, exec, s[98:99]
	s_and_saveexec_b64 s[0:1], s[38:39]
	s_cbranch_execz .LBB0_644
	s_waitcnt vmcnt(0) lgkmcnt(0)
	v_mul_f32_e32 v10, v201, v10
	v_cndmask_b32_e64 v10, v10, -v10, vcc
	v_fmac_f32_e32 v10, v6, v200
	v_mov_b32_e32 v6, v10
.LBB0_644:
	s_or_b64 exec, exec, s[0:1]
	v_mul_f32_e32 v7, v7, v15
	v_mul_f32_e32 v7, v11, v7
	s_waitcnt lgkmcnt(0)
	ds_bpermute_b32 v10, v1, v7
	s_and_saveexec_b64 s[0:1], s[38:39]
	s_cbranch_execz .LBB0_646
	s_waitcnt vmcnt(0) lgkmcnt(0)
	v_mul_f32_e32 v10, v203, v10
	v_cndmask_b32_e64 v10, v10, -v10, vcc
	v_fmac_f32_e32 v10, v7, v202
	v_mov_b32_e32 v7, v10
.LBB0_646:
	s_or_b64 exec, exec, s[0:1]
	v_mul_f32_e32 v8, v8, v15
	s_waitcnt lgkmcnt(0)
	v_mul_f32_e32 v10, v12, v8
	ds_bpermute_b32 v8, v1, v10
	s_and_saveexec_b64 s[0:1], s[38:39]
	s_cbranch_execz .LBB0_648
	s_waitcnt vmcnt(0) lgkmcnt(0)
	v_mul_f32_e32 v8, v205, v8
	v_cndmask_b32_e64 v8, v8, -v8, vcc
	v_fmac_f32_e32 v8, v10, v204
	v_mov_b32_e32 v10, v8
.LBB0_648:
	s_or_b64 exec, exec, s[0:1]
	s_waitcnt lgkmcnt(0)
	v_mul_f32_e32 v8, v9, v15
	v_mul_f32_e32 v8, v13, v8
	ds_bpermute_b32 v9, v1, v8
	s_and_saveexec_b64 s[0:1], s[38:39]
	s_cbranch_execz .LBB0_650
	s_waitcnt vmcnt(0) lgkmcnt(0)
	v_mul_f32_e32 v9, v207, v9
	v_cndmask_b32_e64 v9, v9, -v9, vcc
	v_fmac_f32_e32 v9, v8, v206
	v_mov_b32_e32 v8, v9
.LBB0_650:
	s_or_b64 exec, exec, s[0:1]
	v_mul_f32_e32 v12, 0x3e16c740, v6
	v_or_b32_e32 v6, 1, v20
	s_movk_i32 s0, 0x900
	v_mul_f32_e32 v13, 0x3e16c740, v7
	v_mad_i64_i32 v[6:7], s[0:1], v6, s0, v[22:23]
	v_readlane_b32 s0, v253, 36
	v_readlane_b32 s2, v253, 38
	v_readlane_b32 s12, v253, 48
	v_readlane_b32 s13, v253, 49
	s_waitcnt lgkmcnt(0)
	v_mul_f32_e32 v9, 0x3e16c740, v10
	v_readlane_b32 s1, v253, 37
	v_mov_b64_e32 v[10:11], s[12:13]
	s_movk_i32 s2, 0xc0
	v_mad_u64_u32 v[10:11], s[0:1], v6, s2, v[10:11]
	v_mad_i32_i24 v11, v7, s2, v11
	v_mul_f32_e32 v7, 0x3e16c740, v8
	v_cvt_pk_bf16_f32 v6, v12, v13
	v_cvt_pk_bf16_f32 v7, v9, v7
	v_lshl_add_u64 v[10:11], v[10:11], 0, v[110:111]
	global_store_dwordx2 v[10:11], v[6:7], off offset:128
	global_load_dwordx4 v[6:9], v[66:67], off offset:64
	v_mul_f32_e32 v2, v2, v15
	v_readlane_b32 s3, v253, 39
	v_readlane_b32 s4, v253, 40
	v_readlane_b32 s5, v253, 41
	v_readlane_b32 s6, v253, 42
	v_readlane_b32 s7, v253, 43
	v_readlane_b32 s8, v253, 44
	v_readlane_b32 s9, v253, 45
	v_readlane_b32 s10, v253, 46
	v_readlane_b32 s11, v253, 47
	v_readlane_b32 s14, v253, 50
	v_readlane_b32 s15, v253, 51
	s_waitcnt vmcnt(0)
	v_mul_f32_e32 v2, v2, v6
	ds_bpermute_b32 v6, v1, v2
	s_and_saveexec_b64 s[98:99], s[38:39]
	s_cbranch_execz .Lrope_pf_15
	global_load_dwordx4 v[200:203], v14, s[68:69]
	global_load_dwordx4 v[204:207], v14, s[68:69] offset:16
.Lrope_pf_15:
	s_or_b64 exec, exec, s[98:99]
	s_and_saveexec_b64 s[0:1], s[38:39]
	s_cbranch_execz .LBB0_652
	s_waitcnt vmcnt(0) lgkmcnt(0)
	v_mul_f32_e32 v6, v201, v6
	v_cndmask_b32_e64 v6, v6, -v6, vcc
	v_fmac_f32_e32 v6, v2, v200
	v_mov_b32_e32 v2, v6
.LBB0_652:
	s_or_b64 exec, exec, s[0:1]
	v_mul_f32_e32 v3, v3, v15
	v_mul_f32_e32 v3, v3, v7
	s_waitcnt lgkmcnt(0)
	ds_bpermute_b32 v6, v1, v3
	s_and_saveexec_b64 s[0:1], s[38:39]
	s_cbranch_execz .LBB0_654
	s_waitcnt vmcnt(0) lgkmcnt(0)
	v_mul_f32_e32 v6, v203, v6
	v_cndmask_b32_e64 v6, v6, -v6, vcc
	v_fmac_f32_e32 v6, v3, v202
	v_mov_b32_e32 v3, v6
.LBB0_654:
	s_or_b64 exec, exec, s[0:1]
	v_mul_f32_e32 v4, v4, v15
	v_mul_f32_e32 v4, v4, v8
	s_waitcnt lgkmcnt(0)
	ds_bpermute_b32 v6, v1, v4
	s_and_saveexec_b64 s[0:1], s[38:39]
	s_cbranch_execz .LBB0_656
	s_waitcnt vmcnt(0) lgkmcnt(0)
	v_mul_f32_e32 v6, v205, v6
	v_cndmask_b32_e64 v6, v6, -v6, vcc
	v_fmac_f32_e32 v6, v4, v204
	v_mov_b32_e32 v4, v6
.LBB0_656:
	s_or_b64 exec, exec, s[0:1]
	v_mul_f32_e32 v5, v5, v15
	v_mul_f32_e32 v5, v5, v9
	ds_bpermute_b32 v1, v1, v5
	s_and_saveexec_b64 s[0:1], s[38:39]
	s_cbranch_execz .LBB0_658
	s_waitcnt lgkmcnt(1)
	s_waitcnt vmcnt(0) lgkmcnt(0)
	v_mul_f32_e32 v1, v207, v1
	v_cndmask_b32_e64 v1, v1, -v1, vcc
	v_fmac_f32_e32 v1, v5, v206
	v_mov_b32_e32 v5, v1
